# GEMM K-loops re-phased from 8 phases / 16 barriers to 4 phases / 8 barriers per 128-deep iteration (32 MFMA per compute segment, same stage and MFMA order), all LDS-DMA in SGPR-base form
# baseline (speedup 1.0000x reference)
; #define PG8_STAGE(bufoff, gbase, voff) do { _Pragma("unroll") for (int _i = 0; _i < 2; ++_i) \
;         __builtin_amdgcn_global_load_lds((const unsigned*)((const char*)(gbase) + (voff)[_i]), (LAS unsigned*)(lds + (bufoff) + ldsw + _i * 8192), 16, 0, 0); } while (0)
; #define PG8_WAIT_V(n) asm volatile("s_waitcnt vmcnt(" #n ")" ::: "memory")
; #define PG8_BAR __builtin_amdgcn_s_barrier()
; template <class Epi, bool KS0 = false>
; __device__ __forceinline__ void gemm_phase(const int WID, LAS unsigned char* lds, const Gemm g, const StaticOrder& S, const Epi& E) {
;     ...
;     for (int i = 0; i < 2; ++i) { int R, C; stage_rc(tid * 16 + i * 8192, R, C); const int Rb = Epi::PERM ? ((R & ~31) + perm32(R & 31)) : R;
;         voffA[i] = (unsigned)(R * K + C) * 2u; voffB[i] = (unsigned)(Rb * K + C) * 2u; }
;     const size_t kstep = KS0 ? (size_t)0 : (size_t)(BK * 2);
;     const size_t hstep = (size_t)HALF * K * 2;
;     const size_t tstep = 2 * hstep;
;     const unsigned ldsw = (unsigned)wid * 1024u;
;     const int aoff = lds_byte(wr * 64 + fr, fq * 8), boff = lds_byte(wc * 32 + fr, fq * 8);
;     ...
;     PG8_STAGE(PG8_SB(0, 0), cB, voffB); PG8_STAGE(PG8_SA(0, 0), cA, voffA); PG8_STAGE(PG8_SB(0, 1), cB + hstep, voffB); PG8_STAGE(PG8_SA(0, 1), cA + hstep, voffA);
;     if (wr == 1) PG8_BAR;
;     PG8_WAIT_V(4); PG8_BAR;
;     PG8_STAGE(PG8_SB(1, 0), cB + kstep, voffB); PG8_STAGE(PG8_SA(1, 0), cA + kstep, voffA); PG8_STAGE(PG8_SB(1, 1), cB + hstep + kstep, voffB);
;     PG8_WAIT_V(6); PG8_BAR;
.LBB0_80:
	s_mov_b64 s[8:9], 0x80
	v_lshl_add_u64 v[6:7], v[6:7], 0, s[8:9]
	s_add_i32 m0, s34, 0x18000
	s_waitcnt vmcnt(0)
	s_barrier
	global_load_lds_dwordx4 v[6:7], off
	v_lshl_add_u64 v[4:5], v[4:5], 0, s[8:9]
	s_add_i32 m0, s34, 0x1a000
	s_add_i32 s40, s34, 0x8000
	s_add_i32 s41, s34, 0xa000
	global_load_lds_dwordx4 v[4:5], off
	v_lshl_add_u64 v[2:3], v[2:3], 0, s[8:9]
	s_mov_b32 m0, s40
	s_add_u32 s12, s22, 0x80080
	global_load_lds_dwordx4 v[2:3], off
	v_lshl_add_u64 v[0:1], v[0:1], 0, s[8:9]
	s_mov_b32 m0, s41
	s_addc_u32 s13, s23, 0
	global_load_lds_dwordx4 v[0:1], off
	v_lshl_add_u64 v[0:1], s[12:13], 0, v[132:133]
	s_add_i32 m0, s34, 0x1c000
	s_sext_i32_i16 s45, s0
	global_load_lds_dwordx4 v[0:1], off
	v_lshl_add_u64 v[0:1], s[12:13], 0, v[128:129]
	s_add_i32 m0, s34, 0x1e000
	v_readlane_b32 s0, v254, 17
	global_load_lds_dwordx4 v[0:1], off
	v_and_b32_e32 v0, 15, v10
	v_and_b32_e32 v1, 48, v10
	v_lshl_or_b32 v0, v0, 6, v1
	v_and_b32_e32 v1, 0xfffffc00, v11
	v_add_u32_e32 v2, s0, v1
	v_lshlrev_b32_e32 v3, 2, v10
	v_readlane_b32 s0, v254, 18
	v_and_b32_e32 v3, 32, v3
	v_bitop3_b32 v2, v0, v2, v3 bitop3:0xde
	v_add_u32_e32 v1, s0, v1
	v_bitop3_b32 v147, v0, v1, v3 bitop3:0xde
	v_lshlrev_b32_e32 v0, 15, v13
	v_and_b32_e32 v0, 0xffff0000, v0
	v_lshl_add_u32 v0, v14, 12, v0
	v_and_b32_e32 v1, 1, v13
	v_lshl_or_b32 v0, v1, 6, v0
	v_lshl_add_u32 v136, v15, 1, v0
	v_lshlrev_b32_e32 v0, 15, v8
	v_and_b32_e32 v0, 0xffff0000, v0
	s_waitcnt vmcnt(6)
	v_lshl_add_u32 v0, v9, 12, v0
	v_and_b32_e32 v1, 1, v8
	v_lshl_or_b32 v0, v1, 6, v0
	s_add_i32 s42, 0, 0x10000
	s_add_i32 s43, 0, 0x14000
	s_mov_b32 s11, 0
	v_mov_b32_e32 v137, v133
	v_lshl_add_u32 v138, v12, 1, v0
	v_mov_b32_e32 v139, v133
	v_mov_b64_e32 v[140:141], 0x700
	v_mov_b64_e32 v[142:143], 0x6ff
	v_add_u32_e32 v148, s42, v147
	v_add_u32_e32 v149, 0, v2
	v_add_u32_e32 v150, s43, v147
	s_mov_b32 s44, 0
	s_barrier
	s_branch .LBB0_83

; #define PG8_STAGE(bufoff, gbase, voff) do { _Pragma("unroll") for (int _i = 0; _i < 2; ++_i) \
;         __builtin_amdgcn_global_load_lds((const unsigned*)((const char*)(gbase) + (voff)[_i]), (LAS unsigned*)(lds + (bufoff) + ldsw + _i * 8192), 16, 0, 0); } while (0)
; #define PG8_LDA(dst, b, h) do { _Pragma("unroll") for (int m = 0; m < 4; ++m) _Pragma("unroll") for (int k = 0; k < 2; ++k) dst[m][k] = *(const LAS bf16x8*)(lds + PG8_SA(b, h) + aoff + m * 2048 + k * 1024); } while (0)
; #define PG8_LDB(dst, b, h) do { _Pragma("unroll") for (int n = 0; n < 2; ++n) _Pragma("unroll") for (int k = 0; k < 2; ++k) dst[n][k] = *(const LAS bf16x8*)(lds + PG8_SB(b, h) + boff + n * 2048 + k * 1024); } while (0)
; #define PG8_MMA(ai, bj, At, Bt) do { __builtin_amdgcn_s_setprio(1); _Pragma("unroll") for (int m = 0; m < 4; ++m) _Pragma("unroll") for (int n = 0; n < 2; ++n) _Pragma("unroll") for (int k = 0; k < 2; ++k) \
;         acc[ai][bj][m][n] = __builtin_amdgcn_mfma_f32_16x16x32_bf16(Bt[n][k], At[m][k], acc[ai][bj][m][n], 0, 0, 0); __builtin_amdgcn_s_setprio(0); } while (0)
; #define PG8_WAIT_V(n) asm volatile("s_waitcnt vmcnt(" #n ")" ::: "memory")
; #define PG8_WAIT_L(n) asm volatile("s_waitcnt lgkmcnt(" #n ")" ::: "memory")
; #define PG8_BAR __builtin_amdgcn_s_barrier()
; #define PG8_SCHED __builtin_amdgcn_sched_barrier(0)
; template <class Epi, bool KS0 = false>
; __device__ __forceinline__ void gemm_phase(const int WID, LAS unsigned char* lds, const Gemm g, const StaticOrder& S, const Epi& E) {
;     ...
;             PG8_LDB(B0, 0, 0); PG8_SCHED; PG8_LDA(At, 0, 0); PG8_STAGE(PG8_SA(1, 1), a1 + hstep, voffA);
;             PG8_WAIT_L(8); PG8_BAR; PG8_WAIT_L(0); PG8_MMA(0, 0, At, B0); PG8_BAR; PG8_SCHED;
;             PG8_LDB(B1, 0, 1); PG8_STAGE(PG8_SB(0, 0), b2, voffB);
;             PG8_BAR; PG8_WAIT_L(0); PG8_MMA(0, 1, At, B1); PG8_BAR;
;             PG8_LDA(At, 0, 1); PG8_STAGE(PG8_SA(0, 0), a2, voffA);
;             PG8_BAR; PG8_WAIT_L(0); PG8_MMA(1, 0, At, B0); PG8_BAR; PG8_SCHED;
;             PG8_STAGE(PG8_SB(0, 1), b2 + hstep, voffB);
;             PG8_WAIT_V(6); PG8_BAR; PG8_MMA(1, 1, At, B1); PG8_BAR;
.LBB0_86:
	ds_read_b128 v[152:155], v148
	ds_read_b128 v[156:159], v148 offset:1024
	ds_read_b128 v[160:163], v148 offset:2048
	ds_read_b128 v[164:167], v148 offset:3072
	ds_read_b128 v[168:171], v149
	ds_read_b128 v[172:175], v149 offset:1024
	ds_read_b128 v[176:179], v149 offset:2048
	ds_read_b128 v[180:183], v149 offset:3072
	ds_read_b128 v[184:187], v149 offset:4096
	ds_read_b128 v[188:191], v149 offset:5120
	ds_read_b128 v[192:195], v149 offset:6144
	ds_read_b128 v[196:199], v149 offset:7168
	ds_read_b128 v[200:203], v150
	ds_read_b128 v[204:207], v150 offset:1024
	ds_read_b128 v[208:211], v150 offset:2048
	ds_read_b128 v[212:215], v150 offset:3072
	s_add_u32 s22, s20, 0xfff80080
	s_addc_u32 s23, s21, -1
	s_cmp_eq_u32 s50, 28
	s_cselect_b32 s25, s15, s23
	s_cselect_b32 s24, s46, s22
	s_cselect_b32 s23, s13, s49
	s_cselect_b32 s22, s47, s48
	s_add_i32 m0, s34, 0xc000
	s_nop 0
	global_load_lds_dwordx4 v136, s[20:21]
	s_add_i32 m0, s34, 0xe000
	s_nop 0
	global_load_lds_dwordx4 v138, s[20:21]
	s_waitcnt vmcnt(8) lgkmcnt(0)
	s_barrier
	s_waitcnt lgkmcnt(0)
	v_mfma_f32_16x16x32_bf16 v[124:127], v[152:155], v[168:171], v[124:127]
	v_mfma_f32_16x16x32_bf16 v[120:123], v[160:163], v[168:171], v[120:123]
	v_mfma_f32_16x16x32_bf16 v[112:115], v[152:155], v[176:179], v[112:115]
	v_mfma_f32_16x16x32_bf16 v[104:107], v[160:163], v[176:179], v[104:107]
	v_mfma_f32_16x16x32_bf16 v[100:103], v[152:155], v[184:187], v[100:103]
	v_mfma_f32_16x16x32_bf16 v[92:95], v[160:163], v[184:187], v[92:95]
	v_mfma_f32_16x16x32_bf16 v[84:87], v[152:155], v[192:195], v[84:87]
	v_mfma_f32_16x16x32_bf16 v[76:79], v[160:163], v[192:195], v[76:79]
	v_mfma_f32_16x16x32_bf16 v[124:127], v[156:159], v[172:175], v[124:127]
	v_mfma_f32_16x16x32_bf16 v[120:123], v[164:167], v[172:175], v[120:123]
	v_mfma_f32_16x16x32_bf16 v[112:115], v[156:159], v[180:183], v[112:115]
	v_mfma_f32_16x16x32_bf16 v[104:107], v[164:167], v[180:183], v[104:107]
	v_mfma_f32_16x16x32_bf16 v[100:103], v[156:159], v[188:191], v[100:103]
	v_mfma_f32_16x16x32_bf16 v[92:95], v[164:167], v[188:191], v[92:95]
	v_mfma_f32_16x16x32_bf16 v[84:87], v[156:159], v[196:199], v[84:87]
	v_mfma_f32_16x16x32_bf16 v[76:79], v[164:167], v[196:199], v[76:79]
	v_mfma_f32_16x16x32_bf16 v[116:119], v[200:203], v[168:171], v[116:119]
	v_mfma_f32_16x16x32_bf16 v[108:111], v[208:211], v[168:171], v[108:111]
	v_mfma_f32_16x16x32_bf16 v[96:99], v[200:203], v[176:179], v[96:99]
	v_mfma_f32_16x16x32_bf16 v[88:91], v[208:211], v[176:179], v[88:91]
	v_mfma_f32_16x16x32_bf16 v[80:83], v[200:203], v[184:187], v[80:83]
	v_mfma_f32_16x16x32_bf16 v[72:75], v[208:211], v[184:187], v[72:75]
	v_mfma_f32_16x16x32_bf16 v[68:71], v[200:203], v[192:195], v[68:71]
	v_mfma_f32_16x16x32_bf16 v[64:67], v[208:211], v[192:195], v[64:67]
	v_mfma_f32_16x16x32_bf16 v[116:119], v[204:207], v[172:175], v[116:119]
	v_mfma_f32_16x16x32_bf16 v[108:111], v[212:215], v[172:175], v[108:111]
	v_mfma_f32_16x16x32_bf16 v[96:99], v[204:207], v[180:183], v[96:99]
	v_mfma_f32_16x16x32_bf16 v[88:91], v[212:215], v[180:183], v[88:91]
	v_mfma_f32_16x16x32_bf16 v[80:83], v[204:207], v[188:191], v[80:83]
	v_mfma_f32_16x16x32_bf16 v[72:75], v[212:215], v[188:191], v[72:75]
	v_mfma_f32_16x16x32_bf16 v[68:71], v[204:207], v[196:199], v[68:71]
	v_mfma_f32_16x16x32_bf16 v[64:67], v[212:215], v[196:199], v[64:67]
	s_barrier
	ds_read_b128 v[168:171], v149 offset:16384
	ds_read_b128 v[172:175], v149 offset:17408
	ds_read_b128 v[176:179], v149 offset:18432
	ds_read_b128 v[180:183], v149 offset:19456
	ds_read_b128 v[184:187], v149 offset:20480
	ds_read_b128 v[188:191], v149 offset:21504
	ds_read_b128 v[192:195], v149 offset:22528
	ds_read_b128 v[196:199], v149 offset:23552
	s_add_i32 s51, s42, s26
	s_add_u32 s98, s22, s8
	s_addc_u32 s99, s23, s9
	s_mov_b32 m0, s51
	s_nop 0
	global_load_lds_dwordx4 v132, s[22:23]
	s_add_i32 m0, s51, 0x2000
	s_nop 0
	global_load_lds_dwordx4 v128, s[22:23]
	s_mov_b32 m0, s34
	s_add_u32 s100, s24, s8
	s_addc_u32 s101, s25, s9
	global_load_lds_dwordx4 v134, s[24:25]
	s_mov_b32 m0, s35
	s_nop 0
	global_load_lds_dwordx4 v130, s[24:25]
	s_add_u32 s52, s22, 0x80000
	s_addc_u32 s53, s23, 0
	s_add_i32 s51, s43, s26
	s_mov_b32 m0, s51
	s_nop 0
	global_load_lds_dwordx4 v132, s[52:53]
	s_add_i32 m0, s51, 0x2000
	s_nop 0
	global_load_lds_dwordx4 v128, s[52:53]
	s_waitcnt vmcnt(8) lgkmcnt(0)
	s_barrier
	s_waitcnt lgkmcnt(0)
	v_mfma_f32_16x16x32_bf16 v[60:63], v[152:155], v[168:171], v[60:63]
	v_mfma_f32_16x16x32_bf16 v[56:59], v[160:163], v[168:171], v[56:59]
	v_mfma_f32_16x16x32_bf16 v[52:55], v[152:155], v[176:179], v[52:55]
	v_mfma_f32_16x16x32_bf16 v[44:47], v[160:163], v[176:179], v[44:47]
	v_mfma_f32_16x16x32_bf16 v[36:39], v[152:155], v[184:187], v[36:39]
	v_mfma_f32_16x16x32_bf16 v[28:31], v[160:163], v[184:187], v[28:31]
	v_mfma_f32_16x16x32_bf16 v[20:23], v[152:155], v[192:195], v[20:23]
	v_mfma_f32_16x16x32_bf16 v[12:15], v[160:163], v[192:195], v[12:15]
	v_mfma_f32_16x16x32_bf16 v[60:63], v[156:159], v[172:175], v[60:63]
	v_mfma_f32_16x16x32_bf16 v[56:59], v[164:167], v[172:175], v[56:59]
	v_mfma_f32_16x16x32_bf16 v[52:55], v[156:159], v[180:183], v[52:55]
	v_mfma_f32_16x16x32_bf16 v[44:47], v[164:167], v[180:183], v[44:47]
	v_mfma_f32_16x16x32_bf16 v[36:39], v[156:159], v[188:191], v[36:39]
	v_mfma_f32_16x16x32_bf16 v[28:31], v[164:167], v[188:191], v[28:31]
	v_mfma_f32_16x16x32_bf16 v[20:23], v[156:159], v[196:199], v[20:23]
	v_mfma_f32_16x16x32_bf16 v[12:15], v[164:167], v[196:199], v[12:15]
	v_mfma_f32_16x16x32_bf16 v[48:51], v[200:203], v[168:171], v[48:51]
	v_mfma_f32_16x16x32_bf16 v[40:43], v[208:211], v[168:171], v[40:43]
	v_mfma_f32_16x16x32_bf16 v[32:35], v[200:203], v[176:179], v[32:35]
	v_mfma_f32_16x16x32_bf16 v[24:27], v[208:211], v[176:179], v[24:27]
	v_mfma_f32_16x16x32_bf16 v[16:19], v[200:203], v[184:187], v[16:19]
	v_mfma_f32_16x16x32_bf16 v[8:11], v[208:211], v[184:187], v[8:11]
	v_mfma_f32_16x16x32_bf16 v[4:7], v[200:203], v[192:195], v[4:7]
	v_mfma_f32_16x16x32_bf16 v[0:3], v[208:211], v[192:195], v[0:3]
	v_mfma_f32_16x16x32_bf16 v[48:51], v[204:207], v[172:175], v[48:51]
	v_mfma_f32_16x16x32_bf16 v[40:43], v[212:215], v[172:175], v[40:43]
	v_mfma_f32_16x16x32_bf16 v[32:35], v[204:207], v[180:183], v[32:35]
	v_mfma_f32_16x16x32_bf16 v[24:27], v[212:215], v[180:183], v[24:27]
	v_mfma_f32_16x16x32_bf16 v[16:19], v[204:207], v[188:191], v[16:19]
	v_mfma_f32_16x16x32_bf16 v[8:11], v[212:215], v[188:191], v[8:11]
	v_mfma_f32_16x16x32_bf16 v[4:7], v[204:207], v[196:199], v[4:7]
	v_mfma_f32_16x16x32_bf16 v[0:3], v[212:215], v[196:199], v[0:3]
	s_barrier
; __device__ __forceinline__ int lane_id_() { int l; asm volatile("v_mbcnt_lo_u32_b32 %0, -1, 0\n\tv_mbcnt_hi_u32_b32 %0, -1, %0" : "=v"(l)); return l; }
; #define PG8_STAGE(bufoff, gbase, voff) do { _Pragma("unroll") for (int _i = 0; _i < 2; ++_i) \
;         __builtin_amdgcn_global_load_lds((const unsigned*)((const char*)(gbase) + (voff)[_i]), (LAS unsigned*)(lds + (bufoff) + ldsw + _i * 8192), 16, 0, 0); } while (0)
; #define PG8_LDA(dst, b, h) do { _Pragma("unroll") for (int m = 0; m < 4; ++m) _Pragma("unroll") for (int k = 0; k < 2; ++k) dst[m][k] = *(const LAS bf16x8*)(lds + PG8_SA(b, h) + aoff + m * 2048 + k * 1024); } while (0)
; #define PG8_LDB(dst, b, h) do { _Pragma("unroll") for (int n = 0; n < 2; ++n) _Pragma("unroll") for (int k = 0; k < 2; ++k) dst[n][k] = *(const LAS bf16x8*)(lds + PG8_SB(b, h) + boff + n * 2048 + k * 1024); } while (0)
; #define PG8_MMA(ai, bj, At, Bt) do { __builtin_amdgcn_s_setprio(1); _Pragma("unroll") for (int m = 0; m < 4; ++m) _Pragma("unroll") for (int n = 0; n < 2; ++n) _Pragma("unroll") for (int k = 0; k < 2; ++k) \
;         acc[ai][bj][m][n] = __builtin_amdgcn_mfma_f32_16x16x32_bf16(Bt[n][k], At[m][k], acc[ai][bj][m][n], 0, 0, 0); __builtin_amdgcn_s_setprio(0); } while (0)
; #define PG8_WAIT_V(n) asm volatile("s_waitcnt vmcnt(" #n ")" ::: "memory")
; #define PG8_WAIT_L(n) asm volatile("s_waitcnt lgkmcnt(" #n ")" ::: "memory")
; #define PG8_BAR __builtin_amdgcn_s_barrier()
; template <class Epi, bool KS0 = false>
; __device__ __forceinline__ void gemm_phase(const int WID, LAS unsigned char* lds, const Gemm g, const StaticOrder& S, const Epi& E) {
;     ...
;             PG8_LDB(B0, 1, 0); PG8_SCHED; PG8_LDA(At, 1, 0); PG8_STAGE(PG8_SA(0, 1), a2 + hstep, voffA);
;             PG8_WAIT_L(8); PG8_BAR; PG8_WAIT_L(0); PG8_MMA(0, 0, At, B0); PG8_BAR; PG8_SCHED;
;             PG8_LDB(B1, 1, 1); PG8_STAGE(PG8_SB(1, 0), b3, voffB);
;             PG8_BAR; PG8_WAIT_L(0); PG8_MMA(0, 1, At, B1); PG8_BAR;
;             PG8_LDA(At, 1, 1); PG8_STAGE(PG8_SA(1, 0), a3, voffA);
;             PG8_BAR; PG8_WAIT_L(0); PG8_MMA(1, 0, At, B0); PG8_BAR; PG8_SCHED;
;             PG8_STAGE(PG8_SB(1, 1), b3 + hstep, voffB);
;             PG8_WAIT_V(6); PG8_BAR; PG8_MMA(1, 1, At, B1); PG8_BAR;
;         }
;         { int fr2 = lane_id_(), fq2; fq2 = fr2 >> 4; fr2 &= 15; asm volatile("" : "+v"(fr2), "+v"(fq2)); E(acc, cur, wr, wc, fr2, fq2); }
	v_add_u32_e32 v152, 0x18000, v147
	ds_read_b128 v[156:159], v152 offset:1024
	ds_read_b128 v[160:163], v152 offset:2048
	ds_read_b128 v[164:167], v152 offset:3072
	ds_read_b128 v[152:155], v152
	ds_read_b128 v[168:171], v149 offset:32768
	ds_read_b128 v[172:175], v149 offset:33792
	ds_read_b128 v[176:179], v149 offset:34816
	ds_read_b128 v[180:183], v149 offset:35840
	ds_read_b128 v[184:187], v149 offset:36864
	ds_read_b128 v[188:191], v149 offset:37888
	ds_read_b128 v[192:195], v149 offset:38912
	ds_read_b128 v[196:199], v149 offset:39936
	v_add_u32_e32 v151, 0x1c000, v147
	ds_read_b128 v[200:203], v151
	ds_read_b128 v[204:207], v151 offset:1024
	ds_read_b128 v[208:211], v151 offset:2048
	ds_read_b128 v[212:215], v151 offset:3072
	s_add_i32 s51, 0, 0x18000
	s_add_u32 s24, s24, 0x80000
	s_addc_u32 s25, s25, 0
	s_mov_b32 m0, s38
	s_nop 0
	global_load_lds_dwordx4 v134, s[24:25]
	s_mov_b32 m0, s39
	s_nop 0
	global_load_lds_dwordx4 v130, s[24:25]
	s_waitcnt vmcnt(8) lgkmcnt(0)
	s_barrier
	s_waitcnt lgkmcnt(0)
	v_mfma_f32_16x16x32_bf16 v[124:127], v[152:155], v[168:171], v[124:127]
	v_mfma_f32_16x16x32_bf16 v[120:123], v[160:163], v[168:171], v[120:123]
	v_mfma_f32_16x16x32_bf16 v[112:115], v[152:155], v[176:179], v[112:115]
	v_mfma_f32_16x16x32_bf16 v[104:107], v[160:163], v[176:179], v[104:107]
	v_mfma_f32_16x16x32_bf16 v[100:103], v[152:155], v[184:187], v[100:103]
	v_mfma_f32_16x16x32_bf16 v[92:95], v[160:163], v[184:187], v[92:95]
	v_mfma_f32_16x16x32_bf16 v[84:87], v[152:155], v[192:195], v[84:87]
	v_mfma_f32_16x16x32_bf16 v[76:79], v[160:163], v[192:195], v[76:79]
	v_mfma_f32_16x16x32_bf16 v[124:127], v[156:159], v[172:175], v[124:127]
	v_mfma_f32_16x16x32_bf16 v[120:123], v[164:167], v[172:175], v[120:123]
	v_mfma_f32_16x16x32_bf16 v[112:115], v[156:159], v[180:183], v[112:115]
	v_mfma_f32_16x16x32_bf16 v[104:107], v[164:167], v[180:183], v[104:107]
	v_mfma_f32_16x16x32_bf16 v[100:103], v[156:159], v[188:191], v[100:103]
	v_mfma_f32_16x16x32_bf16 v[92:95], v[164:167], v[188:191], v[92:95]
	v_mfma_f32_16x16x32_bf16 v[84:87], v[156:159], v[196:199], v[84:87]
	v_mfma_f32_16x16x32_bf16 v[76:79], v[164:167], v[196:199], v[76:79]
	v_mfma_f32_16x16x32_bf16 v[116:119], v[200:203], v[168:171], v[116:119]
	v_mfma_f32_16x16x32_bf16 v[108:111], v[208:211], v[168:171], v[108:111]
	v_mfma_f32_16x16x32_bf16 v[96:99], v[200:203], v[176:179], v[96:99]
	v_mfma_f32_16x16x32_bf16 v[88:91], v[208:211], v[176:179], v[88:91]
	v_mfma_f32_16x16x32_bf16 v[80:83], v[200:203], v[184:187], v[80:83]
	v_mfma_f32_16x16x32_bf16 v[72:75], v[208:211], v[184:187], v[72:75]
	v_mfma_f32_16x16x32_bf16 v[68:71], v[200:203], v[192:195], v[68:71]
	v_mfma_f32_16x16x32_bf16 v[64:67], v[208:211], v[192:195], v[64:67]
	v_mfma_f32_16x16x32_bf16 v[116:119], v[204:207], v[172:175], v[116:119]
	v_mfma_f32_16x16x32_bf16 v[108:111], v[212:215], v[172:175], v[108:111]
	v_mfma_f32_16x16x32_bf16 v[96:99], v[204:207], v[180:183], v[96:99]
	v_mfma_f32_16x16x32_bf16 v[88:91], v[212:215], v[180:183], v[88:91]
	v_mfma_f32_16x16x32_bf16 v[80:83], v[204:207], v[188:191], v[80:83]
	v_mfma_f32_16x16x32_bf16 v[72:75], v[212:215], v[188:191], v[72:75]
	v_mfma_f32_16x16x32_bf16 v[68:71], v[204:207], v[196:199], v[68:71]
	v_mfma_f32_16x16x32_bf16 v[64:67], v[212:215], v[196:199], v[64:67]
	s_barrier
	ds_read_b128 v[168:171], v149 offset:49152
	ds_read_b128 v[172:175], v149 offset:50176
	ds_read_b128 v[176:179], v149 offset:51200
	ds_read_b128 v[180:183], v149 offset:52224
	ds_read_b128 v[184:187], v149 offset:53248
	ds_read_b128 v[188:191], v149 offset:54272
	ds_read_b128 v[192:195], v149 offset:55296
	ds_read_b128 v[196:199], v149 offset:56320
	s_add_i32 s24, 0, 0x1c000
	s_add_i32 s25, s51, s26
	s_mov_b32 m0, s25
	s_nop 0
	global_load_lds_dwordx4 v132, s[98:99]
	s_add_i32 m0, s25, 0x2000
	s_nop 0
	global_load_lds_dwordx4 v128, s[98:99]
	s_mov_b32 m0, s40
	s_nop 0
	global_load_lds_dwordx4 v134, s[100:101]
	s_mov_b32 m0, s41
	s_nop 0
	global_load_lds_dwordx4 v130, s[100:101]
	s_add_u32 s22, s22, 0x80080
	s_addc_u32 s23, s23, 0
	s_add_i32 s24, s24, s26
	s_mov_b32 m0, s24
	s_nop 0
	global_load_lds_dwordx4 v132, s[22:23]
	s_add_i32 m0, s24, 0x2000
	s_nop 0
	global_load_lds_dwordx4 v128, s[22:23]
	s_waitcnt vmcnt(8) lgkmcnt(0)
	s_barrier
	s_waitcnt lgkmcnt(0)
	v_mfma_f32_16x16x32_bf16 v[60:63], v[152:155], v[168:171], v[60:63]
	v_mfma_f32_16x16x32_bf16 v[56:59], v[160:163], v[168:171], v[56:59]
	s_add_i32 s50, s50, 2
	s_add_u32 s20, s20, 0x100
	s_addc_u32 s21, s21, 0
	s_add_u32 s48, s48, 0x100
	s_addc_u32 s49, s49, 0
	s_cmp_gt_u32 s50, 29
	v_mfma_f32_16x16x32_bf16 v[52:55], v[152:155], v[176:179], v[52:55]
	v_mfma_f32_16x16x32_bf16 v[44:47], v[160:163], v[176:179], v[44:47]
	v_mfma_f32_16x16x32_bf16 v[36:39], v[152:155], v[184:187], v[36:39]
	v_mfma_f32_16x16x32_bf16 v[28:31], v[160:163], v[184:187], v[28:31]
	v_mfma_f32_16x16x32_bf16 v[20:23], v[152:155], v[192:195], v[20:23]
	v_mfma_f32_16x16x32_bf16 v[12:15], v[160:163], v[192:195], v[12:15]
	v_mfma_f32_16x16x32_bf16 v[60:63], v[156:159], v[172:175], v[60:63]
	v_mfma_f32_16x16x32_bf16 v[56:59], v[164:167], v[172:175], v[56:59]
	v_mfma_f32_16x16x32_bf16 v[52:55], v[156:159], v[180:183], v[52:55]
	v_mfma_f32_16x16x32_bf16 v[44:47], v[164:167], v[180:183], v[44:47]
	v_mfma_f32_16x16x32_bf16 v[36:39], v[156:159], v[188:191], v[36:39]
	v_mfma_f32_16x16x32_bf16 v[28:31], v[164:167], v[188:191], v[28:31]
	v_mfma_f32_16x16x32_bf16 v[20:23], v[156:159], v[196:199], v[20:23]
	v_mfma_f32_16x16x32_bf16 v[12:15], v[164:167], v[196:199], v[12:15]
	v_mfma_f32_16x16x32_bf16 v[48:51], v[200:203], v[168:171], v[48:51]
	v_mfma_f32_16x16x32_bf16 v[40:43], v[208:211], v[168:171], v[40:43]
	v_mfma_f32_16x16x32_bf16 v[32:35], v[200:203], v[176:179], v[32:35]
	v_mfma_f32_16x16x32_bf16 v[24:27], v[208:211], v[176:179], v[24:27]
	v_mfma_f32_16x16x32_bf16 v[16:19], v[200:203], v[184:187], v[16:19]
	v_mfma_f32_16x16x32_bf16 v[8:11], v[208:211], v[184:187], v[8:11]
	v_mfma_f32_16x16x32_bf16 v[4:7], v[200:203], v[192:195], v[4:7]
	v_mfma_f32_16x16x32_bf16 v[0:3], v[208:211], v[192:195], v[0:3]
	v_mfma_f32_16x16x32_bf16 v[48:51], v[204:207], v[172:175], v[48:51]
	v_mfma_f32_16x16x32_bf16 v[40:43], v[212:215], v[172:175], v[40:43]
	v_mfma_f32_16x16x32_bf16 v[32:35], v[204:207], v[180:183], v[32:35]
	v_mfma_f32_16x16x32_bf16 v[24:27], v[212:215], v[180:183], v[24:27]
	v_mfma_f32_16x16x32_bf16 v[16:19], v[204:207], v[188:191], v[16:19]
	v_mfma_f32_16x16x32_bf16 v[8:11], v[212:215], v[188:191], v[8:11]
	v_mfma_f32_16x16x32_bf16 v[4:7], v[204:207], v[196:199], v[4:7]
	v_mfma_f32_16x16x32_bf16 v[0:3], v[212:215], v[196:199], v[0:3]
	s_barrier
	s_cbranch_scc0 .LBB0_86
	s_waitcnt lgkmcnt(0)
	v_mbcnt_lo_u32_b32 v144, -1, 0
	v_mbcnt_hi_u32_b32 v144, -1, v144
	s_cmp_lt_i32 s45, 8
	v_ashrrev_i32_e32 v145, 4, v144
	v_and_b32_e32 v151, 15, v144
	s_mov_b64 s[20:21], -1
	s_cbranch_scc1 .LBB0_89
	v_add_u32_e32 v144, s55, v151
	v_lshlrev_b32_e32 v152, 7, v145
	v_lshl_add_u32 v144, v144, 3, v152
	s_mov_b64 s[20:21], 0

; #define PG8_STAGE(bufoff, gbase, voff) do { _Pragma("unroll") for (int _i = 0; _i < 2; ++_i) \
;         __builtin_amdgcn_global_load_lds((const unsigned*)((const char*)(gbase) + (voff)[_i]), (LAS unsigned*)(lds + (bufoff) + ldsw + _i * 8192), 16, 0, 0); } while (0)
; #define PG8_WAIT_V(n) asm volatile("s_waitcnt vmcnt(" #n ")" ::: "memory")
; #define PG8_BAR __builtin_amdgcn_s_barrier()
; template <class Epi, bool KS0 = false>
; __device__ __forceinline__ void gemm_phase(const int WID, LAS unsigned char* lds, const Gemm g, const StaticOrder& S, const Epi& E) {
;     ...
;     PG8_STAGE(PG8_SB(0, 0), cB, voffB); PG8_STAGE(PG8_SA(0, 0), cA, voffA); PG8_STAGE(PG8_SB(0, 1), cB + hstep, voffB); PG8_STAGE(PG8_SA(0, 1), cA + hstep, voffA);
;     if (wr == 1) PG8_BAR;
;     PG8_WAIT_V(4); PG8_BAR;
;     PG8_STAGE(PG8_SB(1, 0), cB + kstep, voffB); PG8_STAGE(PG8_SA(1, 0), cA + kstep, voffA); PG8_STAGE(PG8_SB(1, 1), cB + hstep + kstep, voffB);
;     PG8_WAIT_V(6); PG8_BAR;
.LBB0_661:
	v_and_b32_e32 v16, 15, v14
	v_or_b32_e32 v17, s22, v16
	v_lshlrev_b32_e32 v18, 6, v17
	v_and_b32_e32 v19, 48, v14
	s_movk_i32 s0, 0x3c0
	v_and_or_b32 v18, v18, s0, v19
	v_and_b32_e32 v15, 0xfffffc00, v15
	v_readlane_b32 s0, v254, 17
	s_add_i32 m0, s23, 0x18000
	s_waitcnt vmcnt(0)
	s_barrier
	v_add_u32_e32 v20, s0, v15
	v_readlane_b32 s0, v254, 18
	s_add_i32 s29, s23, 0x8000
	s_add_i32 s34, s23, 0xa000
	v_add_u32_e32 v15, s0, v15
	s_mov_b64 s[0:1], 0x80
	v_lshl_add_u64 v[6:7], v[6:7], 0, s[0:1]
	global_load_lds_dwordx4 v[6:7], off
	v_lshl_add_u64 v[4:5], v[4:5], 0, s[0:1]
	s_add_i32 m0, s23, 0x1a000
	v_lshl_add_u64 v[2:3], v[2:3], 0, s[0:1]
	global_load_lds_dwordx4 v[4:5], off
	s_mov_b32 m0, s29
	s_add_u32 s8, s42, 0x80080
	global_load_lds_dwordx4 v[2:3], off
	v_lshl_add_u64 v[0:1], v[0:1], 0, s[0:1]
	s_mov_b32 m0, s34
	s_addc_u32 s9, s43, 0
	global_load_lds_dwordx4 v[0:1], off
	v_lshl_add_u64 v[0:1], s[8:9], 0, v[178:179]
	s_add_i32 m0, s23, 0x1c000
	v_lshlrev_b32_e32 v17, 2, v17
	global_load_lds_dwordx4 v[0:1], off
	v_lshl_add_u64 v[0:1], s[8:9], 0, v[182:183]
	s_add_i32 m0, s23, 0x1e000
	v_lshlrev_b32_e32 v14, 2, v14
	global_load_lds_dwordx4 v[0:1], off
	v_lshlrev_b32_e32 v0, 15, v8
	v_and_b32_e32 v0, 0xffff0000, v0
	v_lshl_add_u32 v0, v9, 12, v0
	v_and_b32_e32 v1, 1, v8
	v_lshl_or_b32 v0, v1, 6, v0
	v_lshl_add_u32 v184, v10, 1, v0
	v_lshlrev_b32_e32 v0, 15, v11
	v_and_b32_e32 v0, 0xffff0000, v0
	v_and_b32_e32 v17, 32, v17
	v_lshl_or_b32 v16, v16, 6, v19
	v_and_b32_e32 v14, 32, v14
	s_waitcnt vmcnt(6)
	v_lshl_add_u32 v0, v12, 12, v0
	v_and_b32_e32 v1, 1, v11
	v_bitop3_b32 v17, v18, v20, v17 bitop3:0xde
	v_bitop3_b32 v205, v16, v15, v14 bitop3:0xde
	v_lshl_or_b32 v0, v1, 6, v0
	s_add_i32 s35, 0, 0x10000
	s_add_i32 s48, 0, 0x14000
	s_mov_b32 s3, 0
	v_mov_b32_e32 v185, v179
	v_lshl_add_u32 v186, v13, 1, v0
	v_mov_b32_e32 v187, v179
	v_mov_b64_e32 v[188:189], 0x200
	v_mov_b64_e32 v[190:191], 0x1ff
	v_add_u32_e32 v206, s35, v205
	v_add_u32_e32 v207, 0, v17
	v_add_u32_e32 v208, s48, v205
	s_mov_b32 s49, 0
	s_barrier
	s_branch .LBB0_663

; #define PG8_STAGE(bufoff, gbase, voff) do { _Pragma("unroll") for (int _i = 0; _i < 2; ++_i) \
;         __builtin_amdgcn_global_load_lds((const unsigned*)((const char*)(gbase) + (voff)[_i]), (LAS unsigned*)(lds + (bufoff) + ldsw + _i * 8192), 16, 0, 0); } while (0)
; #define PG8_LDA(dst, b, h) do { _Pragma("unroll") for (int m = 0; m < 4; ++m) _Pragma("unroll") for (int k = 0; k < 2; ++k) dst[m][k] = *(const LAS bf16x8*)(lds + PG8_SA(b, h) + aoff + m * 2048 + k * 1024); } while (0)
; #define PG8_LDB(dst, b, h) do { _Pragma("unroll") for (int n = 0; n < 2; ++n) _Pragma("unroll") for (int k = 0; k < 2; ++k) dst[n][k] = *(const LAS bf16x8*)(lds + PG8_SB(b, h) + boff + n * 2048 + k * 1024); } while (0)
; #define PG8_MMA(ai, bj, At, Bt) do { __builtin_amdgcn_s_setprio(1); _Pragma("unroll") for (int m = 0; m < 4; ++m) _Pragma("unroll") for (int n = 0; n < 2; ++n) _Pragma("unroll") for (int k = 0; k < 2; ++k) \
;         acc[ai][bj][m][n] = __builtin_amdgcn_mfma_f32_16x16x32_bf16(Bt[n][k], At[m][k], acc[ai][bj][m][n], 0, 0, 0); __builtin_amdgcn_s_setprio(0); } while (0)
; #define PG8_WAIT_V(n) asm volatile("s_waitcnt vmcnt(" #n ")" ::: "memory")
; #define PG8_WAIT_L(n) asm volatile("s_waitcnt lgkmcnt(" #n ")" ::: "memory")
; #define PG8_BAR __builtin_amdgcn_s_barrier()
; #define PG8_SCHED __builtin_amdgcn_sched_barrier(0)
; template <class Epi, bool KS0 = false>
; __device__ __forceinline__ void gemm_phase(const int WID, LAS unsigned char* lds, const Gemm g, const StaticOrder& S, const Epi& E) {
;     ...
;             PG8_LDB(B0, 0, 0); PG8_SCHED; PG8_LDA(At, 0, 0); PG8_STAGE(PG8_SA(1, 1), a1 + hstep, voffA);
;             PG8_WAIT_L(8); PG8_BAR; PG8_WAIT_L(0); PG8_MMA(0, 0, At, B0); PG8_BAR; PG8_SCHED;
;             PG8_LDB(B1, 0, 1); PG8_STAGE(PG8_SB(0, 0), b2, voffB);
;             PG8_BAR; PG8_WAIT_L(0); PG8_MMA(0, 1, At, B1); PG8_BAR;
;             PG8_LDA(At, 0, 1); PG8_STAGE(PG8_SA(0, 0), a2, voffA);
;             PG8_BAR; PG8_WAIT_L(0); PG8_MMA(1, 0, At, B0); PG8_BAR; PG8_SCHED;
;             PG8_STAGE(PG8_SB(0, 1), b2 + hstep, voffB);
;             PG8_WAIT_V(6); PG8_BAR; PG8_MMA(1, 1, At, B1); PG8_BAR;
.LBB0_670:
	ds_read_b128 v[128:131], v206
	ds_read_b128 v[132:135], v206 offset:1024
	ds_read_b128 v[136:139], v206 offset:2048
	ds_read_b128 v[140:143], v206 offset:3072
	ds_read_b128 v[144:147], v207
	ds_read_b128 v[148:151], v207 offset:1024
	ds_read_b128 v[152:155], v207 offset:2048
	ds_read_b128 v[156:159], v207 offset:3072
	ds_read_b128 v[160:163], v207 offset:4096
	ds_read_b128 v[164:167], v207 offset:5120
	ds_read_b128 v[168:171], v207 offset:6144
	ds_read_b128 v[172:175], v207 offset:7168
	ds_read_b128 v[192:195], v208
	ds_read_b128 v[196:199], v208 offset:1024
	ds_read_b128 v[200:203], v208 offset:2048
	ds_read_b128 v[210:213], v208 offset:3072
	s_add_u32 s42, s20, 0xfff80080
	s_addc_u32 s43, s21, -1
	s_cmp_eq_u32 s53, 28
	s_cselect_b32 s45, s11, s43
	s_cselect_b32 s44, s19, s42
	s_cselect_b32 s43, s9, s52
	s_cselect_b32 s42, s50, s51
	s_add_i32 m0, s23, 0xc000
	s_nop 0
	global_load_lds_dwordx4 v184, s[20:21]
	s_add_i32 m0, s23, 0xe000
	s_nop 0
	global_load_lds_dwordx4 v186, s[20:21]
	s_waitcnt vmcnt(8) lgkmcnt(0)
	s_barrier
	s_waitcnt lgkmcnt(0)
	v_mfma_f32_16x16x32_bf16 v[124:127], v[128:131], v[144:147], v[124:127]
	v_mfma_f32_16x16x32_bf16 v[120:123], v[136:139], v[144:147], v[120:123]
	v_mfma_f32_16x16x32_bf16 v[108:111], v[128:131], v[152:155], v[108:111]
	v_mfma_f32_16x16x32_bf16 v[104:107], v[136:139], v[152:155], v[104:107]
	v_mfma_f32_16x16x32_bf16 v[92:95], v[128:131], v[160:163], v[92:95]
	v_mfma_f32_16x16x32_bf16 v[88:91], v[136:139], v[160:163], v[88:91]
	v_mfma_f32_16x16x32_bf16 v[76:79], v[128:131], v[168:171], v[76:79]
	v_mfma_f32_16x16x32_bf16 v[72:75], v[136:139], v[168:171], v[72:75]
	v_mfma_f32_16x16x32_bf16 v[124:127], v[132:135], v[148:151], v[124:127]
	v_mfma_f32_16x16x32_bf16 v[120:123], v[140:143], v[148:151], v[120:123]
	v_mfma_f32_16x16x32_bf16 v[108:111], v[132:135], v[156:159], v[108:111]
	v_mfma_f32_16x16x32_bf16 v[104:107], v[140:143], v[156:159], v[104:107]
	v_mfma_f32_16x16x32_bf16 v[92:95], v[132:135], v[164:167], v[92:95]
	v_mfma_f32_16x16x32_bf16 v[88:91], v[140:143], v[164:167], v[88:91]
	v_mfma_f32_16x16x32_bf16 v[76:79], v[132:135], v[172:175], v[76:79]
	v_mfma_f32_16x16x32_bf16 v[72:75], v[140:143], v[172:175], v[72:75]
	v_mfma_f32_16x16x32_bf16 v[116:119], v[192:195], v[144:147], v[116:119]
	v_mfma_f32_16x16x32_bf16 v[112:115], v[200:203], v[144:147], v[112:115]
	v_mfma_f32_16x16x32_bf16 v[100:103], v[192:195], v[152:155], v[100:103]
	v_mfma_f32_16x16x32_bf16 v[96:99], v[200:203], v[152:155], v[96:99]
	v_mfma_f32_16x16x32_bf16 v[84:87], v[192:195], v[160:163], v[84:87]
	v_mfma_f32_16x16x32_bf16 v[80:83], v[200:203], v[160:163], v[80:83]
	v_mfma_f32_16x16x32_bf16 v[68:71], v[192:195], v[168:171], v[68:71]
	v_mfma_f32_16x16x32_bf16 v[64:67], v[200:203], v[168:171], v[64:67]
	v_mfma_f32_16x16x32_bf16 v[116:119], v[196:199], v[148:151], v[116:119]
	v_mfma_f32_16x16x32_bf16 v[112:115], v[210:213], v[148:151], v[112:115]
	v_mfma_f32_16x16x32_bf16 v[100:103], v[196:199], v[156:159], v[100:103]
	v_mfma_f32_16x16x32_bf16 v[96:99], v[210:213], v[156:159], v[96:99]
	v_mfma_f32_16x16x32_bf16 v[84:87], v[196:199], v[164:167], v[84:87]
	v_mfma_f32_16x16x32_bf16 v[80:83], v[210:213], v[164:167], v[80:83]
	v_mfma_f32_16x16x32_bf16 v[68:71], v[196:199], v[172:175], v[68:71]
	v_mfma_f32_16x16x32_bf16 v[64:67], v[210:213], v[172:175], v[64:67]
	s_barrier
	ds_read_b128 v[144:147], v207 offset:16384
	ds_read_b128 v[148:151], v207 offset:17408
	ds_read_b128 v[152:155], v207 offset:18432
	ds_read_b128 v[156:159], v207 offset:19456
	ds_read_b128 v[160:163], v207 offset:20480
	ds_read_b128 v[164:167], v207 offset:21504
	ds_read_b128 v[168:171], v207 offset:22528
	ds_read_b128 v[172:175], v207 offset:23552
	s_add_i32 s54, s35, s26
	s_add_u32 s98, s42, s0
	s_addc_u32 s99, s43, s1
	s_mov_b32 m0, s54
	s_nop 0
	global_load_lds_dwordx4 v178, s[42:43]
	s_add_i32 m0, s54, 0x2000
	s_nop 0
	global_load_lds_dwordx4 v182, s[42:43]
	s_mov_b32 m0, s23
	s_add_u32 s100, s44, s0
	s_addc_u32 s101, s45, s1
	global_load_lds_dwordx4 v176, s[44:45]
	s_mov_b32 m0, s24
	s_nop 0
	global_load_lds_dwordx4 v180, s[44:45]
	s_add_u32 s54, s42, 0x80000
	s_addc_u32 s55, s43, 0
	s_add_i32 s58, s48, s26
	s_mov_b32 m0, s58
	s_nop 0
	global_load_lds_dwordx4 v178, s[54:55]
	s_add_i32 m0, s58, 0x2000
	s_nop 0
	global_load_lds_dwordx4 v182, s[54:55]
	s_waitcnt vmcnt(8) lgkmcnt(0)
	s_barrier
	s_waitcnt lgkmcnt(0)
	v_mfma_f32_16x16x32_bf16 v[60:63], v[128:131], v[144:147], v[60:63]
	v_mfma_f32_16x16x32_bf16 v[56:59], v[136:139], v[144:147], v[56:59]
	v_mfma_f32_16x16x32_bf16 v[44:47], v[128:131], v[152:155], v[44:47]
	v_mfma_f32_16x16x32_bf16 v[40:43], v[136:139], v[152:155], v[40:43]
	v_mfma_f32_16x16x32_bf16 v[28:31], v[128:131], v[160:163], v[28:31]
	v_mfma_f32_16x16x32_bf16 v[24:27], v[136:139], v[160:163], v[24:27]
	v_mfma_f32_16x16x32_bf16 v[12:15], v[128:131], v[168:171], v[12:15]
	v_mfma_f32_16x16x32_bf16 v[8:11], v[136:139], v[168:171], v[8:11]
	v_mfma_f32_16x16x32_bf16 v[60:63], v[132:135], v[148:151], v[60:63]
	v_mfma_f32_16x16x32_bf16 v[56:59], v[140:143], v[148:151], v[56:59]
	v_mfma_f32_16x16x32_bf16 v[44:47], v[132:135], v[156:159], v[44:47]
	v_mfma_f32_16x16x32_bf16 v[40:43], v[140:143], v[156:159], v[40:43]
	v_mfma_f32_16x16x32_bf16 v[28:31], v[132:135], v[164:167], v[28:31]
	v_mfma_f32_16x16x32_bf16 v[24:27], v[140:143], v[164:167], v[24:27]
	v_mfma_f32_16x16x32_bf16 v[12:15], v[132:135], v[172:175], v[12:15]
	v_mfma_f32_16x16x32_bf16 v[8:11], v[140:143], v[172:175], v[8:11]
	v_mfma_f32_16x16x32_bf16 v[52:55], v[192:195], v[144:147], v[52:55]
	v_mfma_f32_16x16x32_bf16 v[48:51], v[200:203], v[144:147], v[48:51]
	v_mfma_f32_16x16x32_bf16 v[36:39], v[192:195], v[152:155], v[36:39]
	v_mfma_f32_16x16x32_bf16 v[32:35], v[200:203], v[152:155], v[32:35]
	v_mfma_f32_16x16x32_bf16 v[20:23], v[192:195], v[160:163], v[20:23]
	v_mfma_f32_16x16x32_bf16 v[16:19], v[200:203], v[160:163], v[16:19]
	v_mfma_f32_16x16x32_bf16 v[4:7], v[192:195], v[168:171], v[4:7]
	v_mfma_f32_16x16x32_bf16 v[0:3], v[200:203], v[168:171], v[0:3]
	v_mfma_f32_16x16x32_bf16 v[52:55], v[196:199], v[148:151], v[52:55]
	v_mfma_f32_16x16x32_bf16 v[48:51], v[210:213], v[148:151], v[48:51]
	v_mfma_f32_16x16x32_bf16 v[36:39], v[196:199], v[156:159], v[36:39]
	v_mfma_f32_16x16x32_bf16 v[32:35], v[210:213], v[156:159], v[32:35]
	v_mfma_f32_16x16x32_bf16 v[20:23], v[196:199], v[164:167], v[20:23]
	v_mfma_f32_16x16x32_bf16 v[16:19], v[210:213], v[164:167], v[16:19]
	v_mfma_f32_16x16x32_bf16 v[4:7], v[196:199], v[172:175], v[4:7]
	v_mfma_f32_16x16x32_bf16 v[0:3], v[210:213], v[172:175], v[0:3]
	s_barrier
; #define PG8_STAGE(bufoff, gbase, voff) do { _Pragma("unroll") for (int _i = 0; _i < 2; ++_i) \
;         __builtin_amdgcn_global_load_lds((const unsigned*)((const char*)(gbase) + (voff)[_i]), (LAS unsigned*)(lds + (bufoff) + ldsw + _i * 8192), 16, 0, 0); } while (0)
; #define PG8_LDA(dst, b, h) do { _Pragma("unroll") for (int m = 0; m < 4; ++m) _Pragma("unroll") for (int k = 0; k < 2; ++k) dst[m][k] = *(const LAS bf16x8*)(lds + PG8_SA(b, h) + aoff + m * 2048 + k * 1024); } while (0)
; #define PG8_LDB(dst, b, h) do { _Pragma("unroll") for (int n = 0; n < 2; ++n) _Pragma("unroll") for (int k = 0; k < 2; ++k) dst[n][k] = *(const LAS bf16x8*)(lds + PG8_SB(b, h) + boff + n * 2048 + k * 1024); } while (0)
; #define PG8_MMA(ai, bj, At, Bt) do { __builtin_amdgcn_s_setprio(1); _Pragma("unroll") for (int m = 0; m < 4; ++m) _Pragma("unroll") for (int n = 0; n < 2; ++n) _Pragma("unroll") for (int k = 0; k < 2; ++k) \
;         acc[ai][bj][m][n] = __builtin_amdgcn_mfma_f32_16x16x32_bf16(Bt[n][k], At[m][k], acc[ai][bj][m][n], 0, 0, 0); __builtin_amdgcn_s_setprio(0); } while (0)
; #define PG8_WAIT_V(n) asm volatile("s_waitcnt vmcnt(" #n ")" ::: "memory")
; #define PG8_WAIT_L(n) asm volatile("s_waitcnt lgkmcnt(" #n ")" ::: "memory")
; #define PG8_BAR __builtin_amdgcn_s_barrier()
; #define PG8_SCHED __builtin_amdgcn_sched_barrier(0)
; template <class Epi, bool KS0 = false>
; __device__ __forceinline__ void gemm_phase(const int WID, LAS unsigned char* lds, const Gemm g, const StaticOrder& S, const Epi& E) {
;     ...
;             PG8_LDB(B0, 1, 0); PG8_SCHED; PG8_LDA(At, 1, 0); PG8_STAGE(PG8_SA(0, 1), a2 + hstep, voffA);
;             PG8_WAIT_L(8); PG8_BAR; PG8_WAIT_L(0); PG8_MMA(0, 0, At, B0); PG8_BAR; PG8_SCHED;
;             PG8_LDB(B1, 1, 1); PG8_STAGE(PG8_SB(1, 0), b3, voffB);
;             PG8_BAR; PG8_WAIT_L(0); PG8_MMA(0, 1, At, B1); PG8_BAR;
;             PG8_LDA(At, 1, 1); PG8_STAGE(PG8_SA(1, 0), a3, voffA);
;             PG8_BAR; PG8_WAIT_L(0); PG8_MMA(1, 0, At, B0); PG8_BAR; PG8_SCHED;
;             PG8_STAGE(PG8_SB(1, 1), b3 + hstep, voffB);
;             PG8_WAIT_V(6); PG8_BAR; PG8_MMA(1, 1, At, B1); PG8_BAR;
	v_add_u32_e32 v128, 0x18000, v205
	ds_read_b128 v[132:135], v128 offset:1024
	ds_read_b128 v[136:139], v128 offset:2048
	ds_read_b128 v[140:143], v128 offset:3072
	ds_read_b128 v[128:131], v128
	ds_read_b128 v[144:147], v207 offset:32768
	ds_read_b128 v[148:151], v207 offset:33792
	ds_read_b128 v[152:155], v207 offset:34816
	ds_read_b128 v[156:159], v207 offset:35840
	ds_read_b128 v[160:163], v207 offset:36864
	ds_read_b128 v[164:167], v207 offset:37888
	ds_read_b128 v[168:171], v207 offset:38912
	ds_read_b128 v[172:175], v207 offset:39936
	v_add_u32_e32 v210, 0x1c000, v205
	ds_read_b128 v[192:195], v210
	ds_read_b128 v[196:199], v210 offset:1024
	ds_read_b128 v[200:203], v210 offset:2048
	ds_read_b128 v[210:213], v210 offset:3072
	s_add_i32 s54, 0, 0x18000
	s_add_u32 s44, s44, 0x80000
	s_addc_u32 s45, s45, 0
	s_mov_b32 m0, s25
	s_nop 0
	global_load_lds_dwordx4 v176, s[44:45]
	s_mov_b32 m0, s28
	s_nop 0
	global_load_lds_dwordx4 v180, s[44:45]
	s_waitcnt vmcnt(8) lgkmcnt(0)
	s_barrier
	s_waitcnt lgkmcnt(0)
	v_mfma_f32_16x16x32_bf16 v[124:127], v[128:131], v[144:147], v[124:127]
	v_mfma_f32_16x16x32_bf16 v[120:123], v[136:139], v[144:147], v[120:123]
	v_mfma_f32_16x16x32_bf16 v[108:111], v[128:131], v[152:155], v[108:111]
	v_mfma_f32_16x16x32_bf16 v[104:107], v[136:139], v[152:155], v[104:107]
	v_mfma_f32_16x16x32_bf16 v[92:95], v[128:131], v[160:163], v[92:95]
	v_mfma_f32_16x16x32_bf16 v[88:91], v[136:139], v[160:163], v[88:91]
	v_mfma_f32_16x16x32_bf16 v[76:79], v[128:131], v[168:171], v[76:79]
	v_mfma_f32_16x16x32_bf16 v[72:75], v[136:139], v[168:171], v[72:75]
	v_mfma_f32_16x16x32_bf16 v[124:127], v[132:135], v[148:151], v[124:127]
	v_mfma_f32_16x16x32_bf16 v[120:123], v[140:143], v[148:151], v[120:123]
	v_mfma_f32_16x16x32_bf16 v[108:111], v[132:135], v[156:159], v[108:111]
	v_mfma_f32_16x16x32_bf16 v[104:107], v[140:143], v[156:159], v[104:107]
	v_mfma_f32_16x16x32_bf16 v[92:95], v[132:135], v[164:167], v[92:95]
	v_mfma_f32_16x16x32_bf16 v[88:91], v[140:143], v[164:167], v[88:91]
	v_mfma_f32_16x16x32_bf16 v[76:79], v[132:135], v[172:175], v[76:79]
	v_mfma_f32_16x16x32_bf16 v[72:75], v[140:143], v[172:175], v[72:75]
	v_mfma_f32_16x16x32_bf16 v[116:119], v[192:195], v[144:147], v[116:119]
	v_mfma_f32_16x16x32_bf16 v[112:115], v[200:203], v[144:147], v[112:115]
	v_mfma_f32_16x16x32_bf16 v[100:103], v[192:195], v[152:155], v[100:103]
	v_mfma_f32_16x16x32_bf16 v[96:99], v[200:203], v[152:155], v[96:99]
	v_mfma_f32_16x16x32_bf16 v[84:87], v[192:195], v[160:163], v[84:87]
	v_mfma_f32_16x16x32_bf16 v[80:83], v[200:203], v[160:163], v[80:83]
	v_mfma_f32_16x16x32_bf16 v[68:71], v[192:195], v[168:171], v[68:71]
	v_mfma_f32_16x16x32_bf16 v[64:67], v[200:203], v[168:171], v[64:67]
	v_mfma_f32_16x16x32_bf16 v[116:119], v[196:199], v[148:151], v[116:119]
	v_mfma_f32_16x16x32_bf16 v[112:115], v[210:213], v[148:151], v[112:115]
	v_mfma_f32_16x16x32_bf16 v[100:103], v[196:199], v[156:159], v[100:103]
	v_mfma_f32_16x16x32_bf16 v[96:99], v[210:213], v[156:159], v[96:99]
	v_mfma_f32_16x16x32_bf16 v[84:87], v[196:199], v[164:167], v[84:87]
	v_mfma_f32_16x16x32_bf16 v[80:83], v[210:213], v[164:167], v[80:83]
	v_mfma_f32_16x16x32_bf16 v[68:71], v[196:199], v[172:175], v[68:71]
	v_mfma_f32_16x16x32_bf16 v[64:67], v[210:213], v[172:175], v[64:67]
	s_barrier
	ds_read_b128 v[144:147], v207 offset:49152
	ds_read_b128 v[148:151], v207 offset:50176
	ds_read_b128 v[152:155], v207 offset:51200
	ds_read_b128 v[156:159], v207 offset:52224
	ds_read_b128 v[160:163], v207 offset:53248
	ds_read_b128 v[164:167], v207 offset:54272
	ds_read_b128 v[168:171], v207 offset:55296
	ds_read_b128 v[172:175], v207 offset:56320
	s_add_i32 s44, 0, 0x1c000
	s_add_i32 s45, s54, s26
	s_mov_b32 m0, s45
	s_nop 0
	global_load_lds_dwordx4 v178, s[98:99]
	s_add_i32 m0, s45, 0x2000
	s_nop 0
	global_load_lds_dwordx4 v182, s[98:99]
	s_mov_b32 m0, s29
	s_nop 0
	global_load_lds_dwordx4 v176, s[100:101]
	s_mov_b32 m0, s34
	s_nop 0
	global_load_lds_dwordx4 v180, s[100:101]
	s_add_u32 s42, s42, 0x80080
	s_addc_u32 s43, s43, 0
	s_add_i32 s44, s44, s26
	s_mov_b32 m0, s44
	s_nop 0
	global_load_lds_dwordx4 v178, s[42:43]
	s_add_i32 m0, s44, 0x2000
	s_nop 0
	global_load_lds_dwordx4 v182, s[42:43]
	s_waitcnt vmcnt(8) lgkmcnt(0)
	s_barrier
	s_waitcnt lgkmcnt(0)
	v_mfma_f32_16x16x32_bf16 v[60:63], v[128:131], v[144:147], v[60:63]
	v_mfma_f32_16x16x32_bf16 v[56:59], v[136:139], v[144:147], v[56:59]
	s_add_i32 s53, s53, 2
	s_add_u32 s20, s20, 0x100
	s_addc_u32 s21, s21, 0
	s_add_u32 s51, s51, 0x100
	s_addc_u32 s52, s52, 0
	s_cmp_gt_u32 s53, 29
	v_mfma_f32_16x16x32_bf16 v[44:47], v[128:131], v[152:155], v[44:47]
	v_mfma_f32_16x16x32_bf16 v[40:43], v[136:139], v[152:155], v[40:43]
	v_mfma_f32_16x16x32_bf16 v[28:31], v[128:131], v[160:163], v[28:31]
	v_mfma_f32_16x16x32_bf16 v[24:27], v[136:139], v[160:163], v[24:27]
	v_mfma_f32_16x16x32_bf16 v[12:15], v[128:131], v[168:171], v[12:15]
	v_mfma_f32_16x16x32_bf16 v[8:11], v[136:139], v[168:171], v[8:11]
	v_mfma_f32_16x16x32_bf16 v[60:63], v[132:135], v[148:151], v[60:63]
	v_mfma_f32_16x16x32_bf16 v[56:59], v[140:143], v[148:151], v[56:59]
	v_mfma_f32_16x16x32_bf16 v[44:47], v[132:135], v[156:159], v[44:47]
	v_mfma_f32_16x16x32_bf16 v[40:43], v[140:143], v[156:159], v[40:43]
	v_mfma_f32_16x16x32_bf16 v[28:31], v[132:135], v[164:167], v[28:31]
	v_mfma_f32_16x16x32_bf16 v[24:27], v[140:143], v[164:167], v[24:27]
	v_mfma_f32_16x16x32_bf16 v[12:15], v[132:135], v[172:175], v[12:15]
	v_mfma_f32_16x16x32_bf16 v[8:11], v[140:143], v[172:175], v[8:11]
	v_mfma_f32_16x16x32_bf16 v[52:55], v[192:195], v[144:147], v[52:55]
	v_mfma_f32_16x16x32_bf16 v[48:51], v[200:203], v[144:147], v[48:51]
	v_mfma_f32_16x16x32_bf16 v[36:39], v[192:195], v[152:155], v[36:39]
	v_mfma_f32_16x16x32_bf16 v[32:35], v[200:203], v[152:155], v[32:35]
	v_mfma_f32_16x16x32_bf16 v[20:23], v[192:195], v[160:163], v[20:23]
	v_mfma_f32_16x16x32_bf16 v[16:19], v[200:203], v[160:163], v[16:19]
	v_mfma_f32_16x16x32_bf16 v[4:7], v[192:195], v[168:171], v[4:7]
	v_mfma_f32_16x16x32_bf16 v[0:3], v[200:203], v[168:171], v[0:3]
	v_mfma_f32_16x16x32_bf16 v[52:55], v[196:199], v[148:151], v[52:55]
	v_mfma_f32_16x16x32_bf16 v[48:51], v[210:213], v[148:151], v[48:51]
	v_mfma_f32_16x16x32_bf16 v[36:39], v[196:199], v[156:159], v[36:39]
	v_mfma_f32_16x16x32_bf16 v[32:35], v[210:213], v[156:159], v[32:35]
	v_mfma_f32_16x16x32_bf16 v[20:23], v[196:199], v[164:167], v[20:23]
	v_mfma_f32_16x16x32_bf16 v[16:19], v[210:213], v[164:167], v[16:19]
	v_mfma_f32_16x16x32_bf16 v[4:7], v[196:199], v[172:175], v[4:7]
	v_mfma_f32_16x16x32_bf16 v[0:3], v[210:213], v[172:175], v[0:3]
	s_barrier
; __device__ __forceinline__ unsigned cvt_pk_bf16(float lo, float hi) { unsigned r; asm volatile("v_cvt_pk_bf16_f32 %0, %1, %2" : "=v"(r) : "v"(lo), "v"(hi)); return r; }
; __device__ __forceinline__ float bflo(unsigned w) { return __uint_as_float(w << 16); }
; __device__ __forceinline__ float bfhi(unsigned w) { return __uint_as_float(w & 0xffff0000u); }
;     __device__ __forceinline__ void operator()(f32x4 (&acc)[2][2][4][2], const Unit& u, int wr, int wc, int fr, int fq) const {
;         const int row0 = u.pm * BM + wr * 64 + fr, col0 = u.pn * BM + wc * 32 + 8 * fq;
; #pragma unroll
;         for (int ai = 0; ai < 2; ++ai) {
;             f32x4 r[4][2][2];
; #pragma unroll
;             for (int m = 0; m < 4; ++m)
; #pragma unroll
;                 for (int bj = 0; bj < 2; ++bj) { const size_t o = (size_t)(row0 + ai * HALF + m * 16) * DM + col0 + bj * HALF;
;                     if (RB) { const u32x4 w = *(const u32x4*)((const bf16_t*)res + o); r[m][bj][0] = (f32x4){bflo(w.x), bfhi(w.x), bflo(w.y), bfhi(w.y)}; r[m][bj][1] = (f32x4){bflo(w.z), bfhi(w.z), bflo(w.w), bfhi(w.w)}; }
;                     else { r[m][bj][0] = __builtin_nontemporal_load((const f32x4*)((const float*)res + o)); r[m][bj][1] = __builtin_nontemporal_load((const f32x4*)((const float*)res + o + 4)); } }
; #pragma unroll
;             for (int m = 0; m < 4; ++m) { const int row = row0 + ai * HALF + m * 16; const size_t off = (size_t)row * DM + col0; float s = 0.f;
; #pragma unroll
;                 for (int bj = 0; bj < 2; ++bj) { const f32x4 v0 = acc[ai][bj][m][0] + r[m][bj][0], v1 = acc[ai][bj][m][1] + r[m][bj][1];
;                     u32x4 w; w.x = cvt_pk_bf16(v0[0], v0[1]); w.y = cvt_pk_bf16(v0[2], v0[3]); w.z = cvt_pk_bf16(v1[0], v1[1]); w.w = cvt_pk_bf16(v1[2], v1[3]);
;                     *(u32x4*)(outb + off + bj * HALF) = w;
;                     s += ((v0[0] * v0[0] + v0[1] * v0[1]) + (v0[2] * v0[2] + v0[3] * v0[3])) + ((v1[0] * v1[0] + v1[1] * v1[1]) + (v1[2] * v1[2] + v1[3] * v1[3])); }
;                 s += __shfl_xor(s, 16); s += __shfl_xor(s, 32);
;                 if (fq == 0) ssq[(size_t)row * 32 + u.pn * 4 + wc] = s; }
	s_cbranch_scc0 .LBB0_670
	s_waitcnt lgkmcnt(0)
	v_mbcnt_lo_u32_b32 v128, -1, 0
	v_mbcnt_hi_u32_b32 v128, -1, v128
	s_lshl_b32 s9, s18, 8
	v_ashrrev_i32_e32 v210, 4, v128
	v_and_b32_e32 v128, 15, v128
	s_add_i32 s9, s9, s22
	v_readlane_b32 s11, v254, 19
	v_add_u32_e32 v194, s9, v128
	s_lshl_b32 s9, s2, 8
	s_or_b32 s9, s9, s11
	v_lshl_add_u32 v192, v210, 3, s9
	v_ashrrev_i32_e32 v193, 31, v192
	v_ashrrev_i32_e32 v195, 31, v194
	v_lshl_add_u64 v[196:197], v[192:193], 2, s[56:57]
	v_lshlrev_b64 v[128:129], 13, v[194:195]
	v_lshl_add_u64 v[128:129], v[196:197], 0, v[128:129]
	global_load_dwordx4 v[212:215], v[128:129], off nt
	global_load_dwordx4 v[216:219], v[128:129], off offset:16 nt
	global_load_dwordx4 v[220:223], v[128:129], off offset:512 nt
	global_load_dwordx4 v[224:227], v[128:129], off offset:528 nt
	v_add_u32_e32 v202, 16, v194
	v_add_u32_e32 v200, 32, v194
	v_add_u32_e32 v198, 48, v194
	v_ashrrev_i32_e32 v203, 31, v202
	v_ashrrev_i32_e32 v201, 31, v200
	v_ashrrev_i32_e32 v199, 31, v198
	v_lshlrev_b64 v[128:129], 13, v[202:203]
	v_lshlrev_b64 v[130:131], 13, v[200:201]
	v_lshlrev_b64 v[132:133], 13, v[198:199]
	v_lshl_add_u64 v[128:129], v[196:197], 0, v[128:129]
	v_lshl_add_u64 v[130:131], v[196:197], 0, v[130:131]
	v_lshl_add_u64 v[132:133], v[196:197], 0, v[132:133]
	global_load_dwordx4 v[168:171], v[128:129], off offset:16 nt
	global_load_dwordx4 v[172:175], v[128:129], off nt
	global_load_dwordx4 v[160:163], v[128:129], off offset:528 nt
	global_load_dwordx4 v[164:167], v[128:129], off offset:512 nt
	global_load_dwordx4 v[152:155], v[130:131], off offset:16 nt
	global_load_dwordx4 v[156:159], v[130:131], off nt
	global_load_dwordx4 v[144:147], v[130:131], off offset:528 nt
	global_load_dwordx4 v[148:151], v[130:131], off offset:512 nt
	global_load_dwordx4 v[136:139], v[132:133], off offset:16 nt
	global_load_dwordx4 v[140:143], v[132:133], off nt
	s_nop 0
	global_load_dwordx4 v[128:131], v[132:133], off offset:528 nt
	s_nop 0
	global_load_dwordx4 v[132:135], v[132:133], off offset:512 nt
	v_and_b32_e32 v228, 64, v209
	v_xor_b32_e32 v211, 16, v209
	v_add_u32_e32 v228, 64, v228
	v_xor_b32_e32 v229, 32, v209
	v_cmp_lt_i32_e32 vcc, v211, v228
	s_lshl_b32 s18, s2, 2
	s_ashr_i32 s19, s18, 31
	v_cndmask_b32_e32 v211, v209, v211, vcc
	v_cmp_lt_i32_e32 vcc, v229, v228
	s_waitcnt vmcnt(0)
	v_pk_add_f32 v[126:127], v[126:127], v[214:215]
	v_pk_add_f32 v[124:125], v[124:125], v[212:213]
	v_pk_add_f32 v[122:123], v[122:123], v[218:219]
	v_pk_add_f32 v[120:121], v[120:121], v[216:217]
	v_pk_add_f32 v[118:119], v[118:119], v[222:223]
	v_pk_add_f32 v[116:117], v[116:117], v[220:221]
	v_pk_add_f32 v[212:213], v[114:115], v[226:227]
	v_pk_add_f32 v[214:215], v[112:113], v[224:225]
	v_cndmask_b32_e32 v230, v209, v229, vcc
	v_cmp_eq_u32_e32 vcc, 0, v210
	v_lshlrev_b32_e32 v210, 2, v211
	v_cvt_pk_bf16_f32 v112, v124, v125
	v_cvt_pk_bf16_f32 v113, v126, v127
	v_mul_f32_e32 v114, v125, v125
	v_mul_f32_e32 v115, v127, v127
	v_mul_f32_e32 v125, v121, v121
	v_mul_f32_e32 v127, v123, v123
	v_mul_f32_e32 v211, v117, v117
	v_mul_f32_e32 v216, v119, v119
	v_mul_f32_e32 v217, v215, v215
	v_mul_f32_e32 v218, v213, v213
	v_fmac_f32_e32 v114, v124, v124
	v_fmac_f32_e32 v115, v126, v126
	v_fmac_f32_e32 v125, v120, v120
	v_fmac_f32_e32 v127, v122, v122
	v_fmac_f32_e32 v211, v116, v116
	v_fmac_f32_e32 v216, v118, v118
	v_fmac_f32_e32 v217, v214, v214
	v_fmac_f32_e32 v218, v212, v212
	v_add_f32_e32 v114, v114, v115
	v_add_f32_e32 v115, v125, v127
	v_add_f32_e32 v124, v211, v216
	v_add_f32_e32 v125, v217, v218
	v_add_f32_e32 v114, v114, v115
	v_add_f32_e32 v115, v124, v125
	v_add_f32_e32 v124, v114, v115
	ds_bpermute_b32 v125, v210, v124
	v_lshlrev_b64 v[228:229], 12, v[194:195]
	v_lshl_add_u64 v[228:229], s[6:7], 0, v[228:229]
	v_lshl_add_u64 v[228:229], v[192:193], 1, v[228:229]
	v_cvt_pk_bf16_f32 v114, v120, v121
	v_cvt_pk_bf16_f32 v115, v122, v123
	global_store_dwordx4 v[228:229], v[112:115], off
	v_lshlrev_b32_e32 v120, 2, v230
	s_waitcnt lgkmcnt(0)
	v_add_f32_e32 v112, v124, v125
	ds_bpermute_b32 v113, v120, v112
	v_cvt_pk_bf16_f32 v114, v116, v117
	v_cvt_pk_bf16_f32 v115, v118, v119
	v_cvt_pk_bf16_f32 v116, v214, v215
	v_cvt_pk_bf16_f32 v117, v212, v213
	global_store_dwordx4 v[228:229], v[114:117], off offset:256
	s_and_saveexec_b64 s[20:21], vcc
	s_cbranch_execz .LBB0_673
	v_lshlrev_b64 v[114:115], 7, v[194:195]
	v_lshl_add_u64 v[114:115], s[16:17], 0, v[114:115]
	v_lshl_add_u64 v[114:115], s[18:19], 2, v[114:115]
	s_lshl_b32 s2, s27, 2
	v_lshl_add_u64 v[114:115], v[114:115], 0, s[2:3]
	s_waitcnt lgkmcnt(0)
	v_add_f32_e32 v112, v112, v113
	global_store_dword v[114:115], v112, off

; #define LAS __attribute__((address_space(3)))
; #define PG8_STAGE(bufoff, gbase, voff) do { _Pragma("unroll") for (int _i = 0; _i < 2; ++_i) \
;         __builtin_amdgcn_global_load_lds((const unsigned*)((const char*)(gbase) + (voff)[_i]), (LAS unsigned*)(lds + (bufoff) + ldsw + _i * 8192), 16, 0, 0); } while (0)
; #define PG8_WAIT_V(n) asm volatile("s_waitcnt vmcnt(" #n ")" ::: "memory")
; #define PG8_BAR __builtin_amdgcn_s_barrier()
; template <class Epi, bool KS0 = false>
; __device__ __forceinline__ void gemm_phase(const int WID, LAS unsigned char* lds, const Gemm g, const StaticOrder& S, const Epi& E) {
;     ...
;     PG8_STAGE(PG8_SB(0, 0), cB, voffB); PG8_STAGE(PG8_SA(0, 0), cA, voffA); PG8_STAGE(PG8_SB(0, 1), cB + hstep, voffB); PG8_STAGE(PG8_SA(0, 1), cA + hstep, voffA);
;     if (wr == 1) PG8_BAR;
;     PG8_WAIT_V(4); PG8_BAR;
;     PG8_STAGE(PG8_SB(1, 0), cB + kstep, voffB); PG8_STAGE(PG8_SA(1, 0), cA + kstep, voffA); PG8_STAGE(PG8_SB(1, 1), cB + hstep + kstep, voffB);
;     PG8_WAIT_V(6); PG8_BAR;
;     __device__ __forceinline__ void operator()(f32x4 (&acc)[2][2][4][2], const Unit& u, int wr, int wc, int fr, int fq) const {
;     ...
;         LAS float* myc = cws + wv * 256;
.LBB0_772:
	s_lshl_b32 s14, s81, 9
	s_add_i32 s93, s93, 0x3ffff2
	v_lshlrev_b32_e32 v16, 11, v204
	s_add_u32 s34, s76, 0xb000
	v_add_u32_e32 v16, 0, v16
	s_addc_u32 s35, s77, 0
	s_add_u32 s48, s76, 0x16000
	v_add_u32_e32 v172, 0x1f800, v16
	v_add_u32_e32 v173, 0x20800, v16
	v_and_b32_e32 v16, 15, v14
	s_addc_u32 s49, s77, 0
	s_add_i32 s21, s14, 0
	v_readlane_b32 s14, v251, 39
	v_or_b32_e32 v17, s22, v16
	s_add_i32 s25, s14, 0
	v_lshlrev_b32_e32 v18, 6, v17
	v_and_b32_e32 v19, 48, v14
	s_movk_i32 s14, 0x3c0
	s_mov_b64 s[50:51], 0x80
	v_and_or_b32 v18, v18, s14, v19
	v_and_b32_e32 v15, 0xfffffc00, v15
	v_readlane_b32 s14, v254, 17
	v_lshl_add_u64 v[6:7], v[6:7], 0, s[50:51]
	s_add_i32 m0, s9, 0x18000
	s_add_i32 s21, s21, 0x24000
	s_add_i32 s25, s25, 0x25000
	s_add_i32 s60, s9, 0x22000
	v_add_u32_e32 v20, s14, v15
	v_readlane_b32 s14, v254, 18
	s_waitcnt vmcnt(0)
	s_barrier
	global_load_lds_dwordx4 v[6:7], off
	v_lshl_add_u64 v[4:5], v[4:5], 0, s[50:51]
	s_add_i32 m0, s9, 0x1a000
	s_add_i32 s61, s9, 0x8000
	s_add_i32 s62, s9, 0xa000
	v_add_u32_e32 v15, s14, v15
	global_load_lds_dwordx4 v[4:5], off
	v_lshl_add_u64 v[2:3], v[2:3], 0, s[50:51]
	s_mov_b32 m0, s61
	s_add_u32 s14, s12, 0x80080
	global_load_lds_dwordx4 v[2:3], off
	v_lshl_add_u64 v[0:1], v[0:1], 0, s[50:51]
	s_mov_b32 m0, s62
	s_addc_u32 s15, s13, 0
	global_load_lds_dwordx4 v[0:1], off
	v_lshl_add_u64 v[0:1], s[14:15], 0, v[140:141]
	s_add_i32 m0, s9, 0x1c000
	v_lshlrev_b32_e32 v17, 2, v17
	global_load_lds_dwordx4 v[0:1], off
	v_lshl_add_u64 v[0:1], s[14:15], 0, v[142:143]
	s_add_i32 m0, s9, 0x1e000
	v_lshlrev_b32_e32 v14, 2, v14
	global_load_lds_dwordx4 v[0:1], off
	v_lshlrev_b32_e32 v0, 15, v8
	v_and_b32_e32 v0, 0xffff0000, v0
	v_lshl_add_u32 v0, v9, 12, v0
	v_and_b32_e32 v1, 1, v8
	v_lshl_or_b32 v0, v1, 6, v0
	v_lshl_add_u32 v144, v10, 1, v0
	v_lshlrev_b32_e32 v0, 15, v11
	v_and_b32_e32 v0, 0xffff0000, v0
	v_and_b32_e32 v17, 32, v17
	v_lshl_or_b32 v16, v16, 6, v19
	v_and_b32_e32 v14, 32, v14
	s_waitcnt vmcnt(6)
	v_lshl_add_u32 v0, v12, 12, v0
	v_and_b32_e32 v1, 1, v11
	v_bitop3_b32 v17, v18, v20, v17 bitop3:0xde
	v_bitop3_b32 v174, v16, v15, v14 bitop3:0xde
	v_lshl_or_b32 v0, v1, 6, v0
	s_add_i32 s63, 0, 0x10000
	s_add_i32 s64, 0, 0x14000
	v_mov_b32_e32 v145, v141
	v_lshl_add_u32 v146, v13, 1, v0
	v_mov_b32_e32 v147, v141
	v_mov_b64_e32 v[148:149], 0xb00
	v_mov_b64_e32 v[150:151], 0xaff
	v_add_u32_e32 v175, s63, v174
	v_add_u32_e32 v176, 0, v17
	v_add_u32_e32 v177, s64, v174
	v_mov_b32_e32 v178, 0x358637bd
	s_mov_b32 s65, 0x800000
	s_add_i32 s66, 0, 0x20000
	s_add_i32 s67, 0, 0x21000
	s_mov_b32 s68, 0xb000
	s_movk_i32 s69, 0x2c00
	s_barrier
	s_branch .LBB0_774

; #define PG8_STAGE(bufoff, gbase, voff) do { _Pragma("unroll") for (int _i = 0; _i < 2; ++_i) \
;         __builtin_amdgcn_global_load_lds((const unsigned*)((const char*)(gbase) + (voff)[_i]), (LAS unsigned*)(lds + (bufoff) + ldsw + _i * 8192), 16, 0, 0); } while (0)
; #define PG8_LDA(dst, b, h) do { _Pragma("unroll") for (int m = 0; m < 4; ++m) _Pragma("unroll") for (int k = 0; k < 2; ++k) dst[m][k] = *(const LAS bf16x8*)(lds + PG8_SA(b, h) + aoff + m * 2048 + k * 1024); } while (0)
; #define PG8_LDB(dst, b, h) do { _Pragma("unroll") for (int n = 0; n < 2; ++n) _Pragma("unroll") for (int k = 0; k < 2; ++k) dst[n][k] = *(const LAS bf16x8*)(lds + PG8_SB(b, h) + boff + n * 2048 + k * 1024); } while (0)
; #define PG8_MMA(ai, bj, At, Bt) do { __builtin_amdgcn_s_setprio(1); _Pragma("unroll") for (int m = 0; m < 4; ++m) _Pragma("unroll") for (int n = 0; n < 2; ++n) _Pragma("unroll") for (int k = 0; k < 2; ++k) \
;         acc[ai][bj][m][n] = __builtin_amdgcn_mfma_f32_16x16x32_bf16(Bt[n][k], At[m][k], acc[ai][bj][m][n], 0, 0, 0); __builtin_amdgcn_s_setprio(0); } while (0)
; #define PG8_WAIT_V(n) asm volatile("s_waitcnt vmcnt(" #n ")" ::: "memory")
; #define PG8_WAIT_L(n) asm volatile("s_waitcnt lgkmcnt(" #n ")" ::: "memory")
; #define PG8_BAR __builtin_amdgcn_s_barrier()
; #define PG8_SCHED __builtin_amdgcn_sched_barrier(0)
; template <class Epi, bool KS0 = false>
; __device__ __forceinline__ void gemm_phase(const int WID, LAS unsigned char* lds, const Gemm g, const StaticOrder& S, const Epi& E) {
;     ...
;             PG8_LDB(B0, 0, 0); PG8_SCHED; PG8_LDA(At, 0, 0); PG8_STAGE(PG8_SA(1, 1), a1 + hstep, voffA);
;             PG8_WAIT_L(8); PG8_BAR; PG8_WAIT_L(0); PG8_MMA(0, 0, At, B0); PG8_BAR; PG8_SCHED;
;             PG8_LDB(B1, 0, 1); PG8_STAGE(PG8_SB(0, 0), b2, voffB);
;             PG8_BAR; PG8_WAIT_L(0); PG8_MMA(0, 1, At, B1); PG8_BAR;
;             PG8_LDA(At, 0, 1); PG8_STAGE(PG8_SA(0, 0), a2, voffA);
;             PG8_BAR; PG8_WAIT_L(0); PG8_MMA(1, 0, At, B0); PG8_BAR; PG8_SCHED;
;             PG8_STAGE(PG8_SB(0, 1), b2 + hstep, voffB);
;             PG8_WAIT_V(6); PG8_BAR; PG8_MMA(1, 1, At, B1); PG8_BAR;
.LBB0_777:
	ds_read_b128 v[108:111], v175
	ds_read_b128 v[132:135], v175 offset:1024
	ds_read_b128 v[136:139], v175 offset:2048
	ds_read_b128 v[152:155], v175 offset:3072
	ds_read_b128 v[156:159], v176
	ds_read_b128 v[160:163], v176 offset:1024
	ds_read_b128 v[164:167], v176 offset:2048
	ds_read_b128 v[168:171], v176 offset:3072
	ds_read_b128 v[180:183], v176 offset:4096
	ds_read_b128 v[184:187], v176 offset:5120
	ds_read_b128 v[188:191], v176 offset:6144
	ds_read_b128 v[192:195], v176 offset:7168
	ds_read_b128 v[196:199], v177
	ds_read_b128 v[200:203], v177 offset:1024
	ds_read_b128 v[204:207], v177 offset:2048
	ds_read_b128 v[210:213], v177 offset:3072
	s_add_u32 s12, s2, 0xfff80080
	s_addc_u32 s13, s3, -1
	s_cmp_eq_u32 s53, 28
	s_cselect_b32 s15, s28, s13
	s_cselect_b32 s14, s29, s12
	s_cselect_b32 s13, s42, s45
	s_cselect_b32 s12, s43, s44
	s_add_i32 m0, s9, 0xc000
	s_nop 0
	global_load_lds_dwordx4 v144, s[2:3]
	s_add_i32 m0, s9, 0xe000
	s_nop 0
	global_load_lds_dwordx4 v146, s[2:3]
	s_waitcnt vmcnt(8) lgkmcnt(0)
	s_barrier
	s_waitcnt lgkmcnt(0)
	v_mfma_f32_16x16x32_bf16 v[128:131], v[108:111], v[156:159], v[128:131]
	v_mfma_f32_16x16x32_bf16 v[124:127], v[136:139], v[156:159], v[124:127]
	v_mfma_f32_16x16x32_bf16 v[116:119], v[108:111], v[164:167], v[116:119]
	v_mfma_f32_16x16x32_bf16 v[112:115], v[136:139], v[164:167], v[112:115]
	v_mfma_f32_16x16x32_bf16 v[104:107], v[108:111], v[180:183], v[104:107]
	v_mfma_f32_16x16x32_bf16 v[96:99], v[136:139], v[180:183], v[96:99]
	v_mfma_f32_16x16x32_bf16 v[88:91], v[108:111], v[188:191], v[88:91]
	v_mfma_f32_16x16x32_bf16 v[24:27], v[136:139], v[188:191], v[24:27]
	v_mfma_f32_16x16x32_bf16 v[128:131], v[132:135], v[160:163], v[128:131]
	v_mfma_f32_16x16x32_bf16 v[124:127], v[152:155], v[160:163], v[124:127]
	v_mfma_f32_16x16x32_bf16 v[116:119], v[132:135], v[168:171], v[116:119]
	v_mfma_f32_16x16x32_bf16 v[112:115], v[152:155], v[168:171], v[112:115]
	v_mfma_f32_16x16x32_bf16 v[104:107], v[132:135], v[184:187], v[104:107]
	v_mfma_f32_16x16x32_bf16 v[96:99], v[152:155], v[184:187], v[96:99]
	v_mfma_f32_16x16x32_bf16 v[88:91], v[132:135], v[192:195], v[88:91]
	v_mfma_f32_16x16x32_bf16 v[24:27], v[152:155], v[192:195], v[24:27]
	v_mfma_f32_16x16x32_bf16 v[12:15], v[196:199], v[156:159], v[12:15]
	v_mfma_f32_16x16x32_bf16 v[120:123], v[204:207], v[156:159], v[120:123]
	v_mfma_f32_16x16x32_bf16 v[100:103], v[196:199], v[164:167], v[100:103]
	v_mfma_f32_16x16x32_bf16 v[92:95], v[204:207], v[164:167], v[92:95]
	v_mfma_f32_16x16x32_bf16 v[84:87], v[196:199], v[180:183], v[84:87]
	v_mfma_f32_16x16x32_bf16 v[80:83], v[204:207], v[180:183], v[80:83]
	v_mfma_f32_16x16x32_bf16 v[28:31], v[196:199], v[188:191], v[28:31]
	v_mfma_f32_16x16x32_bf16 v[20:23], v[204:207], v[188:191], v[20:23]
	v_mfma_f32_16x16x32_bf16 v[12:15], v[200:203], v[160:163], v[12:15]
	v_mfma_f32_16x16x32_bf16 v[120:123], v[210:213], v[160:163], v[120:123]
	v_mfma_f32_16x16x32_bf16 v[100:103], v[200:203], v[168:171], v[100:103]
	v_mfma_f32_16x16x32_bf16 v[92:95], v[210:213], v[168:171], v[92:95]
	v_mfma_f32_16x16x32_bf16 v[84:87], v[200:203], v[184:187], v[84:87]
	v_mfma_f32_16x16x32_bf16 v[80:83], v[210:213], v[184:187], v[80:83]
	v_mfma_f32_16x16x32_bf16 v[28:31], v[200:203], v[192:195], v[28:31]
	v_mfma_f32_16x16x32_bf16 v[20:23], v[210:213], v[192:195], v[20:23]
	s_barrier
	ds_read_b128 v[156:159], v176 offset:16384
	ds_read_b128 v[160:163], v176 offset:17408
	ds_read_b128 v[164:167], v176 offset:18432
	ds_read_b128 v[168:171], v176 offset:19456
	ds_read_b128 v[180:183], v176 offset:20480
	ds_read_b128 v[184:187], v176 offset:21504
	ds_read_b128 v[188:191], v176 offset:22528
	ds_read_b128 v[192:195], v176 offset:23552
	s_add_i32 s55, s63, s26
	s_add_u32 s98, s12, s50
	s_addc_u32 s99, s13, s51
	s_mov_b32 m0, s55
	s_nop 0
	global_load_lds_dwordx4 v140, s[12:13]
	s_add_i32 m0, s55, 0x2000
	s_nop 0
	global_load_lds_dwordx4 v142, s[12:13]
	s_mov_b32 m0, s9
	s_add_u32 s100, s14, s50
	s_addc_u32 s101, s15, s51
	global_load_lds_dwordx4 v140, s[14:15]
	s_mov_b32 m0, s11
	s_nop 0
	global_load_lds_dwordx4 v142, s[14:15]
	s_add_u32 s70, s12, 0x80000
	s_addc_u32 s71, s13, 0
	s_add_i32 s55, s64, s26
	s_mov_b32 m0, s55
	s_nop 0
	global_load_lds_dwordx4 v140, s[70:71]
	s_add_i32 m0, s55, 0x2000
	s_nop 0
	global_load_lds_dwordx4 v142, s[70:71]
	s_waitcnt vmcnt(8) lgkmcnt(0)
	s_barrier
	s_waitcnt lgkmcnt(0)
	v_mfma_f32_16x16x32_bf16 v[76:79], v[108:111], v[156:159], v[76:79]
	v_mfma_f32_16x16x32_bf16 v[72:75], v[136:139], v[156:159], v[72:75]
	v_mfma_f32_16x16x32_bf16 v[68:71], v[108:111], v[164:167], v[68:71]
	v_mfma_f32_16x16x32_bf16 v[64:67], v[136:139], v[164:167], v[64:67]
	v_mfma_f32_16x16x32_bf16 v[52:55], v[108:111], v[180:183], v[52:55]
	v_mfma_f32_16x16x32_bf16 v[48:51], v[136:139], v[180:183], v[48:51]
	v_mfma_f32_16x16x32_bf16 v[16:19], v[108:111], v[188:191], v[16:19]
	v_mfma_f32_16x16x32_bf16 v[8:11], v[136:139], v[188:191], v[8:11]
	v_mfma_f32_16x16x32_bf16 v[76:79], v[132:135], v[160:163], v[76:79]
	v_mfma_f32_16x16x32_bf16 v[72:75], v[152:155], v[160:163], v[72:75]
	v_mfma_f32_16x16x32_bf16 v[68:71], v[132:135], v[168:171], v[68:71]
	v_mfma_f32_16x16x32_bf16 v[64:67], v[152:155], v[168:171], v[64:67]
	v_mfma_f32_16x16x32_bf16 v[52:55], v[132:135], v[184:187], v[52:55]
	v_mfma_f32_16x16x32_bf16 v[48:51], v[152:155], v[184:187], v[48:51]
	v_mfma_f32_16x16x32_bf16 v[16:19], v[132:135], v[192:195], v[16:19]
	v_mfma_f32_16x16x32_bf16 v[8:11], v[152:155], v[192:195], v[8:11]
	v_mfma_f32_16x16x32_bf16 v[60:63], v[196:199], v[156:159], v[60:63]
	v_mfma_f32_16x16x32_bf16 v[56:59], v[204:207], v[156:159], v[56:59]
	v_mfma_f32_16x16x32_bf16 v[44:47], v[196:199], v[164:167], v[44:47]
	v_mfma_f32_16x16x32_bf16 v[40:43], v[204:207], v[164:167], v[40:43]
	v_mfma_f32_16x16x32_bf16 v[36:39], v[196:199], v[180:183], v[36:39]
	v_mfma_f32_16x16x32_bf16 v[32:35], v[204:207], v[180:183], v[32:35]
	v_mfma_f32_16x16x32_bf16 v[4:7], v[196:199], v[188:191], v[4:7]
	v_mfma_f32_16x16x32_bf16 v[0:3], v[204:207], v[188:191], v[0:3]
	v_mfma_f32_16x16x32_bf16 v[60:63], v[200:203], v[160:163], v[60:63]
	v_mfma_f32_16x16x32_bf16 v[56:59], v[210:213], v[160:163], v[56:59]
	v_mfma_f32_16x16x32_bf16 v[44:47], v[200:203], v[168:171], v[44:47]
	v_mfma_f32_16x16x32_bf16 v[40:43], v[210:213], v[168:171], v[40:43]
	v_mfma_f32_16x16x32_bf16 v[36:39], v[200:203], v[184:187], v[36:39]
	v_mfma_f32_16x16x32_bf16 v[32:35], v[210:213], v[184:187], v[32:35]
	v_mfma_f32_16x16x32_bf16 v[4:7], v[200:203], v[192:195], v[4:7]
	v_mfma_f32_16x16x32_bf16 v[0:3], v[210:213], v[192:195], v[0:3]
	s_barrier
; #define PG8_STAGE(bufoff, gbase, voff) do { _Pragma("unroll") for (int _i = 0; _i < 2; ++_i) \
;         __builtin_amdgcn_global_load_lds((const unsigned*)((const char*)(gbase) + (voff)[_i]), (LAS unsigned*)(lds + (bufoff) + ldsw + _i * 8192), 16, 0, 0); } while (0)
; #define PG8_LDA(dst, b, h) do { _Pragma("unroll") for (int m = 0; m < 4; ++m) _Pragma("unroll") for (int k = 0; k < 2; ++k) dst[m][k] = *(const LAS bf16x8*)(lds + PG8_SA(b, h) + aoff + m * 2048 + k * 1024); } while (0)
; #define PG8_LDB(dst, b, h) do { _Pragma("unroll") for (int n = 0; n < 2; ++n) _Pragma("unroll") for (int k = 0; k < 2; ++k) dst[n][k] = *(const LAS bf16x8*)(lds + PG8_SB(b, h) + boff + n * 2048 + k * 1024); } while (0)
; #define PG8_MMA(ai, bj, At, Bt) do { __builtin_amdgcn_s_setprio(1); _Pragma("unroll") for (int m = 0; m < 4; ++m) _Pragma("unroll") for (int n = 0; n < 2; ++n) _Pragma("unroll") for (int k = 0; k < 2; ++k) \
;         acc[ai][bj][m][n] = __builtin_amdgcn_mfma_f32_16x16x32_bf16(Bt[n][k], At[m][k], acc[ai][bj][m][n], 0, 0, 0); __builtin_amdgcn_s_setprio(0); } while (0)
; #define PG8_WAIT_V(n) asm volatile("s_waitcnt vmcnt(" #n ")" ::: "memory")
; #define PG8_WAIT_L(n) asm volatile("s_waitcnt lgkmcnt(" #n ")" ::: "memory")
; #define PG8_BAR __builtin_amdgcn_s_barrier()
; #define PG8_SCHED __builtin_amdgcn_sched_barrier(0)
; template <class Epi, bool KS0 = false>
; __device__ __forceinline__ void gemm_phase(const int WID, LAS unsigned char* lds, const Gemm g, const StaticOrder& S, const Epi& E) {
;     ...
;             PG8_LDB(B0, 1, 0); PG8_SCHED; PG8_LDA(At, 1, 0); PG8_STAGE(PG8_SA(0, 1), a2 + hstep, voffA);
;             PG8_WAIT_L(8); PG8_BAR; PG8_WAIT_L(0); PG8_MMA(0, 0, At, B0); PG8_BAR; PG8_SCHED;
;             PG8_LDB(B1, 1, 1); PG8_STAGE(PG8_SB(1, 0), b3, voffB);
;             PG8_BAR; PG8_WAIT_L(0); PG8_MMA(0, 1, At, B1); PG8_BAR;
;             PG8_LDA(At, 1, 1); PG8_STAGE(PG8_SA(1, 0), a3, voffA);
;             PG8_BAR; PG8_WAIT_L(0); PG8_MMA(1, 0, At, B0); PG8_BAR; PG8_SCHED;
;             PG8_STAGE(PG8_SB(1, 1), b3 + hstep, voffB);
;             PG8_WAIT_V(6); PG8_BAR; PG8_MMA(1, 1, At, B1); PG8_BAR;
	v_add_u32_e32 v108, 0x18000, v174
	ds_read_b128 v[132:135], v108 offset:1024
	ds_read_b128 v[136:139], v108 offset:2048
	ds_read_b128 v[152:155], v108 offset:3072
	ds_read_b128 v[108:111], v108
	ds_read_b128 v[156:159], v176 offset:32768
	ds_read_b128 v[160:163], v176 offset:33792
	ds_read_b128 v[164:167], v176 offset:34816
	ds_read_b128 v[168:171], v176 offset:35840
	ds_read_b128 v[180:183], v176 offset:36864
	ds_read_b128 v[184:187], v176 offset:37888
	ds_read_b128 v[188:191], v176 offset:38912
	ds_read_b128 v[192:195], v176 offset:39936
	v_add_u32_e32 v179, 0x1c000, v174
	ds_read_b128 v[196:199], v179
	ds_read_b128 v[200:203], v179 offset:1024
	ds_read_b128 v[204:207], v179 offset:2048
	ds_read_b128 v[210:213], v179 offset:3072
	s_add_i32 s55, 0, 0x18000
	s_add_u32 s14, s14, 0x80000
	s_addc_u32 s15, s15, 0
	s_mov_b32 m0, s18
	s_nop 0
	global_load_lds_dwordx4 v140, s[14:15]
	s_mov_b32 m0, s19
	s_nop 0
	global_load_lds_dwordx4 v142, s[14:15]
	s_waitcnt vmcnt(8) lgkmcnt(0)
	s_barrier
	s_waitcnt lgkmcnt(0)
	v_mfma_f32_16x16x32_bf16 v[128:131], v[108:111], v[156:159], v[128:131]
	v_mfma_f32_16x16x32_bf16 v[124:127], v[136:139], v[156:159], v[124:127]
	v_mfma_f32_16x16x32_bf16 v[116:119], v[108:111], v[164:167], v[116:119]
	v_mfma_f32_16x16x32_bf16 v[112:115], v[136:139], v[164:167], v[112:115]
	v_mfma_f32_16x16x32_bf16 v[104:107], v[108:111], v[180:183], v[104:107]
	v_mfma_f32_16x16x32_bf16 v[96:99], v[136:139], v[180:183], v[96:99]
	v_mfma_f32_16x16x32_bf16 v[88:91], v[108:111], v[188:191], v[88:91]
	v_mfma_f32_16x16x32_bf16 v[24:27], v[136:139], v[188:191], v[24:27]
	v_mfma_f32_16x16x32_bf16 v[128:131], v[132:135], v[160:163], v[128:131]
	v_mfma_f32_16x16x32_bf16 v[124:127], v[152:155], v[160:163], v[124:127]
	v_mfma_f32_16x16x32_bf16 v[116:119], v[132:135], v[168:171], v[116:119]
	v_mfma_f32_16x16x32_bf16 v[112:115], v[152:155], v[168:171], v[112:115]
	v_mfma_f32_16x16x32_bf16 v[104:107], v[132:135], v[184:187], v[104:107]
	v_mfma_f32_16x16x32_bf16 v[96:99], v[152:155], v[184:187], v[96:99]
	v_mfma_f32_16x16x32_bf16 v[88:91], v[132:135], v[192:195], v[88:91]
	v_mfma_f32_16x16x32_bf16 v[24:27], v[152:155], v[192:195], v[24:27]
	v_mfma_f32_16x16x32_bf16 v[12:15], v[196:199], v[156:159], v[12:15]
	v_mfma_f32_16x16x32_bf16 v[120:123], v[204:207], v[156:159], v[120:123]
	v_mfma_f32_16x16x32_bf16 v[100:103], v[196:199], v[164:167], v[100:103]
	v_mfma_f32_16x16x32_bf16 v[92:95], v[204:207], v[164:167], v[92:95]
	v_mfma_f32_16x16x32_bf16 v[84:87], v[196:199], v[180:183], v[84:87]
	v_mfma_f32_16x16x32_bf16 v[80:83], v[204:207], v[180:183], v[80:83]
	v_mfma_f32_16x16x32_bf16 v[28:31], v[196:199], v[188:191], v[28:31]
	v_mfma_f32_16x16x32_bf16 v[20:23], v[204:207], v[188:191], v[20:23]
	v_mfma_f32_16x16x32_bf16 v[12:15], v[200:203], v[160:163], v[12:15]
	v_mfma_f32_16x16x32_bf16 v[120:123], v[210:213], v[160:163], v[120:123]
	v_mfma_f32_16x16x32_bf16 v[100:103], v[200:203], v[168:171], v[100:103]
	v_mfma_f32_16x16x32_bf16 v[92:95], v[210:213], v[168:171], v[92:95]
	v_mfma_f32_16x16x32_bf16 v[84:87], v[200:203], v[184:187], v[84:87]
	v_mfma_f32_16x16x32_bf16 v[80:83], v[210:213], v[184:187], v[80:83]
	v_mfma_f32_16x16x32_bf16 v[28:31], v[200:203], v[192:195], v[28:31]
	v_mfma_f32_16x16x32_bf16 v[20:23], v[210:213], v[192:195], v[20:23]
	s_barrier
	ds_read_b128 v[156:159], v176 offset:49152
	ds_read_b128 v[160:163], v176 offset:50176
	ds_read_b128 v[164:167], v176 offset:51200
	ds_read_b128 v[168:171], v176 offset:52224
	ds_read_b128 v[180:183], v176 offset:53248
	ds_read_b128 v[184:187], v176 offset:54272
	ds_read_b128 v[188:191], v176 offset:55296
	ds_read_b128 v[192:195], v176 offset:56320
	s_add_i32 s14, 0, 0x1c000
	s_add_i32 s15, s55, s26
	s_mov_b32 m0, s15
	s_nop 0
	global_load_lds_dwordx4 v140, s[98:99]
	s_add_i32 m0, s15, 0x2000
	s_nop 0
	global_load_lds_dwordx4 v142, s[98:99]
	s_mov_b32 m0, s61
	s_nop 0
	global_load_lds_dwordx4 v140, s[100:101]
	s_mov_b32 m0, s62
	s_nop 0
	global_load_lds_dwordx4 v142, s[100:101]
	s_add_u32 s12, s12, 0x80080
	s_addc_u32 s13, s13, 0
	s_add_i32 s14, s14, s26
	s_mov_b32 m0, s14
	s_nop 0
	global_load_lds_dwordx4 v140, s[12:13]
	s_add_i32 m0, s14, 0x2000
	s_nop 0
	global_load_lds_dwordx4 v142, s[12:13]
	s_waitcnt vmcnt(8) lgkmcnt(0)
	s_barrier
	s_waitcnt lgkmcnt(0)
	v_mfma_f32_16x16x32_bf16 v[76:79], v[108:111], v[156:159], v[76:79]
	v_mfma_f32_16x16x32_bf16 v[72:75], v[136:139], v[156:159], v[72:75]
	s_add_i32 s53, s53, 2
	s_add_u32 s2, s2, 0x100
	s_addc_u32 s3, s3, 0
	s_add_u32 s44, s44, 0x100
	s_addc_u32 s45, s45, 0
	s_cmp_gt_u32 s53, 29
	v_mfma_f32_16x16x32_bf16 v[68:71], v[108:111], v[164:167], v[68:71]
	v_mfma_f32_16x16x32_bf16 v[64:67], v[136:139], v[164:167], v[64:67]
	v_mfma_f32_16x16x32_bf16 v[52:55], v[108:111], v[180:183], v[52:55]
	v_mfma_f32_16x16x32_bf16 v[48:51], v[136:139], v[180:183], v[48:51]
	v_mfma_f32_16x16x32_bf16 v[16:19], v[108:111], v[188:191], v[16:19]
	v_mfma_f32_16x16x32_bf16 v[8:11], v[136:139], v[188:191], v[8:11]
	v_mfma_f32_16x16x32_bf16 v[76:79], v[132:135], v[160:163], v[76:79]
	v_mfma_f32_16x16x32_bf16 v[72:75], v[152:155], v[160:163], v[72:75]
	v_mfma_f32_16x16x32_bf16 v[68:71], v[132:135], v[168:171], v[68:71]
	v_mfma_f32_16x16x32_bf16 v[64:67], v[152:155], v[168:171], v[64:67]
	v_mfma_f32_16x16x32_bf16 v[52:55], v[132:135], v[184:187], v[52:55]
	v_mfma_f32_16x16x32_bf16 v[48:51], v[152:155], v[184:187], v[48:51]
	v_mfma_f32_16x16x32_bf16 v[16:19], v[132:135], v[192:195], v[16:19]
	v_mfma_f32_16x16x32_bf16 v[8:11], v[152:155], v[192:195], v[8:11]
	v_mfma_f32_16x16x32_bf16 v[60:63], v[196:199], v[156:159], v[60:63]
	v_mfma_f32_16x16x32_bf16 v[56:59], v[204:207], v[156:159], v[56:59]
	v_mfma_f32_16x16x32_bf16 v[44:47], v[196:199], v[164:167], v[44:47]
	v_mfma_f32_16x16x32_bf16 v[40:43], v[204:207], v[164:167], v[40:43]
	v_mfma_f32_16x16x32_bf16 v[36:39], v[196:199], v[180:183], v[36:39]
	v_mfma_f32_16x16x32_bf16 v[32:35], v[204:207], v[180:183], v[32:35]
	v_mfma_f32_16x16x32_bf16 v[4:7], v[196:199], v[188:191], v[4:7]
	v_mfma_f32_16x16x32_bf16 v[0:3], v[204:207], v[188:191], v[0:3]
	v_mfma_f32_16x16x32_bf16 v[60:63], v[200:203], v[160:163], v[60:63]
	v_mfma_f32_16x16x32_bf16 v[56:59], v[210:213], v[160:163], v[56:59]
	v_mfma_f32_16x16x32_bf16 v[44:47], v[200:203], v[168:171], v[44:47]
	v_mfma_f32_16x16x32_bf16 v[40:43], v[210:213], v[168:171], v[40:43]
	v_mfma_f32_16x16x32_bf16 v[36:39], v[200:203], v[184:187], v[36:39]
	v_mfma_f32_16x16x32_bf16 v[32:35], v[210:213], v[184:187], v[32:35]
	v_mfma_f32_16x16x32_bf16 v[4:7], v[200:203], v[192:195], v[4:7]
	v_mfma_f32_16x16x32_bf16 v[0:3], v[210:213], v[192:195], v[0:3]
	s_barrier
; #define LAS __attribute__((address_space(3)))
; __device__ __forceinline__ float row_rstd(const float* ssq, int row, int fq) {
;     const f32x4 a = *(const f32x4*)(ssq + (size_t)row * 32 + 8 * fq), b = *(const f32x4*)(ssq + (size_t)row * 32 + 8 * fq + 4);
;     float t = ((a[0] + a[1]) + (a[2] + a[3])) + ((b[0] + b[1]) + (b[2] + b[3]));
;     t += __shfl_xor(t, 16); t += __shfl_xor(t, 32);
;     return rsqrtf(t * (1.0f / 2048.0f) + EPS);
;     __device__ __forceinline__ void operator()(f32x4 (&acc)[2][2][4][2], const Unit& u, int wr, int wc, int fr, int fq) const {
;         const int rowt = u.pm * BM + wr * 64 + fr, cl0 = wc * 32 + 4 * fq, wv = wr * 4 + wc, ln = fq * 16 + fr;
;         float cwr[4];
; #pragma unroll
;         for (int i = 0; i < 4; ++i) { const float* srcp = (i < 3) ? (cw + (size_t)i * FF2) : cb; cwr[i] = srcp[(ln >> 5) * FF + u.pn * HALF + wc * 32 + (ln & 31)]; }
;         {
;             LAS float* myr = rsl + wv * 128; LAS int* mypm = (LAS int*)(rsl + 1024) + wv;
;             if (__builtin_amdgcn_readfirstlane(*mypm) != u.pm) {
; #pragma unroll
;                 for (int ai = 0; ai < 2; ++ai)
; #pragma unroll
;                     for (int m = 0; m < 4; ++m) { const float r_ = row_rstd(ssq_in, rowt + ai * HALF + m * 16, fq); if (fq == 0) myr[(ai * 4 + m) * 16 + fr] = r_; }
	s_cbranch_scc0 .LBB0_777
	s_waitcnt lgkmcnt(0)
	v_mbcnt_lo_u32_b32 v108, -1, 0
	v_mbcnt_hi_u32_b32 v108, -1, v108
	s_movk_i32 s3, 0x1600
	v_ashrrev_i32_e32 v132, 4, v108
	v_and_b32_e32 v179, 15, v108
	s_lshl_b32 s12, s8, 7
	v_lshl_add_u32 v164, v132, 4, v179
	v_lshrrev_b32_e32 v108, 5, v164
	v_mul_lo_u32 v108, v108, s3
	v_add_u32_e32 v108, s12, v108
	v_and_b32_e32 v109, 31, v164
	v_readlane_b32 s3, v254, 19
	s_lshl_b32 s2, s10, 8
	s_add_i32 s2, s2, s22
	v_or3_b32 v108, v108, v109, s3
	v_ashrrev_i32_e32 v109, 31, v108
	v_lshlrev_b64 v[108:109], 2, v[108:109]
	v_lshl_add_u64 v[110:111], s[76:77], 0, v[108:109]
	global_load_dword v165, v[110:111], off
	v_lshl_add_u64 v[110:111], s[34:35], 0, v[108:109]
	global_load_dword v166, v[110:111], off
	v_lshl_add_u64 v[110:111], s[48:49], 0, v[108:109]
	v_lshl_add_u64 v[108:109], s[78:79], 0, v[108:109]
	global_load_dword v167, v[110:111], off
	global_load_dword v168, v[108:109], off
	v_mov_b32_e32 v108, s25
	ds_read_b32 v108, v108
	v_add_u32_e32 v152, s2, v179
	v_lshl_add_u32 v155, v179, 2, s21
	s_waitcnt lgkmcnt(0)
	v_readfirstlane_b32 s2, v108
	s_cmp_eq_u32 s2, s10
	s_cbranch_scc1 .LBB0_798
	v_lshlrev_b32_e32 v108, 3, v132
	v_ashrrev_i32_e32 v109, 31, v108
	v_ashrrev_i32_e32 v153, 31, v152
	v_lshl_add_u64 v[108:109], v[108:109], 2, s[16:17]
	v_lshlrev_b64 v[110:111], 7, v[152:153]
	v_lshl_add_u64 v[110:111], v[108:109], 0, v[110:111]
	s_mov_b64 s[2:3], 0x1000
	v_lshl_add_u64 v[248:249], v[110:111], 0, s[2:3]
	s_mov_b64 s[2:3], 0x4000
	v_lshl_add_u64 v[134:135], v[110:111], 0, s[2:3]
	s_mov_b64 s[2:3], 0x5000
	v_lshl_add_u64 v[108:109], v[110:111], 0, s[2:3]
	global_load_dwordx4 v[180:183], v[110:111], off
	global_load_dwordx4 v[184:187], v[110:111], off offset:16
	global_load_dwordx4 v[188:191], v[110:111], off offset:2048
	global_load_dwordx4 v[192:195], v[110:111], off offset:2064
	global_load_dwordx4 v[196:199], v[248:249], off
	global_load_dwordx4 v[200:203], v[248:249], off offset:16
	global_load_dwordx4 v[204:207], v[248:249], off offset:2048
	global_load_dwordx4 v[210:213], v[248:249], off offset:2064
	global_load_dwordx4 v[214:217], v[134:135], off
	global_load_dwordx4 v[218:221], v[134:135], off offset:16
	global_load_dwordx4 v[222:225], v[134:135], off offset:2048
	global_load_dwordx4 v[226:229], v[134:135], off offset:2064
	global_load_dwordx4 v[230:233], v[108:109], off
	global_load_dwordx4 v[234:237], v[108:109], off offset:16
	global_load_dwordx4 v[238:241], v[108:109], off offset:2048
	global_load_dwordx4 v[242:245], v[108:109], off offset:2064
	v_and_b32_e32 v250, 64, v209
	v_xor_b32_e32 v133, 16, v209
	v_add_u32_e32 v250, 64, v250
	v_cmp_lt_i32_e32 vcc, v133, v250
	v_xor_b32_e32 v110, 32, v209
	s_nop 1
	v_cndmask_b32_e32 v133, v209, v133, vcc
	v_cmp_eq_u32_e64 s[42:43], 0, v132
	v_lshlrev_b32_e32 v133, 2, v133
	v_cmp_lt_i32_e32 vcc, v110, v250
	s_nop 1
	v_cndmask_b32_e32 v110, v209, v110, vcc
	v_lshlrev_b32_e32 v110, 2, v110
	s_waitcnt vmcnt(14)
	v_add_f32_e32 v180, v180, v181
	v_add_f32_e32 v181, v182, v183
	v_add_f32_e32 v184, v184, v185
	v_add_f32_e32 v185, v186, v187
	v_add_f32_e32 v180, v180, v181
	v_add_f32_e32 v184, v184, v185
	v_add_f32_e32 v156, v180, v184
	s_waitcnt vmcnt(12)
	v_add_f32_e32 v188, v188, v189
	v_add_f32_e32 v189, v190, v191
	v_add_f32_e32 v192, v192, v193
	v_add_f32_e32 v193, v194, v195
	v_add_f32_e32 v188, v188, v189
	v_add_f32_e32 v192, v192, v193
	v_add_f32_e32 v157, v188, v192
	s_waitcnt vmcnt(10)
	v_add_f32_e32 v196, v196, v197
	v_add_f32_e32 v197, v198, v199
	v_add_f32_e32 v200, v200, v201
	v_add_f32_e32 v201, v202, v203
	v_add_f32_e32 v196, v196, v197
	v_add_f32_e32 v200, v200, v201
	v_add_f32_e32 v158, v196, v200
	s_waitcnt vmcnt(8)
	v_add_f32_e32 v204, v204, v205
	v_add_f32_e32 v205, v206, v207
	v_add_f32_e32 v210, v210, v211
	v_add_f32_e32 v211, v212, v213
	v_add_f32_e32 v204, v204, v205
	v_add_f32_e32 v210, v210, v211
	v_add_f32_e32 v159, v204, v210
	s_waitcnt vmcnt(6)
	v_add_f32_e32 v214, v214, v215
	v_add_f32_e32 v215, v216, v217
	v_add_f32_e32 v218, v218, v219
	v_add_f32_e32 v219, v220, v221
	v_add_f32_e32 v214, v214, v215
	v_add_f32_e32 v218, v218, v219
	v_add_f32_e32 v160, v214, v218
	s_waitcnt vmcnt(4)
	v_add_f32_e32 v222, v222, v223
	v_add_f32_e32 v223, v224, v225
	v_add_f32_e32 v226, v226, v227
	v_add_f32_e32 v227, v228, v229
	v_add_f32_e32 v222, v222, v223
	v_add_f32_e32 v226, v226, v227
	v_add_f32_e32 v161, v222, v226
	s_waitcnt vmcnt(2)
	v_add_f32_e32 v230, v230, v231
	v_add_f32_e32 v231, v232, v233
	v_add_f32_e32 v234, v234, v235
	v_add_f32_e32 v235, v236, v237
	v_add_f32_e32 v230, v230, v231
	v_add_f32_e32 v234, v234, v235
	v_add_f32_e32 v162, v230, v234
	s_waitcnt vmcnt(0)
	v_add_f32_e32 v238, v238, v239
	v_add_f32_e32 v239, v240, v241
	v_add_f32_e32 v242, v242, v243
	v_add_f32_e32 v243, v244, v245
	v_add_f32_e32 v238, v238, v239
	v_add_f32_e32 v242, v242, v243
	v_add_f32_e32 v163, v238, v242
	ds_bpermute_b32 v136, v133, v156
	ds_bpermute_b32 v137, v133, v157
	ds_bpermute_b32 v138, v133, v158
	ds_bpermute_b32 v139, v133, v159
	ds_bpermute_b32 v108, v133, v160
	ds_bpermute_b32 v109, v133, v161
	ds_bpermute_b32 v246, v133, v162
	ds_bpermute_b32 v247, v133, v163
	s_waitcnt lgkmcnt(0)
	v_add_f32_e32 v156, v156, v136
	v_add_f32_e32 v157, v157, v137
	v_add_f32_e32 v158, v158, v138
	v_add_f32_e32 v159, v159, v139
	v_add_f32_e32 v160, v160, v108
	v_add_f32_e32 v161, v161, v109
	v_add_f32_e32 v162, v162, v246
	v_add_f32_e32 v163, v163, v247
	ds_bpermute_b32 v136, v110, v156
	ds_bpermute_b32 v137, v110, v157
	ds_bpermute_b32 v138, v110, v158
	ds_bpermute_b32 v139, v110, v159
	ds_bpermute_b32 v108, v110, v160
	ds_bpermute_b32 v109, v110, v161
	ds_bpermute_b32 v246, v110, v162
	ds_bpermute_b32 v247, v110, v163
	s_and_saveexec_b64 s[2:3], s[42:43]
	s_cbranch_execz .Lrs_skip
; __device__ __forceinline__ float row_rstd(const float* ssq, int row, int fq) {
;     ...
;     t += __shfl_xor(t, 16); t += __shfl_xor(t, 32);
;     return rsqrtf(t * (1.0f / 2048.0f) + EPS);
;     __device__ __forceinline__ void operator()(f32x4 (&acc)[2][2][4][2], const Unit& u, int wr, int wc, int fr, int fq) const {
;     ...
;                     for (int m = 0; m < 4; ++m) { const float r_ = row_rstd(ssq_in, rowt + ai * HALF + m * 16, fq); if (fq == 0) myr[(ai * 4 + m) * 16 + fr] = r_; }
	s_waitcnt lgkmcnt(0)
	v_add_f32_e32 v156, v156, v136
	v_fmamk_f32 v156, v156, 0x3a000000, v178
	v_mul_f32_e32 v136, 0x4b800000, v156
	v_cmp_gt_f32_e32 vcc, s65, v156
	s_nop 1
	v_cndmask_b32_e32 v156, v156, v136, vcc
	v_rsq_f32_e32 v156, v156
	s_nop 0
	v_mul_f32_e32 v136, 0x45800000, v156
	v_cndmask_b32_e32 v156, v156, v136, vcc
	ds_write_b32 v155, v156
	v_add_f32_e32 v157, v157, v137
	v_fmamk_f32 v157, v157, 0x3a000000, v178
	v_mul_f32_e32 v137, 0x4b800000, v157
	v_cmp_gt_f32_e32 vcc, s65, v157
	s_nop 1
	v_cndmask_b32_e32 v157, v157, v137, vcc
	v_rsq_f32_e32 v157, v157
	s_nop 0
	v_mul_f32_e32 v137, 0x45800000, v157
	v_cndmask_b32_e32 v157, v157, v137, vcc
	ds_write_b32 v155, v157 offset:64
	v_add_f32_e32 v158, v158, v138
	v_fmamk_f32 v158, v158, 0x3a000000, v178
	v_mul_f32_e32 v138, 0x4b800000, v158
	v_cmp_gt_f32_e32 vcc, s65, v158
	s_nop 1
	v_cndmask_b32_e32 v158, v158, v138, vcc
	v_rsq_f32_e32 v158, v158
	s_nop 0
	v_mul_f32_e32 v138, 0x45800000, v158
	v_cndmask_b32_e32 v158, v158, v138, vcc
	ds_write_b32 v155, v158 offset:128
	v_add_f32_e32 v159, v159, v139
	v_fmamk_f32 v159, v159, 0x3a000000, v178
	v_mul_f32_e32 v139, 0x4b800000, v159
	v_cmp_gt_f32_e32 vcc, s65, v159
	s_nop 1
	v_cndmask_b32_e32 v159, v159, v139, vcc
	v_rsq_f32_e32 v159, v159
	s_nop 0
	v_mul_f32_e32 v139, 0x45800000, v159
	v_cndmask_b32_e32 v159, v159, v139, vcc
	ds_write_b32 v155, v159 offset:192
	v_add_f32_e32 v160, v160, v108
	v_fmamk_f32 v160, v160, 0x3a000000, v178
	v_mul_f32_e32 v108, 0x4b800000, v160
	v_cmp_gt_f32_e32 vcc, s65, v160
	s_nop 1
	v_cndmask_b32_e32 v160, v160, v108, vcc
	v_rsq_f32_e32 v160, v160
	s_nop 0
	v_mul_f32_e32 v108, 0x45800000, v160
	v_cndmask_b32_e32 v160, v160, v108, vcc
	ds_write_b32 v155, v160 offset:256
	v_add_f32_e32 v161, v161, v109
	v_fmamk_f32 v161, v161, 0x3a000000, v178
	v_mul_f32_e32 v109, 0x4b800000, v161
	v_cmp_gt_f32_e32 vcc, s65, v161
	s_nop 1
	v_cndmask_b32_e32 v161, v161, v109, vcc
	v_rsq_f32_e32 v161, v161
	s_nop 0
	v_mul_f32_e32 v109, 0x45800000, v161
	v_cndmask_b32_e32 v161, v161, v109, vcc
	ds_write_b32 v155, v161 offset:320
	v_add_f32_e32 v162, v162, v246
	v_fmamk_f32 v162, v162, 0x3a000000, v178
	v_mul_f32_e32 v246, 0x4b800000, v162
	v_cmp_gt_f32_e32 vcc, s65, v162
	s_nop 1
	v_cndmask_b32_e32 v162, v162, v246, vcc
	v_rsq_f32_e32 v162, v162
	s_nop 0
	v_mul_f32_e32 v246, 0x45800000, v162
	v_cndmask_b32_e32 v162, v162, v246, vcc
	ds_write_b32 v155, v162 offset:384
	v_add_f32_e32 v163, v163, v247
	v_fmamk_f32 v163, v163, 0x3a000000, v178
	v_mul_f32_e32 v247, 0x4b800000, v163
	v_cmp_gt_f32_e32 vcc, s65, v163
	s_nop 1
	v_cndmask_b32_e32 v163, v163, v247, vcc
	v_rsq_f32_e32 v163, v163
	s_nop 0
	v_mul_f32_e32 v247, 0x45800000, v163
	v_cndmask_b32_e32 v163, v163, v247, vcc
	ds_write_b32 v155, v163 offset:448

; #define PG8_STAGE(bufoff, gbase, voff) do { _Pragma("unroll") for (int _i = 0; _i < 2; ++_i) \
;         __builtin_amdgcn_global_load_lds((const unsigned*)((const char*)(gbase) + (voff)[_i]), (LAS unsigned*)(lds + (bufoff) + ldsw + _i * 8192), 16, 0, 0); } while (0)
; #define PG8_WAIT_V(n) asm volatile("s_waitcnt vmcnt(" #n ")" ::: "memory")
; #define PG8_BAR __builtin_amdgcn_s_barrier()
; template <class Epi, bool KS0 = false>
; __device__ __forceinline__ void gemm_phase(const int WID, LAS unsigned char* lds, const Gemm g, const StaticOrder& S, const Epi& E) {
;     ...
;     PG8_STAGE(PG8_SB(0, 0), cB, voffB); PG8_STAGE(PG8_SA(0, 0), cA, voffA); PG8_STAGE(PG8_SB(0, 1), cB + hstep, voffB); PG8_STAGE(PG8_SA(0, 1), cA + hstep, voffA);
;     if (wr == 1) PG8_BAR;
;     PG8_WAIT_V(4); PG8_BAR;
;     PG8_STAGE(PG8_SB(1, 0), cB + kstep, voffB); PG8_STAGE(PG8_SA(1, 0), cA + kstep, voffA); PG8_STAGE(PG8_SB(1, 1), cB + hstep + kstep, voffB);
;     PG8_WAIT_V(6); PG8_BAR;
.LBB0_901:
	v_and_b32_e32 v18, 15, v16
	v_or_b32_e32 v19, s22, v18
	v_lshlrev_b32_e32 v20, 6, v19
	v_and_b32_e32 v21, 48, v16
	s_movk_i32 s10, 0x3c0
	v_and_or_b32 v20, v20, s10, v21
	v_and_b32_e32 v17, 0xfffffc00, v17
	v_readlane_b32 s10, v254, 17
	s_add_i32 m0, s25, 0x18000
	s_waitcnt vmcnt(0)
	s_barrier
	v_add_u32_e32 v22, s10, v17
	v_readlane_b32 s10, v254, 18
	s_add_i32 s45, s25, 0x8000
	s_add_i32 s46, s25, 0xa000
	v_add_u32_e32 v17, s10, v17
	s_mov_b64 s[10:11], 0x80
	v_lshl_add_u64 v[6:7], v[6:7], 0, s[10:11]
	global_load_lds_dwordx4 v[6:7], off
	v_lshl_add_u64 v[4:5], v[4:5], 0, s[10:11]
	s_add_i32 m0, s25, 0x1a000
	v_lshl_add_u64 v[2:3], v[2:3], 0, s[10:11]
	global_load_lds_dwordx4 v[4:5], off
	s_mov_b32 m0, s45
	s_add_u32 s20, s18, 0x160080
	global_load_lds_dwordx4 v[2:3], off
	v_lshl_add_u64 v[0:1], v[0:1], 0, s[10:11]
	s_mov_b32 m0, s46
	s_addc_u32 s21, s19, 0
	global_load_lds_dwordx4 v[0:1], off
	v_lshl_add_u64 v[0:1], s[20:21], 0, v[154:155]
	s_add_i32 m0, s25, 0x1c000
	s_mov_b64 s[14:15], 0x160080
	global_load_lds_dwordx4 v[0:1], off
	v_lshl_add_u64 v[0:1], s[20:21], 0, v[158:159]
	s_add_i32 m0, s25, 0x1e000
	v_lshlrev_b32_e32 v19, 2, v19
	global_load_lds_dwordx4 v[0:1], off
	v_lshrrev_b32_e32 v1, 1, v8
	v_mul_lo_u32 v0, v9, s12
	v_mad_u64_u32 v[0:1], s[20:21], v1, s13, v[0:1]
	v_or_b32_e32 v0, v0, v10
	v_add_lshl_u32 v0, v0, v11, 1
	v_mov_b32_e32 v1, v155
	v_lshl_add_u64 v[160:161], v[0:1], 0, s[14:15]
	v_lshrrev_b32_e32 v1, 1, v12
	v_mul_lo_u32 v0, v13, s12
	v_lshlrev_b32_e32 v16, 2, v16
	v_mad_u64_u32 v[0:1], s[12:13], v1, s13, v[0:1]
	v_and_b32_e32 v19, 32, v19
	v_lshl_or_b32 v18, v18, 6, v21
	v_and_b32_e32 v16, 32, v16
	s_waitcnt vmcnt(6)
	v_or_b32_e32 v0, v0, v14
	v_bitop3_b32 v19, v20, v22, v19 bitop3:0xde
	v_bitop3_b32 v186, v18, v17, v16 bitop3:0xde
	v_add_lshl_u32 v0, v0, v15, 1
	v_mov_b32_e32 v1, v155
	s_add_i32 s47, 0, 0x10000
	s_add_i32 s48, 0, 0x14000
	v_lshl_add_u64 v[162:163], v[0:1], 0, s[14:15]
	v_mov_b64_e32 v[164:165], 0x200
	v_mov_b64_e32 v[166:167], 0x1ff
	v_add_u32_e32 v187, s47, v186
	v_add_u32_e32 v188, 0, v19
	v_add_u32_e32 v189, s48, v186
	s_mov_b32 s49, 0
	s_barrier
	s_branch .LBB0_903

; #define PG8_STAGE(bufoff, gbase, voff) do { _Pragma("unroll") for (int _i = 0; _i < 2; ++_i) \
;         __builtin_amdgcn_global_load_lds((const unsigned*)((const char*)(gbase) + (voff)[_i]), (LAS unsigned*)(lds + (bufoff) + ldsw + _i * 8192), 16, 0, 0); } while (0)
; #define PG8_LDA(dst, b, h) do { _Pragma("unroll") for (int m = 0; m < 4; ++m) _Pragma("unroll") for (int k = 0; k < 2; ++k) dst[m][k] = *(const LAS bf16x8*)(lds + PG8_SA(b, h) + aoff + m * 2048 + k * 1024); } while (0)
; #define PG8_LDB(dst, b, h) do { _Pragma("unroll") for (int n = 0; n < 2; ++n) _Pragma("unroll") for (int k = 0; k < 2; ++k) dst[n][k] = *(const LAS bf16x8*)(lds + PG8_SB(b, h) + boff + n * 2048 + k * 1024); } while (0)
; #define PG8_MMA(ai, bj, At, Bt) do { __builtin_amdgcn_s_setprio(1); _Pragma("unroll") for (int m = 0; m < 4; ++m) _Pragma("unroll") for (int n = 0; n < 2; ++n) _Pragma("unroll") for (int k = 0; k < 2; ++k) \
;         acc[ai][bj][m][n] = __builtin_amdgcn_mfma_f32_16x16x32_bf16(Bt[n][k], At[m][k], acc[ai][bj][m][n], 0, 0, 0); __builtin_amdgcn_s_setprio(0); } while (0)
; #define PG8_WAIT_V(n) asm volatile("s_waitcnt vmcnt(" #n ")" ::: "memory")
; #define PG8_WAIT_L(n) asm volatile("s_waitcnt lgkmcnt(" #n ")" ::: "memory")
; #define PG8_BAR __builtin_amdgcn_s_barrier()
; #define PG8_SCHED __builtin_amdgcn_sched_barrier(0)
; template <class Epi, bool KS0 = false>
; __device__ __forceinline__ void gemm_phase(const int WID, LAS unsigned char* lds, const Gemm g, const StaticOrder& S, const Epi& E) {
;     ...
;             PG8_LDB(B0, 0, 0); PG8_SCHED; PG8_LDA(At, 0, 0); PG8_STAGE(PG8_SA(1, 1), a1 + hstep, voffA);
;             PG8_WAIT_L(8); PG8_BAR; PG8_WAIT_L(0); PG8_MMA(0, 0, At, B0); PG8_BAR; PG8_SCHED;
;             PG8_LDB(B1, 0, 1); PG8_STAGE(PG8_SB(0, 0), b2, voffB);
;             PG8_BAR; PG8_WAIT_L(0); PG8_MMA(0, 1, At, B1); PG8_BAR;
;             PG8_LDA(At, 0, 1); PG8_STAGE(PG8_SA(0, 0), a2, voffA);
;             PG8_BAR; PG8_WAIT_L(0); PG8_MMA(1, 0, At, B0); PG8_BAR; PG8_SCHED;
;             PG8_STAGE(PG8_SB(0, 1), b2 + hstep, voffB);
;             PG8_WAIT_V(6); PG8_BAR; PG8_MMA(1, 1, At, B1); PG8_BAR;
.LBB0_914:
	ds_read_b128 v[128:131], v187
	ds_read_b128 v[132:135], v187 offset:1024
	ds_read_b128 v[136:139], v187 offset:2048
	ds_read_b128 v[140:143], v187 offset:3072
	ds_read_b128 v[144:147], v188
	ds_read_b128 v[148:151], v188 offset:1024
	ds_read_b128 v[168:171], v188 offset:2048
	ds_read_b128 v[172:175], v188 offset:3072
	ds_read_b128 v[176:179], v188 offset:4096
	ds_read_b128 v[180:183], v188 offset:5120
	ds_read_b128 v[190:193], v188 offset:6144
	ds_read_b128 v[194:197], v188 offset:7168
	ds_read_b128 v[198:201], v189
	ds_read_b128 v[202:205], v189 offset:1024
	ds_read_b128 v[210:213], v189 offset:2048
	ds_read_b128 v[214:217], v189 offset:3072
	s_add_u32 s18, s2, 0x100
	s_addc_u32 s19, s3, 0
	s_cmpk_eq_i32 s42, 0x54
	s_cselect_b32 s29, s13, s19
	s_cselect_b32 s28, s12, s18
	s_cselect_b32 s21, s15, s41
	s_cselect_b32 s20, s14, s40
	s_add_i32 m0, s25, 0xc000
	s_nop 0
	global_load_lds_dwordx4 v160, s[2:3]
	s_add_i32 m0, s25, 0xe000
	s_nop 0
	global_load_lds_dwordx4 v162, s[2:3]
	s_waitcnt vmcnt(8) lgkmcnt(0)
	s_barrier
	s_waitcnt lgkmcnt(0)
	v_mfma_f32_16x16x32_bf16 v[124:127], v[128:131], v[144:147], v[124:127]
	v_mfma_f32_16x16x32_bf16 v[120:123], v[136:139], v[144:147], v[120:123]
	v_mfma_f32_16x16x32_bf16 v[108:111], v[128:131], v[168:171], v[108:111]
	v_mfma_f32_16x16x32_bf16 v[104:107], v[136:139], v[168:171], v[104:107]
	v_mfma_f32_16x16x32_bf16 v[92:95], v[128:131], v[176:179], v[92:95]
	v_mfma_f32_16x16x32_bf16 v[88:91], v[136:139], v[176:179], v[88:91]
	v_mfma_f32_16x16x32_bf16 v[76:79], v[128:131], v[190:193], v[76:79]
	v_mfma_f32_16x16x32_bf16 v[72:75], v[136:139], v[190:193], v[72:75]
	v_mfma_f32_16x16x32_bf16 v[124:127], v[132:135], v[148:151], v[124:127]
	v_mfma_f32_16x16x32_bf16 v[120:123], v[140:143], v[148:151], v[120:123]
	v_mfma_f32_16x16x32_bf16 v[108:111], v[132:135], v[172:175], v[108:111]
	v_mfma_f32_16x16x32_bf16 v[104:107], v[140:143], v[172:175], v[104:107]
	v_mfma_f32_16x16x32_bf16 v[92:95], v[132:135], v[180:183], v[92:95]
	v_mfma_f32_16x16x32_bf16 v[88:91], v[140:143], v[180:183], v[88:91]
	v_mfma_f32_16x16x32_bf16 v[76:79], v[132:135], v[194:197], v[76:79]
	v_mfma_f32_16x16x32_bf16 v[72:75], v[140:143], v[194:197], v[72:75]
	v_mfma_f32_16x16x32_bf16 v[116:119], v[198:201], v[144:147], v[116:119]
	v_mfma_f32_16x16x32_bf16 v[112:115], v[210:213], v[144:147], v[112:115]
	v_mfma_f32_16x16x32_bf16 v[100:103], v[198:201], v[168:171], v[100:103]
	v_mfma_f32_16x16x32_bf16 v[96:99], v[210:213], v[168:171], v[96:99]
	v_mfma_f32_16x16x32_bf16 v[84:87], v[198:201], v[176:179], v[84:87]
	v_mfma_f32_16x16x32_bf16 v[80:83], v[210:213], v[176:179], v[80:83]
	v_mfma_f32_16x16x32_bf16 v[68:71], v[198:201], v[190:193], v[68:71]
	v_mfma_f32_16x16x32_bf16 v[64:67], v[210:213], v[190:193], v[64:67]
	v_mfma_f32_16x16x32_bf16 v[116:119], v[202:205], v[148:151], v[116:119]
	v_mfma_f32_16x16x32_bf16 v[112:115], v[214:217], v[148:151], v[112:115]
	v_mfma_f32_16x16x32_bf16 v[100:103], v[202:205], v[172:175], v[100:103]
	v_mfma_f32_16x16x32_bf16 v[96:99], v[214:217], v[172:175], v[96:99]
	v_mfma_f32_16x16x32_bf16 v[84:87], v[202:205], v[180:183], v[84:87]
	v_mfma_f32_16x16x32_bf16 v[80:83], v[214:217], v[180:183], v[80:83]
	v_mfma_f32_16x16x32_bf16 v[68:71], v[202:205], v[194:197], v[68:71]
	v_mfma_f32_16x16x32_bf16 v[64:67], v[214:217], v[194:197], v[64:67]
	s_barrier
	ds_read_b128 v[144:147], v188 offset:16384
	ds_read_b128 v[148:151], v188 offset:17408
	ds_read_b128 v[168:171], v188 offset:18432
	ds_read_b128 v[172:175], v188 offset:19456
	ds_read_b128 v[176:179], v188 offset:20480
	ds_read_b128 v[180:183], v188 offset:21504
	ds_read_b128 v[190:193], v188 offset:22528
	ds_read_b128 v[194:197], v188 offset:23552
	s_add_i32 s2, s47, s26
	s_add_u32 s98, s20, s10
	s_addc_u32 s99, s21, s11
	s_mov_b32 m0, s2
	s_nop 0
	global_load_lds_dwordx4 v154, s[20:21]
	s_add_i32 m0, s2, 0x2000
	s_nop 0
	global_load_lds_dwordx4 v158, s[20:21]
	s_mov_b32 m0, s25
	s_add_u32 s100, s28, s10
	s_addc_u32 s101, s29, s11
	global_load_lds_dwordx4 v152, s[28:29]
	s_mov_b32 m0, s30
	s_nop 0
	global_load_lds_dwordx4 v156, s[28:29]
	s_add_u32 s2, s20, 0x160000
	s_addc_u32 s3, s21, 0
	s_add_i32 s43, s48, s26
	s_mov_b32 m0, s43
	s_nop 0
	global_load_lds_dwordx4 v154, s[2:3]
	s_add_i32 m0, s43, 0x2000
	s_nop 0
	global_load_lds_dwordx4 v158, s[2:3]
	s_waitcnt vmcnt(8) lgkmcnt(0)
	s_barrier
	s_waitcnt lgkmcnt(0)
	v_mfma_f32_16x16x32_bf16 v[60:63], v[128:131], v[144:147], v[60:63]
	v_mfma_f32_16x16x32_bf16 v[56:59], v[136:139], v[144:147], v[56:59]
	v_mfma_f32_16x16x32_bf16 v[44:47], v[128:131], v[168:171], v[44:47]
	v_mfma_f32_16x16x32_bf16 v[40:43], v[136:139], v[168:171], v[40:43]
	v_mfma_f32_16x16x32_bf16 v[28:31], v[128:131], v[176:179], v[28:31]
	v_mfma_f32_16x16x32_bf16 v[24:27], v[136:139], v[176:179], v[24:27]
	v_mfma_f32_16x16x32_bf16 v[12:15], v[128:131], v[190:193], v[12:15]
	v_mfma_f32_16x16x32_bf16 v[8:11], v[136:139], v[190:193], v[8:11]
	v_mfma_f32_16x16x32_bf16 v[60:63], v[132:135], v[148:151], v[60:63]
	v_mfma_f32_16x16x32_bf16 v[56:59], v[140:143], v[148:151], v[56:59]
	v_mfma_f32_16x16x32_bf16 v[44:47], v[132:135], v[172:175], v[44:47]
	v_mfma_f32_16x16x32_bf16 v[40:43], v[140:143], v[172:175], v[40:43]
	v_mfma_f32_16x16x32_bf16 v[28:31], v[132:135], v[180:183], v[28:31]
	v_mfma_f32_16x16x32_bf16 v[24:27], v[140:143], v[180:183], v[24:27]
	v_mfma_f32_16x16x32_bf16 v[12:15], v[132:135], v[194:197], v[12:15]
	v_mfma_f32_16x16x32_bf16 v[8:11], v[140:143], v[194:197], v[8:11]
	v_mfma_f32_16x16x32_bf16 v[52:55], v[198:201], v[144:147], v[52:55]
	v_mfma_f32_16x16x32_bf16 v[48:51], v[210:213], v[144:147], v[48:51]
	v_mfma_f32_16x16x32_bf16 v[36:39], v[198:201], v[168:171], v[36:39]
	v_mfma_f32_16x16x32_bf16 v[32:35], v[210:213], v[168:171], v[32:35]
	v_mfma_f32_16x16x32_bf16 v[20:23], v[198:201], v[176:179], v[20:23]
	v_mfma_f32_16x16x32_bf16 v[16:19], v[210:213], v[176:179], v[16:19]
	v_mfma_f32_16x16x32_bf16 v[4:7], v[198:201], v[190:193], v[4:7]
	v_mfma_f32_16x16x32_bf16 v[0:3], v[210:213], v[190:193], v[0:3]
	v_mfma_f32_16x16x32_bf16 v[52:55], v[202:205], v[148:151], v[52:55]
	v_mfma_f32_16x16x32_bf16 v[48:51], v[214:217], v[148:151], v[48:51]
	v_mfma_f32_16x16x32_bf16 v[36:39], v[202:205], v[172:175], v[36:39]
	v_mfma_f32_16x16x32_bf16 v[32:35], v[214:217], v[172:175], v[32:35]
	v_mfma_f32_16x16x32_bf16 v[20:23], v[202:205], v[180:183], v[20:23]
	v_mfma_f32_16x16x32_bf16 v[16:19], v[214:217], v[180:183], v[16:19]
	v_mfma_f32_16x16x32_bf16 v[4:7], v[202:205], v[194:197], v[4:7]
	v_mfma_f32_16x16x32_bf16 v[0:3], v[214:217], v[194:197], v[0:3]
	s_barrier
; #define PG8_STAGE(bufoff, gbase, voff) do { _Pragma("unroll") for (int _i = 0; _i < 2; ++_i) \
;         __builtin_amdgcn_global_load_lds((const unsigned*)((const char*)(gbase) + (voff)[_i]), (LAS unsigned*)(lds + (bufoff) + ldsw + _i * 8192), 16, 0, 0); } while (0)
; #define PG8_LDA(dst, b, h) do { _Pragma("unroll") for (int m = 0; m < 4; ++m) _Pragma("unroll") for (int k = 0; k < 2; ++k) dst[m][k] = *(const LAS bf16x8*)(lds + PG8_SA(b, h) + aoff + m * 2048 + k * 1024); } while (0)
; #define PG8_LDB(dst, b, h) do { _Pragma("unroll") for (int n = 0; n < 2; ++n) _Pragma("unroll") for (int k = 0; k < 2; ++k) dst[n][k] = *(const LAS bf16x8*)(lds + PG8_SB(b, h) + boff + n * 2048 + k * 1024); } while (0)
; #define PG8_MMA(ai, bj, At, Bt) do { __builtin_amdgcn_s_setprio(1); _Pragma("unroll") for (int m = 0; m < 4; ++m) _Pragma("unroll") for (int n = 0; n < 2; ++n) _Pragma("unroll") for (int k = 0; k < 2; ++k) \
;         acc[ai][bj][m][n] = __builtin_amdgcn_mfma_f32_16x16x32_bf16(Bt[n][k], At[m][k], acc[ai][bj][m][n], 0, 0, 0); __builtin_amdgcn_s_setprio(0); } while (0)
; #define PG8_WAIT_V(n) asm volatile("s_waitcnt vmcnt(" #n ")" ::: "memory")
; #define PG8_WAIT_L(n) asm volatile("s_waitcnt lgkmcnt(" #n ")" ::: "memory")
; #define PG8_BAR __builtin_amdgcn_s_barrier()
; #define PG8_SCHED __builtin_amdgcn_sched_barrier(0)
; template <class Epi, bool KS0 = false>
; __device__ __forceinline__ void gemm_phase(const int WID, LAS unsigned char* lds, const Gemm g, const StaticOrder& S, const Epi& E) {
;     ...
;             PG8_LDB(B0, 1, 0); PG8_SCHED; PG8_LDA(At, 1, 0); PG8_STAGE(PG8_SA(0, 1), a2 + hstep, voffA);
;             PG8_WAIT_L(8); PG8_BAR; PG8_WAIT_L(0); PG8_MMA(0, 0, At, B0); PG8_BAR; PG8_SCHED;
;             PG8_LDB(B1, 1, 1); PG8_STAGE(PG8_SB(1, 0), b3, voffB);
;             PG8_BAR; PG8_WAIT_L(0); PG8_MMA(0, 1, At, B1); PG8_BAR;
;             PG8_LDA(At, 1, 1); PG8_STAGE(PG8_SA(1, 0), a3, voffA);
;             PG8_BAR; PG8_WAIT_L(0); PG8_MMA(1, 0, At, B0); PG8_BAR; PG8_SCHED;
;             PG8_STAGE(PG8_SB(1, 1), b3 + hstep, voffB);
;             PG8_WAIT_V(6); PG8_BAR; PG8_MMA(1, 1, At, B1); PG8_BAR;
	v_add_u32_e32 v128, 0x18000, v186
	ds_read_b128 v[132:135], v128 offset:1024
	ds_read_b128 v[136:139], v128 offset:2048
	ds_read_b128 v[140:143], v128 offset:3072
	ds_read_b128 v[128:131], v128
	ds_read_b128 v[144:147], v188 offset:32768
	ds_read_b128 v[148:151], v188 offset:33792
	ds_read_b128 v[168:171], v188 offset:34816
	ds_read_b128 v[172:175], v188 offset:35840
	ds_read_b128 v[176:179], v188 offset:36864
	ds_read_b128 v[180:183], v188 offset:37888
	ds_read_b128 v[190:193], v188 offset:38912
	ds_read_b128 v[194:197], v188 offset:39936
	v_add_u32_e32 v208, 0x1c000, v186
	ds_read_b128 v[198:201], v208
	ds_read_b128 v[202:205], v208 offset:1024
	ds_read_b128 v[210:213], v208 offset:2048
	ds_read_b128 v[214:217], v208 offset:3072
	s_add_i32 s43, 0, 0x18000
	s_add_u32 s2, s28, 0x160000
	s_addc_u32 s3, s29, 0
	s_mov_b32 m0, s31
	s_nop 0
	global_load_lds_dwordx4 v152, s[2:3]
	s_mov_b32 m0, s44
	s_nop 0
	global_load_lds_dwordx4 v156, s[2:3]
	s_waitcnt vmcnt(8) lgkmcnt(0)
	s_barrier
	s_waitcnt lgkmcnt(0)
	v_mfma_f32_16x16x32_bf16 v[124:127], v[128:131], v[144:147], v[124:127]
	v_mfma_f32_16x16x32_bf16 v[120:123], v[136:139], v[144:147], v[120:123]
	v_mfma_f32_16x16x32_bf16 v[108:111], v[128:131], v[168:171], v[108:111]
	v_mfma_f32_16x16x32_bf16 v[104:107], v[136:139], v[168:171], v[104:107]
	v_mfma_f32_16x16x32_bf16 v[92:95], v[128:131], v[176:179], v[92:95]
	v_mfma_f32_16x16x32_bf16 v[88:91], v[136:139], v[176:179], v[88:91]
	v_mfma_f32_16x16x32_bf16 v[76:79], v[128:131], v[190:193], v[76:79]
	v_mfma_f32_16x16x32_bf16 v[72:75], v[136:139], v[190:193], v[72:75]
	v_mfma_f32_16x16x32_bf16 v[124:127], v[132:135], v[148:151], v[124:127]
	v_mfma_f32_16x16x32_bf16 v[120:123], v[140:143], v[148:151], v[120:123]
	v_mfma_f32_16x16x32_bf16 v[108:111], v[132:135], v[172:175], v[108:111]
	v_mfma_f32_16x16x32_bf16 v[104:107], v[140:143], v[172:175], v[104:107]
	v_mfma_f32_16x16x32_bf16 v[92:95], v[132:135], v[180:183], v[92:95]
	v_mfma_f32_16x16x32_bf16 v[88:91], v[140:143], v[180:183], v[88:91]
	v_mfma_f32_16x16x32_bf16 v[76:79], v[132:135], v[194:197], v[76:79]
	v_mfma_f32_16x16x32_bf16 v[72:75], v[140:143], v[194:197], v[72:75]
	v_mfma_f32_16x16x32_bf16 v[116:119], v[198:201], v[144:147], v[116:119]
	v_mfma_f32_16x16x32_bf16 v[112:115], v[210:213], v[144:147], v[112:115]
	v_mfma_f32_16x16x32_bf16 v[100:103], v[198:201], v[168:171], v[100:103]
	v_mfma_f32_16x16x32_bf16 v[96:99], v[210:213], v[168:171], v[96:99]
	v_mfma_f32_16x16x32_bf16 v[84:87], v[198:201], v[176:179], v[84:87]
	v_mfma_f32_16x16x32_bf16 v[80:83], v[210:213], v[176:179], v[80:83]
	v_mfma_f32_16x16x32_bf16 v[68:71], v[198:201], v[190:193], v[68:71]
	v_mfma_f32_16x16x32_bf16 v[64:67], v[210:213], v[190:193], v[64:67]
	v_mfma_f32_16x16x32_bf16 v[116:119], v[202:205], v[148:151], v[116:119]
	v_mfma_f32_16x16x32_bf16 v[112:115], v[214:217], v[148:151], v[112:115]
	v_mfma_f32_16x16x32_bf16 v[100:103], v[202:205], v[172:175], v[100:103]
	v_mfma_f32_16x16x32_bf16 v[96:99], v[214:217], v[172:175], v[96:99]
	v_mfma_f32_16x16x32_bf16 v[84:87], v[202:205], v[180:183], v[84:87]
	v_mfma_f32_16x16x32_bf16 v[80:83], v[214:217], v[180:183], v[80:83]
	v_mfma_f32_16x16x32_bf16 v[68:71], v[202:205], v[194:197], v[68:71]
	v_mfma_f32_16x16x32_bf16 v[64:67], v[214:217], v[194:197], v[64:67]
	s_barrier
	ds_read_b128 v[144:147], v188 offset:49152
	ds_read_b128 v[148:151], v188 offset:50176
	ds_read_b128 v[168:171], v188 offset:51200
	ds_read_b128 v[172:175], v188 offset:52224
	ds_read_b128 v[176:179], v188 offset:53248
	ds_read_b128 v[180:183], v188 offset:54272
	ds_read_b128 v[190:193], v188 offset:55296
	ds_read_b128 v[194:197], v188 offset:56320
	s_add_i32 s28, 0, 0x1c000
	s_add_i32 s2, s43, s26
	s_mov_b32 m0, s2
	s_nop 0
	global_load_lds_dwordx4 v154, s[98:99]
	s_add_i32 m0, s2, 0x2000
	s_nop 0
	global_load_lds_dwordx4 v158, s[98:99]
	s_mov_b32 m0, s45
	s_nop 0
	global_load_lds_dwordx4 v152, s[100:101]
	s_mov_b32 m0, s46
	s_nop 0
	global_load_lds_dwordx4 v156, s[100:101]
	s_add_u32 s2, s20, 0x160080
	s_addc_u32 s3, s21, 0
	s_add_i32 s20, s28, s26
	s_mov_b32 m0, s20
	s_nop 0
	global_load_lds_dwordx4 v154, s[2:3]
	s_add_i32 m0, s20, 0x2000
	s_nop 0
	global_load_lds_dwordx4 v158, s[2:3]
	s_waitcnt vmcnt(8) lgkmcnt(0)
	s_barrier
	s_waitcnt lgkmcnt(0)
	v_mfma_f32_16x16x32_bf16 v[60:63], v[128:131], v[144:147], v[60:63]
	v_mfma_f32_16x16x32_bf16 v[56:59], v[136:139], v[144:147], v[56:59]
	s_add_i32 s42, s42, 2
	s_add_u32 s40, s40, 0x100
	s_addc_u32 s41, s41, 0
	s_cmpk_gt_u32 s42, 0x55
	s_mov_b64 s[2:3], s[18:19]
	v_mfma_f32_16x16x32_bf16 v[44:47], v[128:131], v[168:171], v[44:47]
	v_mfma_f32_16x16x32_bf16 v[40:43], v[136:139], v[168:171], v[40:43]
	v_mfma_f32_16x16x32_bf16 v[28:31], v[128:131], v[176:179], v[28:31]
	v_mfma_f32_16x16x32_bf16 v[24:27], v[136:139], v[176:179], v[24:27]
	v_mfma_f32_16x16x32_bf16 v[12:15], v[128:131], v[190:193], v[12:15]
	v_mfma_f32_16x16x32_bf16 v[8:11], v[136:139], v[190:193], v[8:11]
	v_mfma_f32_16x16x32_bf16 v[60:63], v[132:135], v[148:151], v[60:63]
	v_mfma_f32_16x16x32_bf16 v[56:59], v[140:143], v[148:151], v[56:59]
	v_mfma_f32_16x16x32_bf16 v[44:47], v[132:135], v[172:175], v[44:47]
	v_mfma_f32_16x16x32_bf16 v[40:43], v[140:143], v[172:175], v[40:43]
	v_mfma_f32_16x16x32_bf16 v[28:31], v[132:135], v[180:183], v[28:31]
	v_mfma_f32_16x16x32_bf16 v[24:27], v[140:143], v[180:183], v[24:27]
	v_mfma_f32_16x16x32_bf16 v[12:15], v[132:135], v[194:197], v[12:15]
	v_mfma_f32_16x16x32_bf16 v[8:11], v[140:143], v[194:197], v[8:11]
	v_mfma_f32_16x16x32_bf16 v[52:55], v[198:201], v[144:147], v[52:55]
	v_mfma_f32_16x16x32_bf16 v[48:51], v[210:213], v[144:147], v[48:51]
	v_mfma_f32_16x16x32_bf16 v[36:39], v[198:201], v[168:171], v[36:39]
	v_mfma_f32_16x16x32_bf16 v[32:35], v[210:213], v[168:171], v[32:35]
	v_mfma_f32_16x16x32_bf16 v[20:23], v[198:201], v[176:179], v[20:23]
	v_mfma_f32_16x16x32_bf16 v[16:19], v[210:213], v[176:179], v[16:19]
	v_mfma_f32_16x16x32_bf16 v[4:7], v[198:201], v[190:193], v[4:7]
	v_mfma_f32_16x16x32_bf16 v[0:3], v[210:213], v[190:193], v[0:3]
	v_mfma_f32_16x16x32_bf16 v[52:55], v[202:205], v[148:151], v[52:55]
	v_mfma_f32_16x16x32_bf16 v[48:51], v[214:217], v[148:151], v[48:51]
	v_mfma_f32_16x16x32_bf16 v[36:39], v[202:205], v[172:175], v[36:39]
	v_mfma_f32_16x16x32_bf16 v[32:35], v[214:217], v[172:175], v[32:35]
	v_mfma_f32_16x16x32_bf16 v[20:23], v[202:205], v[180:183], v[20:23]
	v_mfma_f32_16x16x32_bf16 v[16:19], v[214:217], v[180:183], v[16:19]
	v_mfma_f32_16x16x32_bf16 v[4:7], v[202:205], v[194:197], v[4:7]
	v_mfma_f32_16x16x32_bf16 v[0:3], v[214:217], v[194:197], v[0:3]
	s_barrier
; __device__ __forceinline__ unsigned cvt_pk_bf16(float lo, float hi) { unsigned r; asm volatile("v_cvt_pk_bf16_f32 %0, %1, %2" : "=v"(r) : "v"(lo), "v"(hi)); return r; }
; __device__ __forceinline__ float bflo(unsigned w) { return __uint_as_float(w << 16); }
; __device__ __forceinline__ float bfhi(unsigned w) { return __uint_as_float(w & 0xffff0000u); }
;     __device__ __forceinline__ void operator()(f32x4 (&acc)[2][2][4][2], const Unit& u, int wr, int wc, int fr, int fq) const {
;         const int row0 = u.pm * BM + wr * 64 + fr, col0 = u.pn * BM + wc * 32 + 8 * fq;
; #pragma unroll
;         for (int ai = 0; ai < 2; ++ai) {
;             f32x4 r[4][2][2];
; #pragma unroll
;             for (int m = 0; m < 4; ++m)
; #pragma unroll
;                 for (int bj = 0; bj < 2; ++bj) { const size_t o = (size_t)(row0 + ai * HALF + m * 16) * DM + col0 + bj * HALF;
;                     if (RB) { const u32x4 w = *(const u32x4*)((const bf16_t*)res + o); r[m][bj][0] = (f32x4){bflo(w.x), bfhi(w.x), bflo(w.y), bfhi(w.y)}; r[m][bj][1] = (f32x4){bflo(w.z), bfhi(w.z), bflo(w.w), bfhi(w.w)}; }
;                     else { r[m][bj][0] = __builtin_nontemporal_load((const f32x4*)((const float*)res + o)); r[m][bj][1] = __builtin_nontemporal_load((const f32x4*)((const float*)res + o + 4)); } }
; #pragma unroll
;             for (int m = 0; m < 4; ++m) { const int row = row0 + ai * HALF + m * 16; const size_t off = (size_t)row * DM + col0; float s = 0.f;
; #pragma unroll
;                 for (int bj = 0; bj < 2; ++bj) { const f32x4 v0 = acc[ai][bj][m][0] + r[m][bj][0], v1 = acc[ai][bj][m][1] + r[m][bj][1];
;                     u32x4 w; w.x = cvt_pk_bf16(v0[0], v0[1]); w.y = cvt_pk_bf16(v0[2], v0[3]); w.z = cvt_pk_bf16(v1[0], v1[1]); w.w = cvt_pk_bf16(v1[2], v1[3]);
;                     *(u32x4*)(outb + off + bj * HALF) = w;
;                     s += ((v0[0] * v0[0] + v0[1] * v0[1]) + (v0[2] * v0[2] + v0[3] * v0[3])) + ((v1[0] * v1[0] + v1[1] * v1[1]) + (v1[2] * v1[2] + v1[3] * v1[3])); }
;                 s += __shfl_xor(s, 16); s += __shfl_xor(s, 32);
;                 if (fq == 0) ssq[(size_t)row * 32 + u.pn * 4 + wc] = s; }
	s_cbranch_scc0 .LBB0_914
	s_waitcnt lgkmcnt(0)
	v_mbcnt_lo_u32_b32 v128, -1, 0
	v_mbcnt_hi_u32_b32 v128, -1, v128
	s_lshl_b32 s2, s52, 8
	v_ashrrev_i32_e32 v129, 4, v128
	v_and_b32_e32 v128, 15, v128
	s_add_i32 s2, s2, s22
	v_readlane_b32 s3, v254, 19
	v_add_u32_e32 v172, s2, v128
	s_lshl_b32 s2, s8, 8
	s_or_b32 s2, s2, s3
	v_lshl_add_u32 v168, v129, 3, s2
	v_ashrrev_i32_e32 v169, 31, v168
	v_lshlrev_b64 v[190:191], 1, v[168:169]
	v_ashrrev_i32_e32 v173, 31, v172
	v_lshl_add_u64 v[170:171], s[6:7], 0, v[190:191]
	v_lshlrev_b64 v[192:193], 12, v[172:173]
	v_lshl_add_u64 v[132:133], v[170:171], 0, v[192:193]
	v_cmp_eq_u32_e32 vcc, 0, v129
	global_load_dwordx4 v[128:131], v[132:133], off
	v_add_u32_e32 v182, 16, v172
	v_ashrrev_i32_e32 v183, 31, v182
	v_add_u32_e32 v178, 32, v172
	v_lshlrev_b64 v[184:185], 12, v[182:183]
	v_ashrrev_i32_e32 v179, 31, v178
	v_add_u32_e32 v174, 48, v172
	v_lshlrev_b64 v[180:181], 12, v[178:179]
	v_ashrrev_i32_e32 v175, 31, v174
	v_lshlrev_b64 v[176:177], 12, v[174:175]
	v_lshl_add_u64 v[192:193], s[6:7], 0, v[192:193]
	v_lshl_add_u64 v[190:191], v[192:193], 0, v[190:191]
	s_lshl_b32 s18, s8, 2
	s_ashr_i32 s19, s18, 31
	s_waitcnt vmcnt(0)
	v_lshlrev_b32_e32 v194, 16, v128
	v_and_b32_e32 v195, 0xffff0000, v128
	v_lshlrev_b32_e32 v196, 16, v129
	v_and_b32_e32 v197, 0xffff0000, v129
	v_lshlrev_b32_e32 v198, 16, v130
	v_and_b32_e32 v199, 0xffff0000, v130
	v_lshlrev_b32_e32 v200, 16, v131
	v_and_b32_e32 v201, 0xffff0000, v131
	global_load_dwordx4 v[128:131], v[132:133], off offset:256
	v_pk_add_f32 v[126:127], v[126:127], v[196:197]
	v_pk_add_f32 v[124:125], v[124:125], v[194:195]
	v_pk_add_f32 v[196:197], v[120:121], v[198:199]
	v_pk_add_f32 v[194:195], v[122:123], v[200:201]
	s_waitcnt vmcnt(0)
	v_lshlrev_b32_e32 v202, 16, v128
	v_and_b32_e32 v203, 0xffff0000, v128
	v_lshlrev_b32_e32 v204, 16, v129
	v_and_b32_e32 v205, 0xffff0000, v129
	v_lshl_add_u64 v[128:129], v[170:171], 0, v[184:185]
	global_load_dwordx4 v[148:151], v[128:129], off
	global_load_dwordx4 v[144:147], v[128:129], off offset:256
	v_lshl_add_u64 v[128:129], v[170:171], 0, v[180:181]
	global_load_dwordx4 v[140:143], v[128:129], off
	global_load_dwordx4 v[136:139], v[128:129], off offset:256
	v_lshl_add_u64 v[128:129], v[170:171], 0, v[176:177]
	v_lshlrev_b32_e32 v206, 16, v130
	v_and_b32_e32 v207, 0xffff0000, v130
	v_lshlrev_b32_e32 v210, 16, v131
	v_and_b32_e32 v211, 0xffff0000, v131
	global_load_dwordx4 v[132:135], v[128:129], off
	s_nop 0
	global_load_dwordx4 v[128:131], v[128:129], off offset:256
	v_cvt_pk_bf16_f32 v120, v124, v125
	v_cvt_pk_bf16_f32 v121, v126, v127
	v_cvt_pk_bf16_f32 v122, v196, v197
	v_cvt_pk_bf16_f32 v123, v194, v195
	global_store_dwordx4 v[190:191], v[120:123], off
	v_pk_add_f32 v[118:119], v[118:119], v[204:205]
	v_pk_add_f32 v[116:117], v[116:117], v[202:203]
	v_mul_f32_e32 v120, v125, v125
	v_mul_f32_e32 v121, v127, v127
	v_fmac_f32_e32 v120, v124, v124
	v_fmac_f32_e32 v121, v126, v126
	v_add_f32_e32 v120, v120, v121
	v_mul_f32_e32 v121, v197, v197
	v_mul_f32_e32 v122, v195, v195
	v_fmac_f32_e32 v121, v196, v196
	v_fmac_f32_e32 v122, v194, v194
	v_add_f32_e32 v121, v121, v122
	v_pk_add_f32 v[122:123], v[112:113], v[206:207]
	v_cvt_pk_bf16_f32 v112, v116, v117
	v_cvt_pk_bf16_f32 v113, v118, v119
	v_add_f32_e32 v124, v120, v121
	v_pk_add_f32 v[120:121], v[114:115], v[210:211]
	v_cvt_pk_bf16_f32 v114, v122, v123
	s_nop 0
	v_cvt_pk_bf16_f32 v115, v120, v121
	global_store_dwordx4 v[190:191], v[112:115], off offset:256
	s_nop 1
	v_mul_f32_e32 v112, v117, v117
	v_mul_f32_e32 v113, v119, v119
	v_fmac_f32_e32 v112, v116, v116
	v_fmac_f32_e32 v113, v118, v118
	v_add_f32_e32 v112, v112, v113
	v_mul_f32_e32 v113, v123, v123
	v_mul_f32_e32 v114, v121, v121
	v_fmac_f32_e32 v113, v122, v122
	v_fmac_f32_e32 v114, v120, v120
	v_add_f32_e32 v113, v113, v114
	v_add_f32_e32 v112, v112, v113
	v_and_b32_e32 v114, 64, v209
	v_add_f32_e32 v113, v124, v112
	v_xor_b32_e32 v112, 16, v209
	v_add_u32_e32 v115, 64, v114
	v_cmp_lt_i32_e64 s[2:3], v112, v115
	s_nop 1
	v_cndmask_b32_e64 v112, v209, v112, s[2:3]
	v_lshlrev_b32_e32 v112, 2, v112
	ds_bpermute_b32 v114, v112, v113
	s_waitcnt lgkmcnt(0)
	v_add_f32_e32 v114, v113, v114
	v_xor_b32_e32 v113, 32, v209
	v_cmp_lt_i32_e64 s[2:3], v113, v115
	s_nop 1
	v_cndmask_b32_e64 v113, v209, v113, s[2:3]
	v_lshlrev_b32_e32 v113, 2, v113
	ds_bpermute_b32 v115, v113, v114
	s_and_saveexec_b64 s[2:3], vcc
	s_cbranch_execz .LBB0_917
	v_lshlrev_b64 v[116:117], 7, v[172:173]
	v_lshl_add_u64 v[116:117], s[16:17], 0, v[116:117]
	v_lshl_add_u64 v[116:117], s[18:19], 2, v[116:117]
	s_lshl_b32 s8, s27, 2
	v_lshl_add_u64 v[116:117], v[116:117], 0, s[8:9]
	s_waitcnt lgkmcnt(0)
	v_add_f32_e32 v114, v114, v115
	global_store_dword v[116:117], v114, off

; #define PG8_STAGE(bufoff, gbase, voff) do { _Pragma("unroll") for (int _i = 0; _i < 2; ++_i) \
;         __builtin_amdgcn_global_load_lds((const unsigned*)((const char*)(gbase) + (voff)[_i]), (LAS unsigned*)(lds + (bufoff) + ldsw + _i * 8192), 16, 0, 0); } while (0)
; #define PG8_WAIT_V(n) asm volatile("s_waitcnt vmcnt(" #n ")" ::: "memory")
; #define PG8_BAR __builtin_amdgcn_s_barrier()
; template <class Epi, bool KS0 = false>
; __device__ __forceinline__ void gemm_phase(const int WID, LAS unsigned char* lds, const Gemm g, const StaticOrder& S, const Epi& E) {
;     ...
;     PG8_STAGE(PG8_SB(0, 0), cB, voffB); PG8_STAGE(PG8_SA(0, 0), cA, voffA); PG8_STAGE(PG8_SB(0, 1), cB + hstep, voffB); PG8_STAGE(PG8_SA(0, 1), cA + hstep, voffA);
;     if (wr == 1) PG8_BAR;
;     PG8_WAIT_V(4); PG8_BAR;
;     PG8_STAGE(PG8_SB(1, 0), cB + kstep, voffB); PG8_STAGE(PG8_SA(1, 0), cA + kstep, voffA); PG8_STAGE(PG8_SB(1, 1), cB + hstep + kstep, voffB);
;     PG8_WAIT_V(6); PG8_BAR;
.LBB0_997:
	s_add_u32 s28, s94, 0x1d400000
	s_mov_b64 s[30:31], 0x80
	s_addc_u32 s29, s95, 0
	v_lshl_add_u64 v[6:7], v[6:7], 0, s[30:31]
	s_add_i32 m0, s18, 0x18000
	s_waitcnt vmcnt(0)
	s_barrier
	global_load_lds_dwordx4 v[6:7], off
	v_lshl_add_u64 v[4:5], v[4:5], 0, s[30:31]
	s_add_i32 m0, s18, 0x1a000
	s_add_i32 s25, s18, 0x8000
	s_add_i32 s39, s18, 0xa000
	global_load_lds_dwordx4 v[4:5], off
	v_lshl_add_u64 v[2:3], v[2:3], 0, s[30:31]
	s_mov_b32 m0, s25
	s_add_u32 s12, s10, 0x80080
	global_load_lds_dwordx4 v[2:3], off
	v_lshl_add_u64 v[0:1], v[0:1], 0, s[30:31]
	s_mov_b32 m0, s39
	s_addc_u32 s13, s11, 0
	global_load_lds_dwordx4 v[0:1], off
	v_lshl_add_u64 v[0:1], s[12:13], 0, v[194:195]
	s_add_i32 m0, s18, 0x1c000
	v_and_b32_e32 v16, 15, v14
	global_load_lds_dwordx4 v[0:1], off
	v_lshl_add_u64 v[0:1], s[12:13], 0, v[198:199]
	s_add_i32 m0, s18, 0x1e000
	v_or_b32_e32 v17, s22, v16
	global_load_lds_dwordx4 v[0:1], off
	v_lshlrev_b32_e32 v0, 15, v8
	v_and_b32_e32 v0, 0xffff0000, v0
	v_lshl_add_u32 v0, v9, 12, v0
	v_and_b32_e32 v1, 1, v8
	v_lshlrev_b32_e32 v18, 6, v17
	v_and_b32_e32 v19, 48, v14
	s_movk_i32 s3, 0x3c0
	v_lshl_or_b32 v0, v1, 6, v0
	v_and_or_b32 v18, v18, s3, v19
	v_and_b32_e32 v15, 0xfffffc00, v15
	v_readlane_b32 s3, v254, 17
	v_lshl_add_u32 v200, v10, 1, v0
	v_lshlrev_b32_e32 v0, 15, v11
	v_add_u32_e32 v20, s3, v15
	v_lshlrev_b32_e32 v17, 2, v17
	v_readlane_b32 s3, v254, 18
	v_lshlrev_b32_e32 v14, 2, v14
	v_and_b32_e32 v0, 0xffff0000, v0
	v_and_b32_e32 v17, 32, v17
	v_lshl_or_b32 v16, v16, 6, v19
	v_add_u32_e32 v15, s3, v15
	v_and_b32_e32 v14, 32, v14
	s_waitcnt vmcnt(6)
	v_lshl_add_u32 v0, v12, 12, v0
	v_and_b32_e32 v1, 1, v11
	v_bitop3_b32 v17, v18, v20, v17 bitop3:0xde
	v_bitop3_b32 v245, v16, v15, v14 bitop3:0xde
	v_lshl_or_b32 v0, v1, 6, v0
	s_add_i32 s50, 0, 0x10000
	s_add_i32 s51, 0, 0x14000
	v_mov_b32_e32 v201, v195
	v_lshl_add_u32 v202, v13, 1, v0
	v_mov_b32_e32 v203, v195
	v_mov_b64_e32 v[204:205], 0x200
	v_mov_b64_e32 v[206:207], 0x1ff
	v_add_u32_e32 v246, s50, v245
	v_add_u32_e32 v247, 0, v17
	v_add_u32_e32 v248, s51, v245
	s_mov_b32 s38, 0x3a000000
	s_mov_b32 s52, 0x800000
	v_mov_b32_e32 v208, 0x358637bd
	s_mov_b32 s53, 0
	s_barrier
	s_branch .LBB0_999

; #define PG8_STAGE(bufoff, gbase, voff) do { _Pragma("unroll") for (int _i = 0; _i < 2; ++_i) \
;         __builtin_amdgcn_global_load_lds((const unsigned*)((const char*)(gbase) + (voff)[_i]), (LAS unsigned*)(lds + (bufoff) + ldsw + _i * 8192), 16, 0, 0); } while (0)
; #define PG8_LDA(dst, b, h) do { _Pragma("unroll") for (int m = 0; m < 4; ++m) _Pragma("unroll") for (int k = 0; k < 2; ++k) dst[m][k] = *(const LAS bf16x8*)(lds + PG8_SA(b, h) + aoff + m * 2048 + k * 1024); } while (0)
; #define PG8_LDB(dst, b, h) do { _Pragma("unroll") for (int n = 0; n < 2; ++n) _Pragma("unroll") for (int k = 0; k < 2; ++k) dst[n][k] = *(const LAS bf16x8*)(lds + PG8_SB(b, h) + boff + n * 2048 + k * 1024); } while (0)
; #define PG8_MMA(ai, bj, At, Bt) do { __builtin_amdgcn_s_setprio(1); _Pragma("unroll") for (int m = 0; m < 4; ++m) _Pragma("unroll") for (int n = 0; n < 2; ++n) _Pragma("unroll") for (int k = 0; k < 2; ++k) \
;         acc[ai][bj][m][n] = __builtin_amdgcn_mfma_f32_16x16x32_bf16(Bt[n][k], At[m][k], acc[ai][bj][m][n], 0, 0, 0); __builtin_amdgcn_s_setprio(0); } while (0)
; #define PG8_WAIT_V(n) asm volatile("s_waitcnt vmcnt(" #n ")" ::: "memory")
; #define PG8_WAIT_L(n) asm volatile("s_waitcnt lgkmcnt(" #n ")" ::: "memory")
; #define PG8_BAR __builtin_amdgcn_s_barrier()
; #define PG8_SCHED __builtin_amdgcn_sched_barrier(0)
; template <class Epi, bool KS0 = false>
; __device__ __forceinline__ void gemm_phase(const int WID, LAS unsigned char* lds, const Gemm g, const StaticOrder& S, const Epi& E) {
;     ...
;             PG8_LDB(B0, 0, 0); PG8_SCHED; PG8_LDA(At, 0, 0); PG8_STAGE(PG8_SA(1, 1), a1 + hstep, voffA);
;             PG8_WAIT_L(8); PG8_BAR; PG8_WAIT_L(0); PG8_MMA(0, 0, At, B0); PG8_BAR; PG8_SCHED;
;             PG8_LDB(B1, 0, 1); PG8_STAGE(PG8_SB(0, 0), b2, voffB);
;             PG8_BAR; PG8_WAIT_L(0); PG8_MMA(0, 1, At, B1); PG8_BAR;
;             PG8_LDA(At, 0, 1); PG8_STAGE(PG8_SA(0, 0), a2, voffA);
;             PG8_BAR; PG8_WAIT_L(0); PG8_MMA(1, 0, At, B0); PG8_BAR; PG8_SCHED;
;             PG8_STAGE(PG8_SB(0, 1), b2 + hstep, voffB);
;             PG8_WAIT_V(6); PG8_BAR; PG8_MMA(1, 1, At, B1); PG8_BAR;
.LBB0_1006:
	ds_read_b128 v[104:107], v246
	ds_read_b128 v[108:111], v246 offset:1024
	ds_read_b128 v[112:115], v246 offset:2048
	ds_read_b128 v[120:123], v246 offset:3072
	ds_read_b128 v[136:139], v247
	ds_read_b128 v[144:147], v247 offset:1024
	ds_read_b128 v[148:151], v247 offset:2048
	ds_read_b128 v[156:159], v247 offset:3072
	ds_read_b128 v[160:163], v247 offset:4096
	ds_read_b128 v[164:167], v247 offset:5120
	ds_read_b128 v[168:171], v247 offset:6144
	ds_read_b128 v[172:175], v247 offset:7168
	ds_read_b128 v[176:179], v248
	ds_read_b128 v[180:183], v248 offset:1024
	ds_read_b128 v[184:187], v248 offset:2048
	ds_read_b128 v[188:191], v248 offset:3072
	s_add_u32 s10, s8, 0xfff80080
	s_addc_u32 s11, s9, -1
	s_cmp_eq_u32 s43, 28
	s_cselect_b32 s13, s3, s11
	s_cselect_b32 s12, s14, s10
	s_cselect_b32 s11, s15, s41
	s_cselect_b32 s10, s36, s37
	s_add_i32 m0, s18, 0xc000
	s_nop 0
	global_load_lds_dwordx4 v200, s[8:9]
	s_add_i32 m0, s18, 0xe000
	s_nop 0
	global_load_lds_dwordx4 v202, s[8:9]
	s_waitcnt vmcnt(8) lgkmcnt(0)
	s_barrier
	s_waitcnt lgkmcnt(0)
	v_mfma_f32_16x16x32_bf16 v[152:155], v[104:107], v[136:139], v[152:155]
	v_mfma_f32_16x16x32_bf16 v[140:143], v[112:115], v[136:139], v[140:143]
	v_mfma_f32_16x16x32_bf16 v[124:127], v[104:107], v[148:151], v[124:127]
	v_mfma_f32_16x16x32_bf16 v[116:119], v[112:115], v[148:151], v[116:119]
	v_mfma_f32_16x16x32_bf16 v[92:95], v[104:107], v[160:163], v[92:95]
	v_mfma_f32_16x16x32_bf16 v[88:91], v[112:115], v[160:163], v[88:91]
	v_mfma_f32_16x16x32_bf16 v[76:79], v[104:107], v[168:171], v[76:79]
	v_mfma_f32_16x16x32_bf16 v[72:75], v[112:115], v[168:171], v[72:75]
	v_mfma_f32_16x16x32_bf16 v[152:155], v[108:111], v[144:147], v[152:155]
	v_mfma_f32_16x16x32_bf16 v[140:143], v[120:123], v[144:147], v[140:143]
	v_mfma_f32_16x16x32_bf16 v[124:127], v[108:111], v[156:159], v[124:127]
	v_mfma_f32_16x16x32_bf16 v[116:119], v[120:123], v[156:159], v[116:119]
	v_mfma_f32_16x16x32_bf16 v[92:95], v[108:111], v[164:167], v[92:95]
	v_mfma_f32_16x16x32_bf16 v[88:91], v[120:123], v[164:167], v[88:91]
	v_mfma_f32_16x16x32_bf16 v[76:79], v[108:111], v[172:175], v[76:79]
	v_mfma_f32_16x16x32_bf16 v[72:75], v[120:123], v[172:175], v[72:75]
	v_mfma_f32_16x16x32_bf16 v[132:135], v[176:179], v[136:139], v[132:135]
	v_mfma_f32_16x16x32_bf16 v[128:131], v[184:187], v[136:139], v[128:131]
	v_mfma_f32_16x16x32_bf16 v[100:103], v[176:179], v[148:151], v[100:103]
	v_mfma_f32_16x16x32_bf16 v[96:99], v[184:187], v[148:151], v[96:99]
	v_mfma_f32_16x16x32_bf16 v[84:87], v[176:179], v[160:163], v[84:87]
	v_mfma_f32_16x16x32_bf16 v[80:83], v[184:187], v[160:163], v[80:83]
	v_mfma_f32_16x16x32_bf16 v[68:71], v[176:179], v[168:171], v[68:71]
	v_mfma_f32_16x16x32_bf16 v[64:67], v[184:187], v[168:171], v[64:67]
	v_mfma_f32_16x16x32_bf16 v[132:135], v[180:183], v[144:147], v[132:135]
	v_mfma_f32_16x16x32_bf16 v[128:131], v[188:191], v[144:147], v[128:131]
	v_mfma_f32_16x16x32_bf16 v[100:103], v[180:183], v[156:159], v[100:103]
	v_mfma_f32_16x16x32_bf16 v[96:99], v[188:191], v[156:159], v[96:99]
	v_mfma_f32_16x16x32_bf16 v[84:87], v[180:183], v[164:167], v[84:87]
	v_mfma_f32_16x16x32_bf16 v[80:83], v[188:191], v[164:167], v[80:83]
	v_mfma_f32_16x16x32_bf16 v[68:71], v[180:183], v[172:175], v[68:71]
	v_mfma_f32_16x16x32_bf16 v[64:67], v[188:191], v[172:175], v[64:67]
	s_barrier
	ds_read_b128 v[136:139], v247 offset:16384
	ds_read_b128 v[144:147], v247 offset:17408
	ds_read_b128 v[148:151], v247 offset:18432
	ds_read_b128 v[156:159], v247 offset:19456
	ds_read_b128 v[160:163], v247 offset:20480
	ds_read_b128 v[164:167], v247 offset:21504
	ds_read_b128 v[168:171], v247 offset:22528
	ds_read_b128 v[172:175], v247 offset:23552
	s_add_i32 s48, s50, s26
	s_add_u32 s98, s10, s30
	s_addc_u32 s99, s11, s31
	s_mov_b32 m0, s48
	s_nop 0
	global_load_lds_dwordx4 v194, s[10:11]
	s_add_i32 m0, s48, 0x2000
	s_nop 0
	global_load_lds_dwordx4 v198, s[10:11]
	s_mov_b32 m0, s18
	s_add_u32 s100, s12, s30
	s_addc_u32 s101, s13, s31
	global_load_lds_dwordx4 v192, s[12:13]
	s_mov_b32 m0, s19
	s_nop 0
	global_load_lds_dwordx4 v196, s[12:13]
	s_add_u32 s48, s10, 0x80000
	s_addc_u32 s49, s11, 0
	s_add_i32 s54, s51, s26
	s_mov_b32 m0, s54
	s_nop 0
	global_load_lds_dwordx4 v194, s[48:49]
	s_add_i32 m0, s54, 0x2000
	s_nop 0
	global_load_lds_dwordx4 v198, s[48:49]
	s_waitcnt vmcnt(8) lgkmcnt(0)
	s_barrier
	s_waitcnt lgkmcnt(0)
	v_mfma_f32_16x16x32_bf16 v[60:63], v[104:107], v[136:139], v[60:63]
	v_mfma_f32_16x16x32_bf16 v[56:59], v[112:115], v[136:139], v[56:59]
	v_mfma_f32_16x16x32_bf16 v[44:47], v[104:107], v[148:151], v[44:47]
	v_mfma_f32_16x16x32_bf16 v[40:43], v[112:115], v[148:151], v[40:43]
	v_mfma_f32_16x16x32_bf16 v[28:31], v[104:107], v[160:163], v[28:31]
	v_mfma_f32_16x16x32_bf16 v[24:27], v[112:115], v[160:163], v[24:27]
	v_mfma_f32_16x16x32_bf16 v[12:15], v[104:107], v[168:171], v[12:15]
	v_mfma_f32_16x16x32_bf16 v[8:11], v[112:115], v[168:171], v[8:11]
	v_mfma_f32_16x16x32_bf16 v[60:63], v[108:111], v[144:147], v[60:63]
	v_mfma_f32_16x16x32_bf16 v[56:59], v[120:123], v[144:147], v[56:59]
	v_mfma_f32_16x16x32_bf16 v[44:47], v[108:111], v[156:159], v[44:47]
	v_mfma_f32_16x16x32_bf16 v[40:43], v[120:123], v[156:159], v[40:43]
	v_mfma_f32_16x16x32_bf16 v[28:31], v[108:111], v[164:167], v[28:31]
	v_mfma_f32_16x16x32_bf16 v[24:27], v[120:123], v[164:167], v[24:27]
	v_mfma_f32_16x16x32_bf16 v[12:15], v[108:111], v[172:175], v[12:15]
	v_mfma_f32_16x16x32_bf16 v[8:11], v[120:123], v[172:175], v[8:11]
	v_mfma_f32_16x16x32_bf16 v[52:55], v[176:179], v[136:139], v[52:55]
	v_mfma_f32_16x16x32_bf16 v[48:51], v[184:187], v[136:139], v[48:51]
	v_mfma_f32_16x16x32_bf16 v[36:39], v[176:179], v[148:151], v[36:39]
	v_mfma_f32_16x16x32_bf16 v[32:35], v[184:187], v[148:151], v[32:35]
	v_mfma_f32_16x16x32_bf16 v[20:23], v[176:179], v[160:163], v[20:23]
	v_mfma_f32_16x16x32_bf16 v[16:19], v[184:187], v[160:163], v[16:19]
	v_mfma_f32_16x16x32_bf16 v[4:7], v[176:179], v[168:171], v[4:7]
	v_mfma_f32_16x16x32_bf16 v[0:3], v[184:187], v[168:171], v[0:3]
	v_mfma_f32_16x16x32_bf16 v[52:55], v[180:183], v[144:147], v[52:55]
	v_mfma_f32_16x16x32_bf16 v[48:51], v[188:191], v[144:147], v[48:51]
	v_mfma_f32_16x16x32_bf16 v[36:39], v[180:183], v[156:159], v[36:39]
	v_mfma_f32_16x16x32_bf16 v[32:35], v[188:191], v[156:159], v[32:35]
	v_mfma_f32_16x16x32_bf16 v[20:23], v[180:183], v[164:167], v[20:23]
	v_mfma_f32_16x16x32_bf16 v[16:19], v[188:191], v[164:167], v[16:19]
	v_mfma_f32_16x16x32_bf16 v[4:7], v[180:183], v[172:175], v[4:7]
	v_mfma_f32_16x16x32_bf16 v[0:3], v[188:191], v[172:175], v[0:3]
	s_barrier
; #define PG8_STAGE(bufoff, gbase, voff) do { _Pragma("unroll") for (int _i = 0; _i < 2; ++_i) \
;         __builtin_amdgcn_global_load_lds((const unsigned*)((const char*)(gbase) + (voff)[_i]), (LAS unsigned*)(lds + (bufoff) + ldsw + _i * 8192), 16, 0, 0); } while (0)
; #define PG8_LDA(dst, b, h) do { _Pragma("unroll") for (int m = 0; m < 4; ++m) _Pragma("unroll") for (int k = 0; k < 2; ++k) dst[m][k] = *(const LAS bf16x8*)(lds + PG8_SA(b, h) + aoff + m * 2048 + k * 1024); } while (0)
; #define PG8_LDB(dst, b, h) do { _Pragma("unroll") for (int n = 0; n < 2; ++n) _Pragma("unroll") for (int k = 0; k < 2; ++k) dst[n][k] = *(const LAS bf16x8*)(lds + PG8_SB(b, h) + boff + n * 2048 + k * 1024); } while (0)
; #define PG8_MMA(ai, bj, At, Bt) do { __builtin_amdgcn_s_setprio(1); _Pragma("unroll") for (int m = 0; m < 4; ++m) _Pragma("unroll") for (int n = 0; n < 2; ++n) _Pragma("unroll") for (int k = 0; k < 2; ++k) \
;         acc[ai][bj][m][n] = __builtin_amdgcn_mfma_f32_16x16x32_bf16(Bt[n][k], At[m][k], acc[ai][bj][m][n], 0, 0, 0); __builtin_amdgcn_s_setprio(0); } while (0)
; #define PG8_WAIT_V(n) asm volatile("s_waitcnt vmcnt(" #n ")" ::: "memory")
; #define PG8_WAIT_L(n) asm volatile("s_waitcnt lgkmcnt(" #n ")" ::: "memory")
; #define PG8_BAR __builtin_amdgcn_s_barrier()
; #define PG8_SCHED __builtin_amdgcn_sched_barrier(0)
; template <class Epi, bool KS0 = false>
; __device__ __forceinline__ void gemm_phase(const int WID, LAS unsigned char* lds, const Gemm g, const StaticOrder& S, const Epi& E) {
;     ...
;             PG8_LDB(B0, 1, 0); PG8_SCHED; PG8_LDA(At, 1, 0); PG8_STAGE(PG8_SA(0, 1), a2 + hstep, voffA);
;             PG8_WAIT_L(8); PG8_BAR; PG8_WAIT_L(0); PG8_MMA(0, 0, At, B0); PG8_BAR; PG8_SCHED;
;             PG8_LDB(B1, 1, 1); PG8_STAGE(PG8_SB(1, 0), b3, voffB);
;             PG8_BAR; PG8_WAIT_L(0); PG8_MMA(0, 1, At, B1); PG8_BAR;
;             PG8_LDA(At, 1, 1); PG8_STAGE(PG8_SA(1, 0), a3, voffA);
;             PG8_BAR; PG8_WAIT_L(0); PG8_MMA(1, 0, At, B0); PG8_BAR; PG8_SCHED;
;             PG8_STAGE(PG8_SB(1, 1), b3 + hstep, voffB);
;             PG8_WAIT_V(6); PG8_BAR; PG8_MMA(1, 1, At, B1); PG8_BAR;
	v_add_u32_e32 v104, 0x18000, v245
	ds_read_b128 v[108:111], v104 offset:1024
	ds_read_b128 v[112:115], v104 offset:2048
	ds_read_b128 v[120:123], v104 offset:3072
	ds_read_b128 v[104:107], v104
	ds_read_b128 v[136:139], v247 offset:32768
	ds_read_b128 v[144:147], v247 offset:33792
	ds_read_b128 v[148:151], v247 offset:34816
	ds_read_b128 v[156:159], v247 offset:35840
	ds_read_b128 v[160:163], v247 offset:36864
	ds_read_b128 v[164:167], v247 offset:37888
	ds_read_b128 v[168:171], v247 offset:38912
	ds_read_b128 v[172:175], v247 offset:39936
	v_add_u32_e32 v188, 0x1c000, v245
	ds_read_b128 v[176:179], v188
	ds_read_b128 v[180:183], v188 offset:1024
	ds_read_b128 v[184:187], v188 offset:2048
	ds_read_b128 v[188:191], v188 offset:3072
	s_add_i32 s48, 0, 0x18000
	s_add_u32 s12, s12, 0x80000
	s_addc_u32 s13, s13, 0
	s_mov_b32 m0, s20
	s_nop 0
	global_load_lds_dwordx4 v192, s[12:13]
	s_mov_b32 m0, s21
	s_nop 0
	global_load_lds_dwordx4 v196, s[12:13]
	s_waitcnt vmcnt(8) lgkmcnt(0)
	s_barrier
	s_waitcnt lgkmcnt(0)
	v_mfma_f32_16x16x32_bf16 v[152:155], v[104:107], v[136:139], v[152:155]
	v_mfma_f32_16x16x32_bf16 v[140:143], v[112:115], v[136:139], v[140:143]
	v_mfma_f32_16x16x32_bf16 v[124:127], v[104:107], v[148:151], v[124:127]
	v_mfma_f32_16x16x32_bf16 v[116:119], v[112:115], v[148:151], v[116:119]
	v_mfma_f32_16x16x32_bf16 v[92:95], v[104:107], v[160:163], v[92:95]
	v_mfma_f32_16x16x32_bf16 v[88:91], v[112:115], v[160:163], v[88:91]
	v_mfma_f32_16x16x32_bf16 v[76:79], v[104:107], v[168:171], v[76:79]
	v_mfma_f32_16x16x32_bf16 v[72:75], v[112:115], v[168:171], v[72:75]
	v_mfma_f32_16x16x32_bf16 v[152:155], v[108:111], v[144:147], v[152:155]
	v_mfma_f32_16x16x32_bf16 v[140:143], v[120:123], v[144:147], v[140:143]
	v_mfma_f32_16x16x32_bf16 v[124:127], v[108:111], v[156:159], v[124:127]
	v_mfma_f32_16x16x32_bf16 v[116:119], v[120:123], v[156:159], v[116:119]
	v_mfma_f32_16x16x32_bf16 v[92:95], v[108:111], v[164:167], v[92:95]
	v_mfma_f32_16x16x32_bf16 v[88:91], v[120:123], v[164:167], v[88:91]
	v_mfma_f32_16x16x32_bf16 v[76:79], v[108:111], v[172:175], v[76:79]
	v_mfma_f32_16x16x32_bf16 v[72:75], v[120:123], v[172:175], v[72:75]
	v_mfma_f32_16x16x32_bf16 v[132:135], v[176:179], v[136:139], v[132:135]
	v_mfma_f32_16x16x32_bf16 v[128:131], v[184:187], v[136:139], v[128:131]
	v_mfma_f32_16x16x32_bf16 v[100:103], v[176:179], v[148:151], v[100:103]
	v_mfma_f32_16x16x32_bf16 v[96:99], v[184:187], v[148:151], v[96:99]
	v_mfma_f32_16x16x32_bf16 v[84:87], v[176:179], v[160:163], v[84:87]
	v_mfma_f32_16x16x32_bf16 v[80:83], v[184:187], v[160:163], v[80:83]
	v_mfma_f32_16x16x32_bf16 v[68:71], v[176:179], v[168:171], v[68:71]
	v_mfma_f32_16x16x32_bf16 v[64:67], v[184:187], v[168:171], v[64:67]
	v_mfma_f32_16x16x32_bf16 v[132:135], v[180:183], v[144:147], v[132:135]
	v_mfma_f32_16x16x32_bf16 v[128:131], v[188:191], v[144:147], v[128:131]
	v_mfma_f32_16x16x32_bf16 v[100:103], v[180:183], v[156:159], v[100:103]
	v_mfma_f32_16x16x32_bf16 v[96:99], v[188:191], v[156:159], v[96:99]
	v_mfma_f32_16x16x32_bf16 v[84:87], v[180:183], v[164:167], v[84:87]
	v_mfma_f32_16x16x32_bf16 v[80:83], v[188:191], v[164:167], v[80:83]
	v_mfma_f32_16x16x32_bf16 v[68:71], v[180:183], v[172:175], v[68:71]
	v_mfma_f32_16x16x32_bf16 v[64:67], v[188:191], v[172:175], v[64:67]
	s_barrier
	ds_read_b128 v[136:139], v247 offset:49152
	ds_read_b128 v[144:147], v247 offset:50176
	ds_read_b128 v[148:151], v247 offset:51200
	ds_read_b128 v[156:159], v247 offset:52224
	ds_read_b128 v[160:163], v247 offset:53248
	ds_read_b128 v[164:167], v247 offset:54272
	ds_read_b128 v[168:171], v247 offset:55296
	ds_read_b128 v[172:175], v247 offset:56320
	s_add_i32 s12, 0, 0x1c000
	s_add_i32 s13, s48, s26
	s_mov_b32 m0, s13
	s_nop 0
	global_load_lds_dwordx4 v194, s[98:99]
	s_add_i32 m0, s13, 0x2000
	s_nop 0
	global_load_lds_dwordx4 v198, s[98:99]
	s_mov_b32 m0, s25
	s_nop 0
	global_load_lds_dwordx4 v192, s[100:101]
	s_mov_b32 m0, s39
	s_nop 0
	global_load_lds_dwordx4 v196, s[100:101]
	s_add_u32 s10, s10, 0x80080
	s_addc_u32 s11, s11, 0
	s_add_i32 s12, s12, s26
	s_mov_b32 m0, s12
	s_nop 0
	global_load_lds_dwordx4 v194, s[10:11]
	s_add_i32 m0, s12, 0x2000
	s_nop 0
	global_load_lds_dwordx4 v198, s[10:11]
	s_waitcnt vmcnt(8) lgkmcnt(0)
	s_barrier
	s_waitcnt lgkmcnt(0)
	v_mfma_f32_16x16x32_bf16 v[60:63], v[104:107], v[136:139], v[60:63]
	v_mfma_f32_16x16x32_bf16 v[56:59], v[112:115], v[136:139], v[56:59]
	s_add_i32 s43, s43, 2
	s_add_u32 s8, s8, 0x100
	s_addc_u32 s9, s9, 0
	s_add_u32 s37, s37, 0x100
	s_addc_u32 s41, s41, 0
	s_cmp_gt_u32 s43, 29
	v_mfma_f32_16x16x32_bf16 v[44:47], v[104:107], v[148:151], v[44:47]
	v_mfma_f32_16x16x32_bf16 v[40:43], v[112:115], v[148:151], v[40:43]
	v_mfma_f32_16x16x32_bf16 v[28:31], v[104:107], v[160:163], v[28:31]
	v_mfma_f32_16x16x32_bf16 v[24:27], v[112:115], v[160:163], v[24:27]
	v_mfma_f32_16x16x32_bf16 v[12:15], v[104:107], v[168:171], v[12:15]
	v_mfma_f32_16x16x32_bf16 v[8:11], v[112:115], v[168:171], v[8:11]
	v_mfma_f32_16x16x32_bf16 v[60:63], v[108:111], v[144:147], v[60:63]
	v_mfma_f32_16x16x32_bf16 v[56:59], v[120:123], v[144:147], v[56:59]
	v_mfma_f32_16x16x32_bf16 v[44:47], v[108:111], v[156:159], v[44:47]
	v_mfma_f32_16x16x32_bf16 v[40:43], v[120:123], v[156:159], v[40:43]
	v_mfma_f32_16x16x32_bf16 v[28:31], v[108:111], v[164:167], v[28:31]
	v_mfma_f32_16x16x32_bf16 v[24:27], v[120:123], v[164:167], v[24:27]
	v_mfma_f32_16x16x32_bf16 v[12:15], v[108:111], v[172:175], v[12:15]
	v_mfma_f32_16x16x32_bf16 v[8:11], v[120:123], v[172:175], v[8:11]
	v_mfma_f32_16x16x32_bf16 v[52:55], v[176:179], v[136:139], v[52:55]
	v_mfma_f32_16x16x32_bf16 v[48:51], v[184:187], v[136:139], v[48:51]
	v_mfma_f32_16x16x32_bf16 v[36:39], v[176:179], v[148:151], v[36:39]
	v_mfma_f32_16x16x32_bf16 v[32:35], v[184:187], v[148:151], v[32:35]
	v_mfma_f32_16x16x32_bf16 v[20:23], v[176:179], v[160:163], v[20:23]
	v_mfma_f32_16x16x32_bf16 v[16:19], v[184:187], v[160:163], v[16:19]
	v_mfma_f32_16x16x32_bf16 v[4:7], v[176:179], v[168:171], v[4:7]
	v_mfma_f32_16x16x32_bf16 v[0:3], v[184:187], v[168:171], v[0:3]
	v_mfma_f32_16x16x32_bf16 v[52:55], v[180:183], v[144:147], v[52:55]
	v_mfma_f32_16x16x32_bf16 v[48:51], v[188:191], v[144:147], v[48:51]
	v_mfma_f32_16x16x32_bf16 v[36:39], v[180:183], v[156:159], v[36:39]
	v_mfma_f32_16x16x32_bf16 v[32:35], v[188:191], v[156:159], v[32:35]
	v_mfma_f32_16x16x32_bf16 v[20:23], v[180:183], v[164:167], v[20:23]
	v_mfma_f32_16x16x32_bf16 v[16:19], v[188:191], v[164:167], v[16:19]
	v_mfma_f32_16x16x32_bf16 v[4:7], v[180:183], v[172:175], v[4:7]
	v_mfma_f32_16x16x32_bf16 v[0:3], v[188:191], v[172:175], v[0:3]
	s_barrier
; __device__ __forceinline__ float row_rstd(const float* ssq, int row, int fq) {
;     const f32x4 a = *(const f32x4*)(ssq + (size_t)row * 32 + 8 * fq), b = *(const f32x4*)(ssq + (size_t)row * 32 + 8 * fq + 4);
;     float t = ((a[0] + a[1]) + (a[2] + a[3])) + ((b[0] + b[1]) + (b[2] + b[3]));
;     t += __shfl_xor(t, 16); t += __shfl_xor(t, 32);
;     return rsqrtf(t * (1.0f / 2048.0f) + EPS);
;     __device__ __forceinline__ void operator()(f32x4 (&acc)[2][2][4][2], const Unit& u, int wr, int wc, int fr, int fq) const {
;         const int row0 = u.pm * BM + wr * 64 + fr, col0 = u.pn * BM + wc * 32 + 8 * fq;
;         const bf16_t* ppf = pp + ((size_t)(u.pm * (DM / 256) + u.pn) << 16) + (size_t)((((wr * 4 + wc) * 16) * 64 + fq * 16 + fr) << 3);
; #pragma unroll
;         for (int ai = 0; ai < 2; ++ai) {
;             u32x4 hw[4][2], pw[4][2]; float rstd[4];
; #pragma unroll
;             for (int m = 0; m < 4; ++m) { const int row = row0 + ai * HALF + m * 16;
; #pragma unroll
;                 for (int bj = 0; bj < 2; ++bj) { const size_t o = (size_t)row * DM + col0 + bj * HALF; hw[m][bj] = *(const u32x4*)(hb + o); pw[m][bj] = *(const u32x4*)(ppf + (((ai * 4 + m) * 2 + bj) << 9)); }
;                 rstd[m] = row_rstd(ssq_in, row, fq); }
	s_cbranch_scc0 .LBB0_1006
	s_waitcnt lgkmcnt(0)
	s_lshl_b32 s3, s4, 8
	v_mbcnt_lo_u32_b32 v104, -1, 0
	v_mbcnt_hi_u32_b32 v104, -1, v104
	s_add_i32 s3, s3, s22
	v_ashrrev_i32_e32 v108, 4, v104
	v_and_b32_e32 v109, 15, v104
	v_readlane_b32 s8, v254, 19
	v_add_u32_e32 v212, s3, v109
	v_lshlrev_b32_e32 v104, 3, v108
	v_ashrrev_i32_e32 v105, 31, v104
	v_ashrrev_i32_e32 v213, 31, v212
	v_add_u32_e32 v160, 16, v212
	v_lshl_add_u64 v[214:215], v[104:105], 2, s[16:17]
	v_lshlrev_b64 v[236:237], 7, v[212:213]
	v_ashrrev_i32_e32 v161, 31, v160
	v_lshl_add_u64 v[106:107], v[214:215], 0, v[236:237]
	v_lshlrev_b64 v[228:229], 7, v[160:161]
	global_load_dwordx4 v[136:139], v[106:107], off
	global_load_dwordx4 v[144:147], v[106:107], off offset:16
	v_lshl_add_u64 v[106:107], v[214:215], 0, v[228:229]
	global_load_dwordx4 v[148:151], v[106:107], off
	global_load_dwordx4 v[156:159], v[106:107], off offset:16
	v_and_b32_e32 v106, 64, v209
	v_xor_b32_e32 v105, 16, v209
	v_add_u32_e32 v106, 64, v106
	v_add_u32_e32 v162, 32, v212
	v_xor_b32_e32 v107, 32, v209
	v_cmp_lt_i32_e32 vcc, v105, v106
	v_ashrrev_i32_e32 v163, 31, v162
	v_lshlrev_b64 v[222:223], 7, v[162:163]
	v_cndmask_b32_e32 v105, v209, v105, vcc
	v_cmp_lt_i32_e32 vcc, v107, v106
	v_add_u32_e32 v226, 48, v212
	s_lshl_b32 s3, s2, 8
	v_cndmask_b32_e32 v110, v209, v107, vcc
	v_lshl_add_u64 v[106:107], v[214:215], 0, v[222:223]
	v_ashrrev_i32_e32 v227, 31, v226
	s_or_b32 s3, s3, s8
	global_load_dwordx4 v[112:115], v[106:107], off
	global_load_dwordx4 v[120:123], v[106:107], off offset:16
	v_lshlrev_b64 v[220:221], 7, v[226:227]
	v_lshlrev_b32_e32 v250, 2, v105
	v_add_u32_e32 v210, s3, v104
	v_lshl_add_u64 v[104:105], v[214:215], 0, v[220:221]
	v_add_u32_e32 v164, s55, v109
	v_lshlrev_b32_e32 v165, 7, v108
	v_lshlrev_b32_e32 v249, 2, v110
	v_cmp_eq_u32_e64 s[36:37], 0, v108
	global_load_dwordx4 v[108:111], v[104:105], off
	s_nop 0
	global_load_dwordx4 v[104:107], v[104:105], off offset:16
	s_lshl_b32 s4, s4, 3
	s_add_i32 s8, s4, s2
	s_ashr_i32 s9, s8, 31
	s_lshl_b64 s[8:9], s[8:9], 17
	v_ashrrev_i32_e32 v211, 31, v210
	s_add_u32 s8, s23, s8
	v_lshl_add_u32 v164, v164, 3, v165
	v_lshlrev_b64 v[240:241], 1, v[210:211]
	s_addc_u32 s9, s24, s9
	v_ashrrev_i32_e32 v165, 31, v164
	v_lshlrev_b64 v[238:239], 12, v[212:213]
	v_lshl_add_u64 v[216:217], s[6:7], 0, v[240:241]
	v_lshl_add_u64 v[218:219], v[164:165], 1, s[8:9]
	v_lshl_add_u64 v[164:165], v[216:217], 0, v[238:239]
	global_load_dwordx4 v[184:187], v[218:219], off
	global_load_dwordx4 v[188:191], v[164:165], off
	global_load_dwordx4 v[176:179], v[218:219], off offset:1024
	s_lshl_b32 s48, s2, 2
	v_lshlrev_b64 v[234:235], 12, v[160:161]
	v_lshlrev_b64 v[224:225], 12, v[162:163]
	v_lshlrev_b64 v[226:227], 12, v[226:227]
	s_ashr_i32 s49, s48, 31
	s_waitcnt vmcnt(0)
	v_mov_b32_e32 v166, v136
	v_mov_b32_e32 v167, v144
	v_mov_b32_e32 v144, v137
	v_mov_b32_e32 v136, v138
	v_mov_b32_e32 v137, v146
	v_mov_b32_e32 v146, v139
	v_pk_add_f32 v[138:139], v[166:167], v[144:145]
	v_pk_add_f32 v[136:137], v[136:137], v[146:147]
	v_mov_b32_e32 v144, v148
	v_mov_b32_e32 v145, v156
	v_mov_b32_e32 v156, v149
	v_mov_b32_e32 v146, v150
	v_mov_b32_e32 v147, v158
	v_mov_b32_e32 v158, v151
	v_pk_add_f32 v[136:137], v[138:139], v[136:137]
	v_pk_add_f32 v[138:139], v[144:145], v[156:157]
	v_pk_add_f32 v[144:145], v[146:147], v[158:159]
	v_lshl_add_u64 v[150:151], v[216:217], 0, v[234:235]
	v_pk_add_f32 v[138:139], v[138:139], v[144:145]
	v_mov_b32_e32 v145, v136
	v_mov_b32_e32 v144, v138
	v_mov_b32_e32 v136, v139
	v_pk_add_f32 v[136:137], v[144:145], v[136:137]
	ds_bpermute_b32 v139, v250, v137
	ds_bpermute_b32 v138, v250, v136
	v_mov_b32_e32 v232, v112
	v_mov_b32_e32 v233, v120
	v_mov_b32_e32 v120, v113
	v_pk_add_f32 v[112:113], v[232:233], v[120:121]
	s_waitcnt lgkmcnt(0)
	v_pk_add_f32 v[146:147], v[136:137], v[138:139]
	global_load_dwordx4 v[168:171], v[218:219], off offset:2048
	global_load_dwordx4 v[136:139], v[218:219], off offset:3072
	global_load_dwordx4 v[180:183], v[164:165], off offset:256
	ds_bpermute_b32 v149, v249, v147
	ds_bpermute_b32 v148, v249, v146
	v_mov_b32_e32 v120, v114
	v_mov_b32_e32 v121, v122
	v_mov_b32_e32 v122, v115
	v_pk_add_f32 v[114:115], v[120:121], v[122:123]
	s_waitcnt lgkmcnt(0)
; __device__ __forceinline__ unsigned cvt_pk_bf16(float lo, float hi) { unsigned r; asm volatile("v_cvt_pk_bf16_f32 %0, %1, %2" : "=v"(r) : "v"(lo), "v"(hi)); return r; }
; __device__ __forceinline__ float bflo(unsigned w) { return __uint_as_float(w << 16); }
; __device__ __forceinline__ float bfhi(unsigned w) { return __uint_as_float(w & 0xffff0000u); }
; __device__ __forceinline__ float sigmoidf_(float x) { return __builtin_amdgcn_rcpf(1.0f + __expf(-x)); }
;     __device__ __forceinline__ void operator()(f32x4 (&acc)[2][2][4][2], const Unit& u, int wr, int wc, int fr, int fq) const {
;     ...
;                 rstd[m] = row_rstd(ssq_in, row, fq); }
;     ...
;             for (int m = 0; m < 4; ++m) { const int row = row0 + ai * HALF + m * 16; const size_t off = (size_t)row * DM + col0; float s = 0.f;
; #pragma unroll
;                 for (int bj = 0; bj < 2; ++bj) { const f32x4 z0 = acc[ai][bj][m][0] * rstd[m], z1 = acc[ai][bj][m][1] * rstd[m]; const u32x4 h2 = hw[m][bj], p2 = pw[m][bj]; f32x4 v0, v1;
;                     v0[0] = bflo(h2.x) + sigmoidf_(z0[0]) * bflo(p2.x); v0[1] = bfhi(h2.x) + sigmoidf_(z0[1]) * bfhi(p2.x);
;                     v0[2] = bflo(h2.y) + sigmoidf_(z0[2]) * bflo(p2.y); v0[3] = bfhi(h2.y) + sigmoidf_(z0[3]) * bfhi(p2.y);
;                     v1[0] = bflo(h2.z) + sigmoidf_(z1[0]) * bflo(p2.z); v1[1] = bfhi(h2.z) + sigmoidf_(z1[1]) * bfhi(p2.z);
;                     v1[2] = bflo(h2.w) + sigmoidf_(z1[2]) * bflo(p2.w); v1[3] = bfhi(h2.w) + sigmoidf_(z1[3]) * bfhi(p2.w);
;                     u32x4 w; w.x = cvt_pk_bf16(v0[0], v0[1]); w.y = cvt_pk_bf16(v0[2], v0[3]); w.z = cvt_pk_bf16(v1[0], v1[1]); w.w = cvt_pk_bf16(v1[2], v1[3]);
;                     *(u32x4*)(out + off + bj * HALF) = w;
;                     s += ((v0[0] * v0[0] + v0[1] * v0[1]) + (v0[2] * v0[2] + v0[3] * v0[3])) + ((v1[0] * v1[0] + v1[1] * v1[1]) + (v1[2] * v1[2] + v1[3] * v1[3])); }
	v_pk_add_f32 v[146:147], v[146:147], v[148:149]
	v_mov_b32_e32 v120, v108
	v_pk_fma_f32 v[242:243], v[146:147], s[38:39], v[208:209] op_sel_hi:[1,0,0]
	v_mov_b32_e32 v121, v104
	v_mul_f32_e32 v146, 0x4b800000, v243
	v_cmp_gt_f32_e64 s[2:3], s52, v243
	v_mov_b32_e32 v104, v109
	v_mov_b32_e32 v108, v110
	v_cndmask_b32_e64 v146, v243, v146, s[2:3]
	v_rsq_f32_e32 v146, v146
	v_mov_b32_e32 v109, v106
	v_mov_b32_e32 v106, v111
	v_pk_add_f32 v[104:105], v[120:121], v[104:105]
	v_mul_f32_e32 v147, 0x45800000, v146
	v_cndmask_b32_e64 v244, v146, v147, s[2:3]
	v_pk_add_f32 v[106:107], v[108:109], v[106:107]
	v_pk_mul_f32 v[152:153], v[152:153], v[244:245] op_sel_hi:[1,0]
	s_movk_i32 s2, 0x1000
	v_pk_add_f32 v[112:113], v[112:113], v[114:115]
	v_pk_add_f32 v[104:105], v[104:105], v[106:107]
	v_mul_f32_e32 v152, 0xbfb8aa3b, v152
	v_lshl_add_u64 v[144:145], v[216:217], 0, v[224:225]
	v_add_co_u32_e64 v230, s[2:3], s2, v218
	v_lshl_add_u64 v[114:115], v[216:217], 0, v[226:227]
	v_mov_b32_e32 v106, v104
	v_mov_b32_e32 v107, v112
	v_mov_b32_e32 v112, v105
	v_exp_f32_e32 v152, v152
	v_mul_f32_e32 v153, 0xbfb8aa3b, v153
	global_load_dwordx4 v[172:175], v[150:151], off
	global_load_dwordx4 v[156:159], v[150:151], off offset:256
	v_addc_co_u32_e64 v231, s[2:3], 0, v219, s[2:3]
	global_load_dwordx4 v[160:163], v[144:145], off
	s_nop 0
	global_load_dwordx4 v[144:147], v[144:145], off offset:256
	s_nop 0
	global_load_dwordx4 v[164:167], v[230:231], off
	global_load_dwordx4 v[148:151], v[230:231], off offset:1024
	v_pk_add_f32 v[232:233], v[106:107], v[112:113]
	global_load_dwordx4 v[120:123], v[114:115], off
	global_load_dwordx4 v[108:111], v[114:115], off offset:256
	s_nop 0
	global_load_dwordx4 v[112:115], v[230:231], off offset:2048
	global_load_dwordx4 v[104:107], v[230:231], off offset:3072
	v_exp_f32_e32 v153, v153
	v_add_f32_e32 v152, 1.0, v152
	v_rcp_f32_e32 v152, v152
	v_lshlrev_b32_e32 v213, 16, v188
	v_add_f32_e32 v153, 1.0, v153
	v_rcp_f32_e32 v153, v153
	v_lshlrev_b32_e32 v243, 16, v184
	v_pk_mul_f32 v[154:155], v[154:155], v[244:245] op_sel_hi:[1,0]
	v_fmac_f32_e32 v213, v152, v243
	v_and_b32_e32 v152, 0xffff0000, v188
	v_and_b32_e32 v184, 0xffff0000, v184
	v_fmac_f32_e32 v152, v153, v184
	v_mul_f32_e32 v153, 0xbfb8aa3b, v154
	v_pk_mul_f32 v[140:141], v[140:141], v[244:245] op_sel_hi:[1,0]
	v_exp_f32_e32 v153, v153
	v_mul_f32_e32 v155, 0xbfb8aa3b, v155
	v_exp_f32_e32 v155, v155
	v_mul_f32_e32 v140, 0xbfb8aa3b, v140
	v_exp_f32_e32 v140, v140
	v_mul_f32_e32 v141, 0xbfb8aa3b, v141
	v_exp_f32_e32 v141, v141
	v_add_f32_e32 v153, 1.0, v153
	v_rcp_f32_e32 v153, v153
	v_add_f32_e32 v155, 1.0, v155
	v_rcp_f32_e32 v155, v155
	v_add_f32_e32 v140, 1.0, v140
	v_rcp_f32_e32 v140, v140
	v_add_f32_e32 v141, 1.0, v141
	v_lshlrev_b32_e32 v154, 16, v189
	v_lshlrev_b32_e32 v184, 16, v185
	v_rcp_f32_e32 v141, v141
	v_fmac_f32_e32 v154, v153, v184
	v_and_b32_e32 v153, 0xffff0000, v189
	v_and_b32_e32 v184, 0xffff0000, v185
	v_fmac_f32_e32 v153, v155, v184
	v_lshlrev_b32_e32 v155, 16, v190
	v_lshlrev_b32_e32 v184, 16, v186
	v_pk_mul_f32 v[142:143], v[142:143], v[244:245] op_sel_hi:[1,0]
	v_fmac_f32_e32 v155, v140, v184
	v_and_b32_e32 v184, 0xffff0000, v190
	v_and_b32_e32 v140, 0xffff0000, v186
	v_fmac_f32_e32 v184, v141, v140
	v_mul_f32_e32 v140, 0xbfb8aa3b, v142
	v_exp_f32_e32 v140, v140
	v_mul_f32_e32 v141, 0xbfb8aa3b, v143
	v_exp_f32_e32 v141, v141
	v_pk_mul_f32 v[132:133], v[132:133], v[244:245] op_sel_hi:[1,0]
	v_add_f32_e32 v140, 1.0, v140
	v_rcp_f32_e32 v140, v140
	v_add_f32_e32 v141, 1.0, v141
	v_rcp_f32_e32 v141, v141
	v_mul_f32_e32 v132, 0xbfb8aa3b, v132
	v_exp_f32_e32 v132, v132
	v_mul_f32_e32 v133, 0xbfb8aa3b, v133
	v_lshlrev_b32_e32 v185, 16, v191
	v_lshlrev_b32_e32 v142, 16, v187
	v_exp_f32_e32 v133, v133
	v_fmac_f32_e32 v185, v140, v142
	v_and_b32_e32 v186, 0xffff0000, v191
	v_and_b32_e32 v140, 0xffff0000, v187
	v_fmac_f32_e32 v186, v141, v140
	v_cvt_pk_bf16_f32 v140, v213, v152
	v_cvt_pk_bf16_f32 v141, v154, v153
	v_mul_f32_e32 v152, v152, v152
	v_mul_f32_e32 v153, v153, v153
	v_fmac_f32_e32 v152, v213, v213
	v_fmac_f32_e32 v153, v154, v154
	v_add_f32_e32 v132, 1.0, v132
	v_add_f32_e32 v152, v152, v153
	v_mul_f32_e32 v153, v184, v184
	v_mul_f32_e32 v154, v186, v186
	v_rcp_f32_e32 v132, v132
	v_add_f32_e32 v133, 1.0, v133
	v_fmac_f32_e32 v153, v155, v155
	v_fmac_f32_e32 v154, v185, v185
	v_rcp_f32_e32 v133, v133
	v_add_f32_e32 v153, v153, v154
	v_add_f32_e32 v152, v152, v153
	s_waitcnt vmcnt(10)
; __device__ __forceinline__ unsigned cvt_pk_bf16(float lo, float hi) { unsigned r; asm volatile("v_cvt_pk_bf16_f32 %0, %1, %2" : "=v"(r) : "v"(lo), "v"(hi)); return r; }
; __device__ __forceinline__ float bflo(unsigned w) { return __uint_as_float(w << 16); }
; __device__ __forceinline__ float bfhi(unsigned w) { return __uint_as_float(w & 0xffff0000u); }
; __device__ __forceinline__ float sigmoidf_(float x) { return __builtin_amdgcn_rcpf(1.0f + __expf(-x)); }
;     __device__ __forceinline__ void operator()(f32x4 (&acc)[2][2][4][2], const Unit& u, int wr, int wc, int fr, int fq) const {
;     ...
;             for (int m = 0; m < 4; ++m) { const int row = row0 + ai * HALF + m * 16; const size_t off = (size_t)row * DM + col0; float s = 0.f;
; #pragma unroll
;                 for (int bj = 0; bj < 2; ++bj) { const f32x4 z0 = acc[ai][bj][m][0] * rstd[m], z1 = acc[ai][bj][m][1] * rstd[m]; const u32x4 h2 = hw[m][bj], p2 = pw[m][bj]; f32x4 v0, v1;
;                     v0[0] = bflo(h2.x) + sigmoidf_(z0[0]) * bflo(p2.x); v0[1] = bfhi(h2.x) + sigmoidf_(z0[1]) * bfhi(p2.x);
;                     v0[2] = bflo(h2.y) + sigmoidf_(z0[2]) * bflo(p2.y); v0[3] = bfhi(h2.y) + sigmoidf_(z0[3]) * bfhi(p2.y);
;                     v1[0] = bflo(h2.z) + sigmoidf_(z1[0]) * bflo(p2.z); v1[1] = bfhi(h2.z) + sigmoidf_(z1[1]) * bfhi(p2.z);
;                     v1[2] = bflo(h2.w) + sigmoidf_(z1[2]) * bflo(p2.w); v1[3] = bfhi(h2.w) + sigmoidf_(z1[3]) * bfhi(p2.w);
;                     u32x4 w; w.x = cvt_pk_bf16(v0[0], v0[1]); w.y = cvt_pk_bf16(v0[2], v0[3]); w.z = cvt_pk_bf16(v1[0], v1[1]); w.w = cvt_pk_bf16(v1[2], v1[3]);
;                     *(u32x4*)(out + off + bj * HALF) = w;
;                     s += ((v0[0] * v0[0] + v0[1] * v0[1]) + (v0[2] * v0[2] + v0[3] * v0[3])) + ((v1[0] * v1[0] + v1[1] * v1[1]) + (v1[2] * v1[2] + v1[3] * v1[3])); }
;                 s += __shfl_xor(s, 16); s += __shfl_xor(s, 32);
;                 if (fq == 0) ssq[(size_t)row * 32 + u.pn * 4 + wc] = s; }
	v_lshlrev_b32_e32 v153, 16, v180
	v_lshlrev_b32_e32 v154, 16, v176
	v_pk_mul_f32 v[134:135], v[134:135], v[244:245] op_sel_hi:[1,0]
	v_fmac_f32_e32 v153, v132, v154
	v_and_b32_e32 v132, 0xffff0000, v180
	v_and_b32_e32 v154, 0xffff0000, v176
	v_fmac_f32_e32 v132, v133, v154
	v_mul_f32_e32 v133, 0xbfb8aa3b, v134
	v_pk_mul_f32 v[128:129], v[128:129], v[244:245] op_sel_hi:[1,0]
	v_exp_f32_e32 v133, v133
	v_mul_f32_e32 v134, 0xbfb8aa3b, v135
	v_exp_f32_e32 v134, v134
	v_mul_f32_e32 v128, 0xbfb8aa3b, v128
	v_exp_f32_e32 v128, v128
	v_mul_f32_e32 v129, 0xbfb8aa3b, v129
	v_exp_f32_e32 v129, v129
	v_add_f32_e32 v133, 1.0, v133
	v_rcp_f32_e32 v133, v133
	v_add_f32_e32 v134, 1.0, v134
	v_rcp_f32_e32 v134, v134
	v_add_f32_e32 v128, 1.0, v128
	v_rcp_f32_e32 v128, v128
	v_add_f32_e32 v129, 1.0, v129
	v_lshlrev_b32_e32 v154, 16, v181
	v_lshlrev_b32_e32 v135, 16, v177
	v_rcp_f32_e32 v129, v129
	v_fmac_f32_e32 v154, v133, v135
	v_and_b32_e32 v133, 0xffff0000, v181
	v_and_b32_e32 v135, 0xffff0000, v177
	v_cvt_pk_bf16_f32 v142, v155, v184
	v_fmac_f32_e32 v133, v134, v135
	v_lshlrev_b32_e32 v155, 16, v182
	v_lshlrev_b32_e32 v134, 16, v178
	v_pk_mul_f32 v[130:131], v[130:131], v[244:245] op_sel_hi:[1,0]
	v_fmac_f32_e32 v155, v128, v134
	v_and_b32_e32 v176, 0xffff0000, v182
	v_and_b32_e32 v128, 0xffff0000, v178
	v_fmac_f32_e32 v176, v129, v128
	v_mul_f32_e32 v128, 0xbfb8aa3b, v130
	v_exp_f32_e32 v128, v128
	v_mul_f32_e32 v129, 0xbfb8aa3b, v131
	v_exp_f32_e32 v129, v129
	v_lshlrev_b32_e32 v177, 16, v183
	v_add_f32_e32 v128, 1.0, v128
	v_rcp_f32_e32 v128, v128
	v_add_f32_e32 v129, 1.0, v129
	v_rcp_f32_e32 v129, v129
	v_lshlrev_b32_e32 v130, 16, v179
	v_fmac_f32_e32 v177, v128, v130
	v_and_b32_e32 v178, 0xffff0000, v183
	v_and_b32_e32 v128, 0xffff0000, v179
	v_fmac_f32_e32 v178, v129, v128
	v_mul_f32_e32 v128, v132, v132
	v_mul_f32_e32 v129, v133, v133
	v_fmac_f32_e32 v128, v153, v153
	v_fmac_f32_e32 v129, v154, v154
	v_add_f32_e32 v128, v128, v129
	v_mul_f32_e32 v129, v176, v176
	v_mul_f32_e32 v130, v178, v178
	v_fmac_f32_e32 v129, v155, v155
	v_fmac_f32_e32 v130, v177, v177
	v_add_f32_e32 v129, v129, v130
	v_add_f32_e32 v128, v128, v129
	v_add_f32_e32 v131, v152, v128
	ds_bpermute_b32 v253, v250, v233
	ds_bpermute_b32 v252, v250, v232
	ds_bpermute_b32 v152, v250, v131
	v_lshl_add_u64 v[128:129], s[0:1], 0, v[238:239]
	v_lshl_add_u64 v[134:135], v[128:129], 0, v[240:241]
	v_cmp_gt_f32_e32 vcc, s52, v242
	s_waitcnt lgkmcnt(1)
	v_pk_add_f32 v[230:231], v[232:233], v[252:253]
	s_waitcnt lgkmcnt(0)
	v_add_f32_e32 v128, v131, v152
	ds_bpermute_b32 v233, v249, v231
	ds_bpermute_b32 v232, v249, v230
	ds_bpermute_b32 v129, v249, v128
	v_cvt_pk_bf16_f32 v143, v185, v186
	global_store_dwordx4 v[134:135], v[140:143], off
	v_cvt_pk_bf16_f32 v130, v153, v132
	v_cvt_pk_bf16_f32 v131, v154, v133
	v_cvt_pk_bf16_f32 v132, v155, v176
	v_cvt_pk_bf16_f32 v133, v177, v178
	global_store_dwordx4 v[134:135], v[130:133], off offset:256
	s_and_saveexec_b64 s[2:3], s[36:37]
	s_cbranch_execz .LBB0_1009
	v_lshl_add_u64 v[130:131], s[28:29], 0, v[236:237]
	v_lshl_add_u64 v[130:131], s[48:49], 2, v[130:131]
	s_lshl_b32 s4, s27, 2
	v_lshl_add_u64 v[130:131], v[130:131], 0, s[4:5]
	s_waitcnt lgkmcnt(0)
	v_add_f32_e32 v128, v128, v129
	global_store_dword v[130:131], v128, off
